# baseline (speedup 1.0000x reference)
; __device__ __forceinline__ float bf2f(bf16r h) { return __uint_as_float(((unsigned)h) << 16); }
; __device__ __forceinline__ float siluf(float x) { return x / (1.f + __expf(-x)); }
; __device__ __forceinline__ void phase_ssd_out(const Params& p, int layer, unsigned char* smem) {
;     ...
;         const int t2 = relaunder(tid);
;         const int lane = t2 & 63, hi = lane >> 5, cl = lane & 31, wm = t2 >> 7, wn = (t2 >> 6) & 1;
; #pragma unroll
;         for (int mt = 0; mt < 2; mt++)
; #pragma unroll
;           for (int i = 0; i < 16; i++) {
;             int row = wm * 64 + mt * 32 + (i & 3) + 8 * (i >> 2) + 4 * hi;
;             int col = wn * 32 + cl;
;             bf16r* ybb = yb + (size_t)c * 128 * 1024 + h * 64;
;             unsigned off = (unsigned)(row * 1024 + col);
;             float z = bf2f(ybb[off]);
;             float y = ay[mt][0][i] * siluf(z);
;             *(ybb + off) = f2bf(y);
;             float sq = y * y;
; #pragma unroll
;             for (int o = 16; o > 0; o >>= 1) sq += __shfl_xor(sq, o, 64);
;             if (cl == 0) atomicAdd(&sRow[row], sq);
;             if ((i & 3) == 3) __builtin_amdgcn_sched_barrier(0);
;           }
.LBB0_1377:
	v_mov_b32_e32 v97, v112
	s_lshl_b32 s1, s6, 7
	v_lshrrev_b32_e32 v99, 3, v97
	v_ashrrev_i32_e32 v98, 1, v97
	v_and_b32_e32 v99, 4, v99
	v_and_b32_e32 v96, 31, v97
	v_and_or_b32 v102, v98, s29, v99
	v_lshrrev_b32_e32 v97, 1, v97
	v_and_b32_e32 v103, 32, v97
	s_add_u32 s18, s77, s1
	v_lshlrev_b32_e32 v97, 10, v102
	s_addc_u32 s19, s78, 0
	v_or3_b32 v114, v97, v103, v96
	v_lshl_add_u64 v[106:107], v[114:115], 1, s[18:19]
	v_lshlrev_b32_e32 v248, 1, v114
	v_add_u32_e32 v240, 0x1000, v248
	v_add_u32_e32 v241, 0x5000, v248
	v_add_u32_e32 v242, 0x9000, v248
	v_add_u32_e32 v243, 0xd000, v248
	v_add_u32_e32 v244, 0x11000, v248
	v_add_u32_e32 v245, 0x15000, v248
	v_add_u32_e32 v246, 0x19000, v248
	v_add_u32_e32 v247, 0x1d000, v248
	global_load_ushort v207, v240, s[18:19] offset:-4096
	global_load_ushort v208, v240, s[18:19] offset:-2048
	global_load_ushort v209, v240, s[18:19] offset:0
	global_load_ushort v210, v240, s[18:19] offset:2048
	global_load_ushort v211, v241, s[18:19] offset:-4096
	global_load_ushort v212, v241, s[18:19] offset:-2048
	global_load_ushort v213, v241, s[18:19] offset:0
	global_load_ushort v214, v241, s[18:19] offset:2048
	global_load_ushort v215, v242, s[18:19] offset:-4096
	global_load_ushort v216, v242, s[18:19] offset:-2048
	global_load_ushort v217, v242, s[18:19] offset:0
	global_load_ushort v218, v242, s[18:19] offset:2048
	global_load_ushort v219, v243, s[18:19] offset:-4096
	global_load_ushort v220, v243, s[18:19] offset:-2048
	global_load_ushort v221, v243, s[18:19] offset:0
	global_load_ushort v222, v243, s[18:19] offset:2048
	global_load_ushort v223, v244, s[18:19] offset:-4096
	global_load_ushort v224, v244, s[18:19] offset:-2048
	global_load_ushort v225, v244, s[18:19] offset:0
	global_load_ushort v226, v244, s[18:19] offset:2048
	global_load_ushort v227, v245, s[18:19] offset:-4096
	global_load_ushort v228, v245, s[18:19] offset:-2048
	global_load_ushort v229, v245, s[18:19] offset:0
	global_load_ushort v231, v245, s[18:19] offset:2048
	global_load_ushort v232, v246, s[18:19] offset:-4096
	global_load_ushort v233, v246, s[18:19] offset:-2048
	global_load_ushort v234, v246, s[18:19] offset:0
	global_load_ushort v235, v246, s[18:19] offset:2048
	global_load_ushort v236, v247, s[18:19] offset:-4096
	global_load_ushort v237, v247, s[18:19] offset:-2048
	global_load_ushort v238, v247, s[18:19] offset:0
	global_load_ushort v239, v247, s[18:19] offset:2048
	s_waitcnt vmcnt(0)
	v_mov_b32_e32 v97, v207
	v_and_b32_e32 v98, 64, v180
	v_xor_b32_e32 v99, 16, v180
	v_add_u32_e32 v101, 64, v98
	v_cmp_lt_i32_e32 vcc, v99, v101
	v_lshlrev_b32_e32 v100, 16, v97
	v_mul_f32_e32 v97, 0xbfb8aa3b, v100
	v_exp_f32_e32 v97, v97
	v_cndmask_b32_e32 v98, v180, v99, vcc
	v_add_f32_e32 v99, 1.0, v97
	v_div_scale_f32 v104, s[6:7], v99, v99, v100
	v_rcp_f32_e32 v105, v104
	v_lshlrev_b32_e32 v97, 2, v98
	v_div_scale_f32 v98, vcc, v100, v99, v100
	v_fma_f32 v108, -v104, v105, 1.0
	v_fmac_f32_e32 v105, v108, v105
	v_mul_f32_e32 v108, v98, v105
	v_fma_f32 v109, -v104, v108, v98
	v_fmac_f32_e32 v108, v109, v105
	v_fma_f32 v98, -v104, v108, v98
	v_div_fmas_f32 v98, v98, v105, v108
	v_div_fixup_f32 v98, v98, v99, v100
	v_mul_f32_e32 v100, v80, v98
	v_mul_f32_e32 v80, v100, v100
	s_nop 1
	v_mov_b32_dpp v99, v80 quad_perm:[1,0,3,2] row_mask:0xf bank_mask:0xf
	v_xor_b32_e32 v80, 8, v180
	v_cmp_lt_i32_e32 vcc, v80, v101
	v_xor_b32_e32 v98, 4, v180
	v_xor_b32_e32 v108, 1, v180
	v_cndmask_b32_e32 v80, v180, v80, vcc
	v_lshlrev_b32_e32 v80, 2, v80
	s_waitcnt lgkmcnt(0)
	v_fmac_f32_e32 v99, v100, v100
	s_nop 1
	v_add_f32_dpp v104, v99, v99 quad_perm:[2,3,0,1] row_mask:0xf bank_mask:0xf
	v_cmp_lt_i32_e32 vcc, v98, v101
	v_cmp_eq_u32_e64 s[6:7], 16, v96
	v_cndmask_b32_e32 v98, v180, v98, vcc
	v_lshlrev_b32_e32 v98, 2, v98
	s_nop 1
	v_add_f32_dpp v104, v104, v104 row_half_mirror row_mask:0xf bank_mask:0xf
	v_xor_b32_e32 v99, 2, v180
	v_cmp_lt_i32_e32 vcc, v99, v101
	v_cndmask_b32_e32 v99, v180, v99, vcc
	v_lshlrev_b32_e32 v99, 2, v99
	s_nop 1
	v_add_f32_dpp v104, v104, v104 row_mirror row_mask:0xf bank_mask:0xf
	v_cmp_lt_i32_e32 vcc, v108, v101
	v_cndmask_b32_e32 v101, v180, v108, vcc
	v_lshlrev_b32_e32 v101, 2, v101
	s_nop 1
	v_mov_b32_dpp v105, v104 row_bcast:15 row_mask:0xa bank_mask:0xf
	v_bfe_u32 v108, v100, 16, 1
	v_add3_u32 v100, v100, v108, s28
	global_store_short_d16_hi v[106:107], v100, off
	v_lshlrev_b32_e32 v100, 2, v102
	s_and_saveexec_b64 s[20:21], s[6:7]
	s_cbranch_execz .LBB0_1379
	v_add_f32_e32 v104, v104, v105
	ds_add_f32 v100, v104 offset:38400
.LBB0_1379:
	s_or_b64 exec, exec, s[20:21]
	v_lshl_or_b32 v102, v102, 10, v103
	s_movk_i32 s1, 0x400
	v_or3_b32 v114, v102, v96, s1
	v_lshl_add_u64 v[104:105], v[114:115], 1, s[18:19]
	v_mov_b32_e32 v103, v208
	v_lshlrev_b32_e32 v103, 16, v103
	v_mul_f32_e32 v106, 0xbfb8aa3b, v103
	v_exp_f32_e32 v106, v106
	s_nop 0
	v_add_f32_e32 v106, 1.0, v106
	v_div_scale_f32 v107, s[20:21], v106, v106, v103
	v_rcp_f32_e32 v108, v107
	v_div_scale_f32 v109, vcc, v103, v106, v103
	v_fma_f32 v110, -v107, v108, 1.0
	v_fmac_f32_e32 v108, v110, v108
	v_mul_f32_e32 v110, v109, v108
	v_fma_f32 v111, -v107, v110, v109
	v_fmac_f32_e32 v110, v111, v108
	v_fma_f32 v107, -v107, v110, v109
	v_div_fmas_f32 v107, v107, v108, v110
	v_div_fixup_f32 v103, v107, v106, v103
	v_mul_f32_e32 v106, v81, v103
	v_mul_f32_e32 v81, v106, v106
	s_nop 1
	v_mov_b32_dpp v81, v81 quad_perm:[1,0,3,2] row_mask:0xf bank_mask:0xf
	v_bfe_u32 v107, v106, 16, 1
	v_fmac_f32_e32 v81, v106, v106
	s_nop 1
	v_add_f32_dpp v81, v81, v81 quad_perm:[2,3,0,1] row_mask:0xf bank_mask:0xf
	v_add3_u32 v106, v106, v107, s28
	global_store_short_d16_hi v[104:105], v106, off
	s_nop 1
	v_add_f32_dpp v81, v81, v81 row_half_mirror row_mask:0xf bank_mask:0xf
	s_nop 1
	v_add_f32_dpp v81, v81, v81 row_mirror row_mask:0xf bank_mask:0xf
	s_nop 1
	v_mov_b32_dpp v103, v81 row_bcast:15 row_mask:0xa bank_mask:0xf
	s_and_saveexec_b64 s[20:21], s[6:7]
	s_cbranch_execz .LBB0_1381
	v_add_f32_e32 v81, v81, v103
	ds_add_f32 v100, v81 offset:38404
; __device__ __forceinline__ float bf2f(bf16r h) { return __uint_as_float(((unsigned)h) << 16); }
; __device__ __forceinline__ float siluf(float x) { return x / (1.f + __expf(-x)); }
; __device__ __forceinline__ void phase_ssd_out(const Params& p, int layer, unsigned char* smem) {
;     ...
;         const int t2 = relaunder(tid);
;         const int lane = t2 & 63, hi = lane >> 5, cl = lane & 31, wm = t2 >> 7, wn = (t2 >> 6) & 1;
; #pragma unroll
;         for (int mt = 0; mt < 2; mt++)
; #pragma unroll
;           for (int i = 0; i < 16; i++) {
;             int row = wm * 64 + mt * 32 + (i & 3) + 8 * (i >> 2) + 4 * hi;
;             int col = wn * 32 + cl;
;             bf16r* ybb = yb + (size_t)c * 128 * 1024 + h * 64;
;             unsigned off = (unsigned)(row * 1024 + col);
;             float z = bf2f(ybb[off]);
;             float y = ay[mt][0][i] * siluf(z);
;             *(ybb + off) = f2bf(y);
;             float sq = y * y;
; #pragma unroll
;             for (int o = 16; o > 0; o >>= 1) sq += __shfl_xor(sq, o, 64);
;             if (cl == 0) atomicAdd(&sRow[row], sq);
;             if ((i & 3) == 3) __builtin_amdgcn_sched_barrier(0);
;           }
.LBB0_1381:
	s_or_b64 exec, exec, s[20:21]
	s_movk_i32 s1, 0x800
	v_or3_b32 v114, v102, v96, s1
	v_lshl_add_u64 v[104:105], v[114:115], 1, s[18:19]
	v_mov_b32_e32 v81, v209
	v_lshlrev_b32_e32 v81, 16, v81
	v_mul_f32_e32 v103, 0xbfb8aa3b, v81
	v_exp_f32_e32 v103, v103
	s_nop 0
	v_add_f32_e32 v103, 1.0, v103
	v_div_scale_f32 v106, s[20:21], v103, v103, v81
	v_rcp_f32_e32 v107, v106
	v_div_scale_f32 v108, vcc, v81, v103, v81
	v_fma_f32 v109, -v106, v107, 1.0
	v_fmac_f32_e32 v107, v109, v107
	v_mul_f32_e32 v109, v108, v107
	v_fma_f32 v110, -v106, v109, v108
	v_fmac_f32_e32 v109, v110, v107
	v_fma_f32 v106, -v106, v109, v108
	v_div_fmas_f32 v106, v106, v107, v109
	v_div_fixup_f32 v81, v106, v103, v81
	v_mul_f32_e32 v103, v82, v81
	v_mul_f32_e32 v81, v103, v103
	s_nop 1
	v_mov_b32_dpp v81, v81 quad_perm:[1,0,3,2] row_mask:0xf bank_mask:0xf
	v_bfe_u32 v106, v103, 16, 1
	v_fmac_f32_e32 v81, v103, v103
	s_nop 1
	v_add_f32_dpp v81, v81, v81 quad_perm:[2,3,0,1] row_mask:0xf bank_mask:0xf
	v_add3_u32 v103, v103, v106, s28
	global_store_short_d16_hi v[104:105], v103, off
	s_nop 1
	v_add_f32_dpp v81, v81, v81 row_half_mirror row_mask:0xf bank_mask:0xf
	s_nop 1
	v_add_f32_dpp v81, v81, v81 row_mirror row_mask:0xf bank_mask:0xf
	s_nop 1
	v_mov_b32_dpp v82, v81 row_bcast:15 row_mask:0xa bank_mask:0xf
	s_and_saveexec_b64 s[20:21], s[6:7]
	s_cbranch_execz .LBB0_1383
	v_add_f32_e32 v81, v81, v82
	ds_add_f32 v100, v81 offset:38408
.LBB0_1383:
	s_or_b64 exec, exec, s[20:21]
	s_movk_i32 s1, 0xc00
	v_or3_b32 v114, v102, v96, s1
	v_lshl_add_u64 v[104:105], v[114:115], 1, s[18:19]
	v_mov_b32_e32 v81, v210
	v_lshlrev_b32_e32 v81, 16, v81
	v_mul_f32_e32 v82, 0xbfb8aa3b, v81
	v_exp_f32_e32 v82, v82
	s_nop 0
	v_add_f32_e32 v82, 1.0, v82
	v_div_scale_f32 v103, s[20:21], v82, v82, v81
	v_rcp_f32_e32 v106, v103
	v_div_scale_f32 v107, vcc, v81, v82, v81
	v_fma_f32 v108, -v103, v106, 1.0
	v_fmac_f32_e32 v106, v108, v106
	v_mul_f32_e32 v108, v107, v106
	v_fma_f32 v109, -v103, v108, v107
	v_fmac_f32_e32 v108, v109, v106
	v_fma_f32 v103, -v103, v108, v107
	v_div_fmas_f32 v103, v103, v106, v108
	v_div_fixup_f32 v81, v103, v82, v81
	v_mul_f32_e32 v83, v83, v81
	v_mul_f32_e32 v81, v83, v83
	s_nop 1
	v_mov_b32_dpp v81, v81 quad_perm:[1,0,3,2] row_mask:0xf bank_mask:0xf
	v_bfe_u32 v103, v83, 16, 1
	v_fmac_f32_e32 v81, v83, v83
	s_nop 1
	v_add_f32_dpp v81, v81, v81 quad_perm:[2,3,0,1] row_mask:0xf bank_mask:0xf
	v_add3_u32 v83, v83, v103, s28
	global_store_short_d16_hi v[104:105], v83, off
	s_nop 1
	v_add_f32_dpp v81, v81, v81 row_half_mirror row_mask:0xf bank_mask:0xf
	s_nop 1
	v_add_f32_dpp v81, v81, v81 row_mirror row_mask:0xf bank_mask:0xf
	s_nop 1
	v_mov_b32_dpp v82, v81 row_bcast:15 row_mask:0xa bank_mask:0xf
	s_and_saveexec_b64 s[20:21], s[6:7]
	s_cbranch_execz .LBB0_1385
	v_add_f32_e32 v81, v81, v82
	ds_add_f32 v100, v81 offset:38412
.LBB0_1385:
	s_or_b64 exec, exec, s[20:21]
	s_movk_i32 s1, 0x2000
	v_or3_b32 v114, v102, v96, s1
	v_lshl_add_u64 v[104:105], v[114:115], 1, s[18:19]
	v_mov_b32_e32 v81, v211
	v_lshlrev_b32_e32 v81, 16, v81
	v_mul_f32_e32 v82, 0xbfb8aa3b, v81
	v_exp_f32_e32 v82, v82
	s_nop 0
	v_add_f32_e32 v82, 1.0, v82
	v_div_scale_f32 v83, s[20:21], v82, v82, v81
	v_rcp_f32_e32 v103, v83
	v_div_scale_f32 v106, vcc, v81, v82, v81
	v_fma_f32 v107, -v83, v103, 1.0
	v_fmac_f32_e32 v103, v107, v103
	v_mul_f32_e32 v107, v106, v103
	v_fma_f32 v108, -v83, v107, v106
	v_fmac_f32_e32 v107, v108, v103
	v_fma_f32 v83, -v83, v107, v106
	v_div_fmas_f32 v83, v83, v103, v107
	v_div_fixup_f32 v81, v83, v82, v81
	v_mul_f32_e32 v83, v84, v81
	v_mul_f32_e32 v81, v83, v83
	s_nop 1
	v_mov_b32_dpp v81, v81 quad_perm:[1,0,3,2] row_mask:0xf bank_mask:0xf
	v_bfe_u32 v84, v83, 16, 1
	v_fmac_f32_e32 v81, v83, v83
	s_nop 1
	v_add_f32_dpp v81, v81, v81 quad_perm:[2,3,0,1] row_mask:0xf bank_mask:0xf
	v_add3_u32 v83, v83, v84, s28
	global_store_short_d16_hi v[104:105], v83, off
	s_nop 1
	v_add_f32_dpp v81, v81, v81 row_half_mirror row_mask:0xf bank_mask:0xf
	s_nop 1
	v_add_f32_dpp v81, v81, v81 row_mirror row_mask:0xf bank_mask:0xf
	s_nop 1
	v_mov_b32_dpp v82, v81 row_bcast:15 row_mask:0xa bank_mask:0xf
	s_and_saveexec_b64 s[20:21], s[6:7]
	s_cbranch_execz .LBB0_1387
	v_add_f32_e32 v81, v81, v82
	ds_add_f32 v100, v81 offset:38432
.LBB0_1387:
	s_or_b64 exec, exec, s[20:21]
	v_or3_b32 v114, v102, v96, s26
	v_lshl_add_u64 v[104:105], v[114:115], 1, s[18:19]
	v_mov_b32_e32 v81, v212
	v_lshlrev_b32_e32 v81, 16, v81
	v_mul_f32_e32 v82, 0xbfb8aa3b, v81
	v_exp_f32_e32 v82, v82
	s_nop 0
	v_add_f32_e32 v82, 1.0, v82
	v_div_scale_f32 v83, s[20:21], v82, v82, v81
	v_rcp_f32_e32 v84, v83
	v_div_scale_f32 v103, vcc, v81, v82, v81
	v_fma_f32 v106, -v83, v84, 1.0
	v_fmac_f32_e32 v84, v106, v84
	v_mul_f32_e32 v106, v103, v84
	v_fma_f32 v107, -v83, v106, v103
	v_fmac_f32_e32 v106, v107, v84
	v_fma_f32 v83, -v83, v106, v103
	v_div_fmas_f32 v83, v83, v84, v106
	v_div_fixup_f32 v81, v83, v82, v81
	v_mul_f32_e32 v83, v85, v81
	v_mul_f32_e32 v81, v83, v83
	s_nop 1
	v_mov_b32_dpp v81, v81 quad_perm:[1,0,3,2] row_mask:0xf bank_mask:0xf
	v_bfe_u32 v84, v83, 16, 1
	v_fmac_f32_e32 v81, v83, v83
	s_nop 1
	v_add_f32_dpp v81, v81, v81 quad_perm:[2,3,0,1] row_mask:0xf bank_mask:0xf
	v_add3_u32 v83, v83, v84, s28
	global_store_short_d16_hi v[104:105], v83, off
	s_nop 1
	v_add_f32_dpp v81, v81, v81 row_half_mirror row_mask:0xf bank_mask:0xf
	s_nop 1
	v_add_f32_dpp v81, v81, v81 row_mirror row_mask:0xf bank_mask:0xf
	s_nop 1
	v_mov_b32_dpp v82, v81 row_bcast:15 row_mask:0xa bank_mask:0xf
	s_and_saveexec_b64 s[20:21], s[6:7]
	s_cbranch_execz .LBB0_1389
	v_add_f32_e32 v81, v81, v82
	ds_add_f32 v100, v81 offset:38436
; __device__ __forceinline__ float bf2f(bf16r h) { return __uint_as_float(((unsigned)h) << 16); }
; __device__ __forceinline__ float siluf(float x) { return x / (1.f + __expf(-x)); }
; __device__ __forceinline__ void phase_ssd_out(const Params& p, int layer, unsigned char* smem) {
;     ...
;         const int t2 = relaunder(tid);
;         const int lane = t2 & 63, hi = lane >> 5, cl = lane & 31, wm = t2 >> 7, wn = (t2 >> 6) & 1;
; #pragma unroll
;         for (int mt = 0; mt < 2; mt++)
; #pragma unroll
;           for (int i = 0; i < 16; i++) {
;             int row = wm * 64 + mt * 32 + (i & 3) + 8 * (i >> 2) + 4 * hi;
;             int col = wn * 32 + cl;
;             bf16r* ybb = yb + (size_t)c * 128 * 1024 + h * 64;
;             unsigned off = (unsigned)(row * 1024 + col);
;             float z = bf2f(ybb[off]);
;             float y = ay[mt][0][i] * siluf(z);
;             *(ybb + off) = f2bf(y);
;             float sq = y * y;
; #pragma unroll
;             for (int o = 16; o > 0; o >>= 1) sq += __shfl_xor(sq, o, 64);
;             if (cl == 0) atomicAdd(&sRow[row], sq);
;             if ((i & 3) == 3) __builtin_amdgcn_sched_barrier(0);
;           }
.LBB0_1389:
	s_or_b64 exec, exec, s[20:21]
	s_movk_i32 s1, 0x2800
	v_or3_b32 v114, v102, v96, s1
	v_lshl_add_u64 v[84:85], v[114:115], 1, s[18:19]
	v_mov_b32_e32 v81, v213
	v_lshlrev_b32_e32 v81, 16, v81
	v_mul_f32_e32 v82, 0xbfb8aa3b, v81
	v_exp_f32_e32 v82, v82
	s_nop 0
	v_add_f32_e32 v82, 1.0, v82
	v_div_scale_f32 v83, s[20:21], v82, v82, v81
	v_rcp_f32_e32 v103, v83
	v_div_scale_f32 v104, vcc, v81, v82, v81
	v_fma_f32 v105, -v83, v103, 1.0
	v_fmac_f32_e32 v103, v105, v103
	v_mul_f32_e32 v105, v104, v103
	v_fma_f32 v106, -v83, v105, v104
	v_fmac_f32_e32 v105, v106, v103
	v_fma_f32 v83, -v83, v105, v104
	v_div_fmas_f32 v83, v83, v103, v105
	v_div_fixup_f32 v81, v83, v82, v81
	v_mul_f32_e32 v83, v86, v81
	v_mul_f32_e32 v81, v83, v83
	s_nop 1
	v_mov_b32_dpp v81, v81 quad_perm:[1,0,3,2] row_mask:0xf bank_mask:0xf
	v_bfe_u32 v86, v83, 16, 1
	v_fmac_f32_e32 v81, v83, v83
	s_nop 1
	v_add_f32_dpp v81, v81, v81 quad_perm:[2,3,0,1] row_mask:0xf bank_mask:0xf
	v_add3_u32 v83, v83, v86, s28
	global_store_short_d16_hi v[84:85], v83, off
	s_nop 1
	v_add_f32_dpp v81, v81, v81 row_half_mirror row_mask:0xf bank_mask:0xf
	s_nop 1
	v_add_f32_dpp v81, v81, v81 row_mirror row_mask:0xf bank_mask:0xf
	s_nop 1
	v_mov_b32_dpp v82, v81 row_bcast:15 row_mask:0xa bank_mask:0xf
	s_and_saveexec_b64 s[20:21], s[6:7]
	s_cbranch_execz .LBB0_1391
	v_add_f32_e32 v81, v81, v82
	ds_add_f32 v100, v81 offset:38440
.LBB0_1391:
	s_or_b64 exec, exec, s[20:21]
	s_movk_i32 s1, 0x2c00
	v_or3_b32 v114, v102, v96, s1
	v_lshl_add_u64 v[84:85], v[114:115], 1, s[18:19]
	v_mov_b32_e32 v81, v214
	v_lshlrev_b32_e32 v81, 16, v81
	v_mul_f32_e32 v82, 0xbfb8aa3b, v81
	v_exp_f32_e32 v82, v82
	s_nop 0
	v_add_f32_e32 v82, 1.0, v82
	v_div_scale_f32 v83, s[20:21], v82, v82, v81
	v_rcp_f32_e32 v86, v83
	v_div_scale_f32 v103, vcc, v81, v82, v81
	v_fma_f32 v104, -v83, v86, 1.0
	v_fmac_f32_e32 v86, v104, v86
	v_mul_f32_e32 v104, v103, v86
	v_fma_f32 v105, -v83, v104, v103
	v_fmac_f32_e32 v104, v105, v86
	v_fma_f32 v83, -v83, v104, v103
	v_div_fmas_f32 v83, v83, v86, v104
	v_div_fixup_f32 v81, v83, v82, v81
	v_mul_f32_e32 v83, v87, v81
	v_mul_f32_e32 v81, v83, v83
	s_nop 1
	v_mov_b32_dpp v81, v81 quad_perm:[1,0,3,2] row_mask:0xf bank_mask:0xf
	v_bfe_u32 v86, v83, 16, 1
	v_fmac_f32_e32 v81, v83, v83
	s_nop 1
	v_add_f32_dpp v81, v81, v81 quad_perm:[2,3,0,1] row_mask:0xf bank_mask:0xf
	v_add3_u32 v83, v83, v86, s28
	global_store_short_d16_hi v[84:85], v83, off
	s_nop 1
	v_add_f32_dpp v81, v81, v81 row_half_mirror row_mask:0xf bank_mask:0xf
	s_nop 1
	v_add_f32_dpp v81, v81, v81 row_mirror row_mask:0xf bank_mask:0xf
	s_nop 1
	v_mov_b32_dpp v82, v81 row_bcast:15 row_mask:0xa bank_mask:0xf
	s_and_saveexec_b64 s[20:21], s[6:7]
	s_cbranch_execz .LBB0_1393
	v_add_f32_e32 v81, v81, v82
	ds_add_f32 v100, v81 offset:38444
.LBB0_1393:
	s_or_b64 exec, exec, s[20:21]
	s_movk_i32 s1, 0x4000
	v_or3_b32 v114, v102, v96, s1
	v_lshl_add_u64 v[84:85], v[114:115], 1, s[18:19]
	v_mov_b32_e32 v81, v215
	v_lshlrev_b32_e32 v81, 16, v81
	v_mul_f32_e32 v82, 0xbfb8aa3b, v81
	v_exp_f32_e32 v82, v82
	s_nop 0
	v_add_f32_e32 v82, 1.0, v82
	v_div_scale_f32 v83, s[20:21], v82, v82, v81
	v_rcp_f32_e32 v86, v83
	v_div_scale_f32 v87, vcc, v81, v82, v81
	v_fma_f32 v103, -v83, v86, 1.0
	v_fmac_f32_e32 v86, v103, v86
	v_mul_f32_e32 v103, v87, v86
	v_fma_f32 v104, -v83, v103, v87
	v_fmac_f32_e32 v103, v104, v86
	v_fma_f32 v83, -v83, v103, v87
	v_div_fmas_f32 v83, v83, v86, v103
	v_div_fixup_f32 v81, v83, v82, v81
	v_mul_f32_e32 v83, v88, v81
	v_mul_f32_e32 v81, v83, v83
	s_nop 1
	v_mov_b32_dpp v81, v81 quad_perm:[1,0,3,2] row_mask:0xf bank_mask:0xf
	v_bfe_u32 v86, v83, 16, 1
	v_fmac_f32_e32 v81, v83, v83
	s_nop 1
	v_add_f32_dpp v81, v81, v81 quad_perm:[2,3,0,1] row_mask:0xf bank_mask:0xf
	v_add3_u32 v83, v83, v86, s28
	global_store_short_d16_hi v[84:85], v83, off
	s_nop 1
	v_add_f32_dpp v81, v81, v81 row_half_mirror row_mask:0xf bank_mask:0xf
	s_nop 1
	v_add_f32_dpp v81, v81, v81 row_mirror row_mask:0xf bank_mask:0xf
	s_nop 1
	v_mov_b32_dpp v82, v81 row_bcast:15 row_mask:0xa bank_mask:0xf
	s_and_saveexec_b64 s[20:21], s[6:7]
	s_cbranch_execz .LBB0_1395
	v_add_f32_e32 v81, v81, v82
	ds_add_f32 v100, v81 offset:38464
.LBB0_1395:
	s_or_b64 exec, exec, s[20:21]
	s_movk_i32 s1, 0x4400
	v_or3_b32 v114, v102, v96, s1
	v_lshl_add_u64 v[84:85], v[114:115], 1, s[18:19]
	v_mov_b32_e32 v81, v216
	v_lshlrev_b32_e32 v81, 16, v81
	v_mul_f32_e32 v82, 0xbfb8aa3b, v81
	v_exp_f32_e32 v82, v82
	s_nop 0
	v_add_f32_e32 v82, 1.0, v82
	v_div_scale_f32 v83, s[20:21], v82, v82, v81
	v_rcp_f32_e32 v86, v83
	v_div_scale_f32 v87, vcc, v81, v82, v81
	v_fma_f32 v88, -v83, v86, 1.0
	v_fmac_f32_e32 v86, v88, v86
	v_mul_f32_e32 v88, v87, v86
	v_fma_f32 v103, -v83, v88, v87
	v_fmac_f32_e32 v88, v103, v86
	v_fma_f32 v83, -v83, v88, v87
	v_div_fmas_f32 v83, v83, v86, v88
	v_div_fixup_f32 v81, v83, v82, v81
	v_mul_f32_e32 v83, v89, v81
	v_mul_f32_e32 v81, v83, v83
	s_nop 1
	v_mov_b32_dpp v81, v81 quad_perm:[1,0,3,2] row_mask:0xf bank_mask:0xf
	v_bfe_u32 v86, v83, 16, 1
	v_fmac_f32_e32 v81, v83, v83
	s_nop 1
	v_add_f32_dpp v81, v81, v81 quad_perm:[2,3,0,1] row_mask:0xf bank_mask:0xf
	v_add3_u32 v83, v83, v86, s28
	global_store_short_d16_hi v[84:85], v83, off
	s_nop 1
	v_add_f32_dpp v81, v81, v81 row_half_mirror row_mask:0xf bank_mask:0xf
	s_nop 1
	v_add_f32_dpp v81, v81, v81 row_mirror row_mask:0xf bank_mask:0xf
	s_nop 1
	v_mov_b32_dpp v82, v81 row_bcast:15 row_mask:0xa bank_mask:0xf
	s_and_saveexec_b64 s[20:21], s[6:7]
	s_cbranch_execz .LBB0_1397
	v_add_f32_e32 v81, v81, v82
	ds_add_f32 v100, v81 offset:38468
; __device__ __forceinline__ float bf2f(bf16r h) { return __uint_as_float(((unsigned)h) << 16); }
; __device__ __forceinline__ float siluf(float x) { return x / (1.f + __expf(-x)); }
; __device__ __forceinline__ void phase_ssd_out(const Params& p, int layer, unsigned char* smem) {
;     ...
;         const int t2 = relaunder(tid);
;         const int lane = t2 & 63, hi = lane >> 5, cl = lane & 31, wm = t2 >> 7, wn = (t2 >> 6) & 1;
; #pragma unroll
;         for (int mt = 0; mt < 2; mt++)
; #pragma unroll
;           for (int i = 0; i < 16; i++) {
;             int row = wm * 64 + mt * 32 + (i & 3) + 8 * (i >> 2) + 4 * hi;
;             int col = wn * 32 + cl;
;             bf16r* ybb = yb + (size_t)c * 128 * 1024 + h * 64;
;             unsigned off = (unsigned)(row * 1024 + col);
;             float z = bf2f(ybb[off]);
;             float y = ay[mt][0][i] * siluf(z);
;             *(ybb + off) = f2bf(y);
;             float sq = y * y;
; #pragma unroll
;             for (int o = 16; o > 0; o >>= 1) sq += __shfl_xor(sq, o, 64);
;             if (cl == 0) atomicAdd(&sRow[row], sq);
;             if ((i & 3) == 3) __builtin_amdgcn_sched_barrier(0);
;           }
.LBB0_1397:
	s_or_b64 exec, exec, s[20:21]
	s_movk_i32 s1, 0x4800
	v_or3_b32 v114, v102, v96, s1
	v_lshl_add_u64 v[84:85], v[114:115], 1, s[18:19]
	v_mov_b32_e32 v81, v217
	v_lshlrev_b32_e32 v81, 16, v81
	v_mul_f32_e32 v82, 0xbfb8aa3b, v81
	v_exp_f32_e32 v82, v82
	s_nop 0
	v_add_f32_e32 v82, 1.0, v82
	v_div_scale_f32 v83, s[20:21], v82, v82, v81
	v_rcp_f32_e32 v86, v83
	v_div_scale_f32 v87, vcc, v81, v82, v81
	v_fma_f32 v88, -v83, v86, 1.0
	v_fmac_f32_e32 v86, v88, v86
	v_mul_f32_e32 v88, v87, v86
	v_fma_f32 v89, -v83, v88, v87
	v_fmac_f32_e32 v88, v89, v86
	v_fma_f32 v83, -v83, v88, v87
	v_div_fmas_f32 v83, v83, v86, v88
	v_div_fixup_f32 v81, v83, v82, v81
	v_mul_f32_e32 v83, v90, v81
	v_mul_f32_e32 v81, v83, v83
	s_nop 1
	v_mov_b32_dpp v81, v81 quad_perm:[1,0,3,2] row_mask:0xf bank_mask:0xf
	v_bfe_u32 v86, v83, 16, 1
	v_fmac_f32_e32 v81, v83, v83
	s_nop 1
	v_add_f32_dpp v81, v81, v81 quad_perm:[2,3,0,1] row_mask:0xf bank_mask:0xf
	v_add3_u32 v83, v83, v86, s28
	global_store_short_d16_hi v[84:85], v83, off
	s_nop 1
	v_add_f32_dpp v81, v81, v81 row_half_mirror row_mask:0xf bank_mask:0xf
	s_nop 1
	v_add_f32_dpp v81, v81, v81 row_mirror row_mask:0xf bank_mask:0xf
	s_nop 1
	v_mov_b32_dpp v82, v81 row_bcast:15 row_mask:0xa bank_mask:0xf
	s_and_saveexec_b64 s[20:21], s[6:7]
	s_cbranch_execz .LBB0_1399
	v_add_f32_e32 v81, v81, v82
	ds_add_f32 v100, v81 offset:38472
.LBB0_1399:
	s_or_b64 exec, exec, s[20:21]
	s_movk_i32 s1, 0x4c00
	v_or3_b32 v114, v102, v96, s1
	v_lshl_add_u64 v[84:85], v[114:115], 1, s[18:19]
	v_mov_b32_e32 v81, v218
	v_lshlrev_b32_e32 v81, 16, v81
	v_mul_f32_e32 v82, 0xbfb8aa3b, v81
	v_exp_f32_e32 v82, v82
	s_nop 0
	v_add_f32_e32 v82, 1.0, v82
	v_div_scale_f32 v83, s[20:21], v82, v82, v81
	v_rcp_f32_e32 v86, v83
	v_div_scale_f32 v87, vcc, v81, v82, v81
	v_fma_f32 v88, -v83, v86, 1.0
	v_fmac_f32_e32 v86, v88, v86
	v_mul_f32_e32 v88, v87, v86
	v_fma_f32 v89, -v83, v88, v87
	v_fmac_f32_e32 v88, v89, v86
	v_fma_f32 v83, -v83, v88, v87
	v_div_fmas_f32 v83, v83, v86, v88
	v_div_fixup_f32 v81, v83, v82, v81
	v_mul_f32_e32 v83, v91, v81
	v_mul_f32_e32 v81, v83, v83
	s_nop 1
	v_mov_b32_dpp v81, v81 quad_perm:[1,0,3,2] row_mask:0xf bank_mask:0xf
	v_bfe_u32 v86, v83, 16, 1
	v_fmac_f32_e32 v81, v83, v83
	s_nop 1
	v_add_f32_dpp v81, v81, v81 quad_perm:[2,3,0,1] row_mask:0xf bank_mask:0xf
	v_add3_u32 v83, v83, v86, s28
	global_store_short_d16_hi v[84:85], v83, off
	s_nop 1
	v_add_f32_dpp v81, v81, v81 row_half_mirror row_mask:0xf bank_mask:0xf
	s_nop 1
	v_add_f32_dpp v81, v81, v81 row_mirror row_mask:0xf bank_mask:0xf
	s_nop 1
	v_mov_b32_dpp v82, v81 row_bcast:15 row_mask:0xa bank_mask:0xf
	s_and_saveexec_b64 s[20:21], s[6:7]
	s_cbranch_execz .LBB0_1401
	v_add_f32_e32 v81, v81, v82
	ds_add_f32 v100, v81 offset:38476
.LBB0_1401:
	s_or_b64 exec, exec, s[20:21]
	s_movk_i32 s1, 0x6000
	v_or3_b32 v114, v102, v96, s1
	v_lshl_add_u64 v[84:85], v[114:115], 1, s[18:19]
	v_mov_b32_e32 v81, v219
	v_lshlrev_b32_e32 v81, 16, v81
	v_mul_f32_e32 v82, 0xbfb8aa3b, v81
	v_exp_f32_e32 v82, v82
	s_nop 0
	v_add_f32_e32 v82, 1.0, v82
	v_div_scale_f32 v83, s[20:21], v82, v82, v81
	v_rcp_f32_e32 v86, v83
	v_div_scale_f32 v87, vcc, v81, v82, v81
	v_fma_f32 v88, -v83, v86, 1.0
	v_fmac_f32_e32 v86, v88, v86
	v_mul_f32_e32 v88, v87, v86
	v_fma_f32 v89, -v83, v88, v87
	v_fmac_f32_e32 v88, v89, v86
	v_fma_f32 v83, -v83, v88, v87
	v_div_fmas_f32 v83, v83, v86, v88
	v_div_fixup_f32 v81, v83, v82, v81
	v_mul_f32_e32 v83, v92, v81
	v_mul_f32_e32 v81, v83, v83
	s_nop 1
	v_mov_b32_dpp v81, v81 quad_perm:[1,0,3,2] row_mask:0xf bank_mask:0xf
	v_bfe_u32 v86, v83, 16, 1
	v_fmac_f32_e32 v81, v83, v83
	s_nop 1
	v_add_f32_dpp v81, v81, v81 quad_perm:[2,3,0,1] row_mask:0xf bank_mask:0xf
	v_add3_u32 v83, v83, v86, s28
	global_store_short_d16_hi v[84:85], v83, off
	s_nop 1
	v_add_f32_dpp v81, v81, v81 row_half_mirror row_mask:0xf bank_mask:0xf
	s_nop 1
	v_add_f32_dpp v81, v81, v81 row_mirror row_mask:0xf bank_mask:0xf
	s_nop 1
	v_mov_b32_dpp v82, v81 row_bcast:15 row_mask:0xa bank_mask:0xf
	s_and_saveexec_b64 s[20:21], s[6:7]
	s_cbranch_execz .LBB0_1403
	v_add_f32_e32 v81, v81, v82
	ds_add_f32 v100, v81 offset:38496
.LBB0_1403:
	s_or_b64 exec, exec, s[20:21]
	s_movk_i32 s1, 0x6400
	v_or3_b32 v114, v102, v96, s1
	v_lshl_add_u64 v[84:85], v[114:115], 1, s[18:19]
	v_mov_b32_e32 v81, v220
	v_lshlrev_b32_e32 v81, 16, v81
	v_mul_f32_e32 v82, 0xbfb8aa3b, v81
	v_exp_f32_e32 v82, v82
	s_nop 0
	v_add_f32_e32 v82, 1.0, v82
	v_div_scale_f32 v83, s[20:21], v82, v82, v81
	v_rcp_f32_e32 v86, v83
	v_div_scale_f32 v87, vcc, v81, v82, v81
	v_fma_f32 v88, -v83, v86, 1.0
	v_fmac_f32_e32 v86, v88, v86
	v_mul_f32_e32 v88, v87, v86
	v_fma_f32 v89, -v83, v88, v87
	v_fmac_f32_e32 v88, v89, v86
	v_fma_f32 v83, -v83, v88, v87
	v_div_fmas_f32 v83, v83, v86, v88
	v_div_fixup_f32 v81, v83, v82, v81
	v_mul_f32_e32 v83, v93, v81
	v_mul_f32_e32 v81, v83, v83
	s_nop 1
	v_mov_b32_dpp v81, v81 quad_perm:[1,0,3,2] row_mask:0xf bank_mask:0xf
	v_bfe_u32 v86, v83, 16, 1
	v_fmac_f32_e32 v81, v83, v83
	s_nop 1
	v_add_f32_dpp v81, v81, v81 quad_perm:[2,3,0,1] row_mask:0xf bank_mask:0xf
	v_add3_u32 v83, v83, v86, s28
	global_store_short_d16_hi v[84:85], v83, off
	s_nop 1
	v_add_f32_dpp v81, v81, v81 row_half_mirror row_mask:0xf bank_mask:0xf
	s_nop 1
	v_add_f32_dpp v81, v81, v81 row_mirror row_mask:0xf bank_mask:0xf
	s_nop 1
	v_mov_b32_dpp v82, v81 row_bcast:15 row_mask:0xa bank_mask:0xf
	s_and_saveexec_b64 s[20:21], s[6:7]
	s_cbranch_execz .LBB0_1405
	v_add_f32_e32 v81, v81, v82
	ds_add_f32 v100, v81 offset:38500
; __device__ __forceinline__ float bf2f(bf16r h) { return __uint_as_float(((unsigned)h) << 16); }
; __device__ __forceinline__ float siluf(float x) { return x / (1.f + __expf(-x)); }
; __device__ __forceinline__ void phase_ssd_out(const Params& p, int layer, unsigned char* smem) {
;     ...
;         const int t2 = relaunder(tid);
;         const int lane = t2 & 63, hi = lane >> 5, cl = lane & 31, wm = t2 >> 7, wn = (t2 >> 6) & 1;
; #pragma unroll
;         for (int mt = 0; mt < 2; mt++)
; #pragma unroll
;           for (int i = 0; i < 16; i++) {
;             int row = wm * 64 + mt * 32 + (i & 3) + 8 * (i >> 2) + 4 * hi;
;             int col = wn * 32 + cl;
;             bf16r* ybb = yb + (size_t)c * 128 * 1024 + h * 64;
;             unsigned off = (unsigned)(row * 1024 + col);
;             float z = bf2f(ybb[off]);
;             float y = ay[mt][0][i] * siluf(z);
;             *(ybb + off) = f2bf(y);
;             float sq = y * y;
; #pragma unroll
;             for (int o = 16; o > 0; o >>= 1) sq += __shfl_xor(sq, o, 64);
;             if (cl == 0) atomicAdd(&sRow[row], sq);
;             if ((i & 3) == 3) __builtin_amdgcn_sched_barrier(0);
;           }
.LBB0_1405:
	s_or_b64 exec, exec, s[20:21]
	s_movk_i32 s1, 0x6800
	v_or3_b32 v114, v102, v96, s1
	v_lshl_add_u64 v[84:85], v[114:115], 1, s[18:19]
	v_mov_b32_e32 v81, v221
	v_lshlrev_b32_e32 v81, 16, v81
	v_mul_f32_e32 v82, 0xbfb8aa3b, v81
	v_exp_f32_e32 v82, v82
	s_nop 0
	v_add_f32_e32 v82, 1.0, v82
	v_div_scale_f32 v83, s[20:21], v82, v82, v81
	v_rcp_f32_e32 v86, v83
	v_div_scale_f32 v87, vcc, v81, v82, v81
	v_fma_f32 v88, -v83, v86, 1.0
	v_fmac_f32_e32 v86, v88, v86
	v_mul_f32_e32 v88, v87, v86
	v_fma_f32 v89, -v83, v88, v87
	v_fmac_f32_e32 v88, v89, v86
	v_fma_f32 v83, -v83, v88, v87
	v_div_fmas_f32 v83, v83, v86, v88
	v_div_fixup_f32 v81, v83, v82, v81
	v_mul_f32_e32 v83, v94, v81
	v_mul_f32_e32 v81, v83, v83
	s_nop 1
	v_mov_b32_dpp v81, v81 quad_perm:[1,0,3,2] row_mask:0xf bank_mask:0xf
	v_bfe_u32 v86, v83, 16, 1
	v_fmac_f32_e32 v81, v83, v83
	s_nop 1
	v_add_f32_dpp v81, v81, v81 quad_perm:[2,3,0,1] row_mask:0xf bank_mask:0xf
	v_add3_u32 v83, v83, v86, s28
	global_store_short_d16_hi v[84:85], v83, off
	s_nop 1
	v_add_f32_dpp v81, v81, v81 row_half_mirror row_mask:0xf bank_mask:0xf
	s_nop 1
	v_add_f32_dpp v81, v81, v81 row_mirror row_mask:0xf bank_mask:0xf
	s_nop 1
	v_mov_b32_dpp v82, v81 row_bcast:15 row_mask:0xa bank_mask:0xf
	s_and_saveexec_b64 s[20:21], s[6:7]
	s_cbranch_execz .LBB0_1407
	v_add_f32_e32 v81, v81, v82
	ds_add_f32 v100, v81 offset:38504
.LBB0_1407:
	s_or_b64 exec, exec, s[20:21]
	s_movk_i32 s1, 0x6c00
	v_or3_b32 v114, v102, v96, s1
	v_lshl_add_u64 v[84:85], v[114:115], 1, s[18:19]
	v_mov_b32_e32 v81, v222
	v_lshlrev_b32_e32 v81, 16, v81
	v_mul_f32_e32 v82, 0xbfb8aa3b, v81
	v_exp_f32_e32 v82, v82
	s_nop 0
	v_add_f32_e32 v82, 1.0, v82
	v_div_scale_f32 v83, s[20:21], v82, v82, v81
	v_rcp_f32_e32 v86, v83
	v_div_scale_f32 v87, vcc, v81, v82, v81
	v_fma_f32 v88, -v83, v86, 1.0
	v_fmac_f32_e32 v86, v88, v86
	v_mul_f32_e32 v88, v87, v86
	v_fma_f32 v89, -v83, v88, v87
	v_fmac_f32_e32 v88, v89, v86
	v_fma_f32 v83, -v83, v88, v87
	v_div_fmas_f32 v83, v83, v86, v88
	v_div_fixup_f32 v81, v83, v82, v81
	v_mul_f32_e32 v83, v95, v81
	v_mul_f32_e32 v81, v83, v83
	s_nop 1
	v_mov_b32_dpp v81, v81 quad_perm:[1,0,3,2] row_mask:0xf bank_mask:0xf
	v_bfe_u32 v86, v83, 16, 1
	v_fmac_f32_e32 v81, v83, v83
	s_nop 1
	v_add_f32_dpp v81, v81, v81 quad_perm:[2,3,0,1] row_mask:0xf bank_mask:0xf
	v_add3_u32 v83, v83, v86, s28
	global_store_short_d16_hi v[84:85], v83, off
	s_nop 1
	v_add_f32_dpp v81, v81, v81 row_half_mirror row_mask:0xf bank_mask:0xf
	s_nop 1
	v_add_f32_dpp v81, v81, v81 row_mirror row_mask:0xf bank_mask:0xf
	s_nop 1
	v_mov_b32_dpp v82, v81 row_bcast:15 row_mask:0xa bank_mask:0xf
	s_and_saveexec_b64 s[20:21], s[6:7]
	s_cbranch_execz .LBB0_1409
	v_add_f32_e32 v81, v81, v82
	ds_add_f32 v100, v81 offset:38508
.LBB0_1409:
	s_or_b64 exec, exec, s[20:21]
	s_mov_b32 s1, 0x8000
	v_or3_b32 v114, v102, v96, s1
	v_lshl_add_u64 v[82:83], v[114:115], 1, s[18:19]
	v_mov_b32_e32 v81, v223
	v_lshlrev_b32_e32 v81, 16, v81
	v_mul_f32_e32 v84, 0xbfb8aa3b, v81
	v_exp_f32_e32 v84, v84
	s_nop 0
	v_add_f32_e32 v84, 1.0, v84
	v_div_scale_f32 v85, s[20:21], v84, v84, v81
	v_rcp_f32_e32 v86, v85
	v_div_scale_f32 v87, vcc, v81, v84, v81
	v_fma_f32 v88, -v85, v86, 1.0
	v_fmac_f32_e32 v86, v88, v86
	v_mul_f32_e32 v88, v87, v86
	v_fma_f32 v89, -v85, v88, v87
	v_fmac_f32_e32 v88, v89, v86
	v_fma_f32 v85, -v85, v88, v87
	v_div_fmas_f32 v85, v85, v86, v88
	v_div_fixup_f32 v81, v85, v84, v81
	v_mul_f32_e32 v84, v64, v81
	v_mul_f32_e32 v64, v84, v84
	s_nop 1
	v_mov_b32_dpp v64, v64 quad_perm:[1,0,3,2] row_mask:0xf bank_mask:0xf
	v_bfe_u32 v85, v84, 16, 1
	v_fmac_f32_e32 v64, v84, v84
	s_nop 1
	v_add_f32_dpp v64, v64, v64 quad_perm:[2,3,0,1] row_mask:0xf bank_mask:0xf
	v_add3_u32 v84, v84, v85, s28
	global_store_short_d16_hi v[82:83], v84, off
	s_nop 1
	v_add_f32_dpp v64, v64, v64 row_half_mirror row_mask:0xf bank_mask:0xf
	s_nop 1
	v_add_f32_dpp v64, v64, v64 row_mirror row_mask:0xf bank_mask:0xf
	s_nop 1
	v_mov_b32_dpp v81, v64 row_bcast:15 row_mask:0xa bank_mask:0xf
	s_and_saveexec_b64 s[20:21], s[6:7]
	s_cbranch_execz .LBB0_1411
	v_add_f32_e32 v64, v64, v81
	ds_add_f32 v100, v64 offset:38528
.LBB0_1411:
	s_or_b64 exec, exec, s[20:21]
	s_mov_b32 s1, 0x8400
	v_or3_b32 v114, v102, v96, s1
	v_lshl_add_u64 v[82:83], v[114:115], 1, s[18:19]
	v_mov_b32_e32 v64, v224
	v_lshlrev_b32_e32 v64, 16, v64
	v_mul_f32_e32 v81, 0xbfb8aa3b, v64
	v_exp_f32_e32 v81, v81
	s_nop 0
	v_add_f32_e32 v81, 1.0, v81
	v_div_scale_f32 v84, s[20:21], v81, v81, v64
	v_rcp_f32_e32 v85, v84
	v_div_scale_f32 v86, vcc, v64, v81, v64
	v_fma_f32 v87, -v84, v85, 1.0
	v_fmac_f32_e32 v85, v87, v85
	v_mul_f32_e32 v87, v86, v85
	v_fma_f32 v88, -v84, v87, v86
	v_fmac_f32_e32 v87, v88, v85
	v_fma_f32 v84, -v84, v87, v86
	v_div_fmas_f32 v84, v84, v85, v87
	v_div_fixup_f32 v64, v84, v81, v64
	v_mul_f32_e32 v81, v65, v64
	v_mul_f32_e32 v64, v81, v81
	s_nop 1
	v_mov_b32_dpp v64, v64 quad_perm:[1,0,3,2] row_mask:0xf bank_mask:0xf
	v_bfe_u32 v84, v81, 16, 1
	v_fmac_f32_e32 v64, v81, v81
	s_nop 1
	v_add_f32_dpp v64, v64, v64 quad_perm:[2,3,0,1] row_mask:0xf bank_mask:0xf
	v_add3_u32 v81, v81, v84, s28
	global_store_short_d16_hi v[82:83], v81, off
	s_nop 1
	v_add_f32_dpp v64, v64, v64 row_half_mirror row_mask:0xf bank_mask:0xf
	s_nop 1
	v_add_f32_dpp v64, v64, v64 row_mirror row_mask:0xf bank_mask:0xf
	s_nop 1
	v_mov_b32_dpp v65, v64 row_bcast:15 row_mask:0xa bank_mask:0xf
	s_and_saveexec_b64 s[20:21], s[6:7]
	s_cbranch_execz .LBB0_1413
	v_add_f32_e32 v64, v64, v65
	ds_add_f32 v100, v64 offset:38532
; __device__ __forceinline__ float bf2f(bf16r h) { return __uint_as_float(((unsigned)h) << 16); }
; __device__ __forceinline__ float siluf(float x) { return x / (1.f + __expf(-x)); }
; __device__ __forceinline__ void phase_ssd_out(const Params& p, int layer, unsigned char* smem) {
;     ...
;         const int t2 = relaunder(tid);
;         const int lane = t2 & 63, hi = lane >> 5, cl = lane & 31, wm = t2 >> 7, wn = (t2 >> 6) & 1;
; #pragma unroll
;         for (int mt = 0; mt < 2; mt++)
; #pragma unroll
;           for (int i = 0; i < 16; i++) {
;             int row = wm * 64 + mt * 32 + (i & 3) + 8 * (i >> 2) + 4 * hi;
;             int col = wn * 32 + cl;
;             bf16r* ybb = yb + (size_t)c * 128 * 1024 + h * 64;
;             unsigned off = (unsigned)(row * 1024 + col);
;             float z = bf2f(ybb[off]);
;             float y = ay[mt][0][i] * siluf(z);
;             *(ybb + off) = f2bf(y);
;             float sq = y * y;
; #pragma unroll
;             for (int o = 16; o > 0; o >>= 1) sq += __shfl_xor(sq, o, 64);
;             if (cl == 0) atomicAdd(&sRow[row], sq);
;             if ((i & 3) == 3) __builtin_amdgcn_sched_barrier(0);
;           }
.LBB0_1413:
	s_or_b64 exec, exec, s[20:21]
	s_mov_b32 s1, 0x8800
	v_or3_b32 v114, v102, v96, s1
	v_lshl_add_u64 v[82:83], v[114:115], 1, s[18:19]
	v_mov_b32_e32 v64, v225
	v_lshlrev_b32_e32 v64, 16, v64
	v_mul_f32_e32 v65, 0xbfb8aa3b, v64
	v_exp_f32_e32 v65, v65
	s_nop 0
	v_add_f32_e32 v65, 1.0, v65
	v_div_scale_f32 v81, s[20:21], v65, v65, v64
	v_rcp_f32_e32 v84, v81
	v_div_scale_f32 v85, vcc, v64, v65, v64
	v_fma_f32 v86, -v81, v84, 1.0
	v_fmac_f32_e32 v84, v86, v84
	v_mul_f32_e32 v86, v85, v84
	v_fma_f32 v87, -v81, v86, v85
	v_fmac_f32_e32 v86, v87, v84
	v_fma_f32 v81, -v81, v86, v85
	v_div_fmas_f32 v81, v81, v84, v86
	v_div_fixup_f32 v64, v81, v65, v64
	v_mul_f32_e32 v66, v66, v64
	v_mul_f32_e32 v64, v66, v66
	s_nop 1
	v_mov_b32_dpp v64, v64 quad_perm:[1,0,3,2] row_mask:0xf bank_mask:0xf
	v_bfe_u32 v81, v66, 16, 1
	v_fmac_f32_e32 v64, v66, v66
	s_nop 1
	v_add_f32_dpp v64, v64, v64 quad_perm:[2,3,0,1] row_mask:0xf bank_mask:0xf
	v_add3_u32 v66, v66, v81, s28
	global_store_short_d16_hi v[82:83], v66, off
	s_nop 1
	v_add_f32_dpp v64, v64, v64 row_half_mirror row_mask:0xf bank_mask:0xf
	s_nop 1
	v_add_f32_dpp v64, v64, v64 row_mirror row_mask:0xf bank_mask:0xf
	s_nop 1
	v_mov_b32_dpp v65, v64 row_bcast:15 row_mask:0xa bank_mask:0xf
	s_and_saveexec_b64 s[20:21], s[6:7]
	s_cbranch_execz .LBB0_1415
	v_add_f32_e32 v64, v64, v65
	ds_add_f32 v100, v64 offset:38536
.LBB0_1415:
	s_or_b64 exec, exec, s[20:21]
	s_mov_b32 s1, 0x8c00
	v_or3_b32 v114, v102, v96, s1
	v_lshl_add_u64 v[82:83], v[114:115], 1, s[18:19]
	v_mov_b32_e32 v64, v226
	v_lshlrev_b32_e32 v64, 16, v64
	v_mul_f32_e32 v65, 0xbfb8aa3b, v64
	v_exp_f32_e32 v65, v65
	s_nop 0
	v_add_f32_e32 v65, 1.0, v65
	v_div_scale_f32 v66, s[20:21], v65, v65, v64
	v_rcp_f32_e32 v81, v66
	v_div_scale_f32 v84, vcc, v64, v65, v64
	v_fma_f32 v85, -v66, v81, 1.0
	v_fmac_f32_e32 v81, v85, v81
	v_mul_f32_e32 v85, v84, v81
	v_fma_f32 v86, -v66, v85, v84
	v_fmac_f32_e32 v85, v86, v81
	v_fma_f32 v66, -v66, v85, v84
	v_div_fmas_f32 v66, v66, v81, v85
	v_div_fixup_f32 v64, v66, v65, v64
	v_mul_f32_e32 v66, v67, v64
	v_mul_f32_e32 v64, v66, v66
	s_nop 1
	v_mov_b32_dpp v64, v64 quad_perm:[1,0,3,2] row_mask:0xf bank_mask:0xf
	v_bfe_u32 v67, v66, 16, 1
	v_fmac_f32_e32 v64, v66, v66
	s_nop 1
	v_add_f32_dpp v64, v64, v64 quad_perm:[2,3,0,1] row_mask:0xf bank_mask:0xf
	v_add3_u32 v66, v66, v67, s28
	global_store_short_d16_hi v[82:83], v66, off
	s_nop 1
	v_add_f32_dpp v64, v64, v64 row_half_mirror row_mask:0xf bank_mask:0xf
	s_nop 1
	v_add_f32_dpp v64, v64, v64 row_mirror row_mask:0xf bank_mask:0xf
	s_nop 1
	v_mov_b32_dpp v65, v64 row_bcast:15 row_mask:0xa bank_mask:0xf
	s_and_saveexec_b64 s[20:21], s[6:7]
	s_cbranch_execz .LBB0_1417
	v_add_f32_e32 v64, v64, v65
	ds_add_f32 v100, v64 offset:38540
.LBB0_1417:
	s_or_b64 exec, exec, s[20:21]
	s_mov_b32 s1, 0xa000
	v_or3_b32 v114, v102, v96, s1
	v_lshl_add_u64 v[66:67], v[114:115], 1, s[18:19]
	v_mov_b32_e32 v64, v227
	v_lshlrev_b32_e32 v64, 16, v64
	v_mul_f32_e32 v65, 0xbfb8aa3b, v64
	v_exp_f32_e32 v65, v65
	s_nop 0
	v_add_f32_e32 v65, 1.0, v65
	v_div_scale_f32 v81, s[20:21], v65, v65, v64
	v_rcp_f32_e32 v82, v81
	v_div_scale_f32 v83, vcc, v64, v65, v64
	v_fma_f32 v84, -v81, v82, 1.0
	v_fmac_f32_e32 v82, v84, v82
	v_mul_f32_e32 v84, v83, v82
	v_fma_f32 v85, -v81, v84, v83
	v_fmac_f32_e32 v84, v85, v82
	v_fma_f32 v81, -v81, v84, v83
	v_div_fmas_f32 v81, v81, v82, v84
	v_div_fixup_f32 v64, v81, v65, v64
	v_mul_f32_e32 v68, v68, v64
	v_mul_f32_e32 v64, v68, v68
	s_nop 1
	v_mov_b32_dpp v64, v64 quad_perm:[1,0,3,2] row_mask:0xf bank_mask:0xf
	v_bfe_u32 v81, v68, 16, 1
	v_fmac_f32_e32 v64, v68, v68
	s_nop 1
	v_add_f32_dpp v64, v64, v64 quad_perm:[2,3,0,1] row_mask:0xf bank_mask:0xf
	v_add3_u32 v68, v68, v81, s28
	global_store_short_d16_hi v[66:67], v68, off
	s_nop 1
	v_add_f32_dpp v64, v64, v64 row_half_mirror row_mask:0xf bank_mask:0xf
	s_nop 1
	v_add_f32_dpp v64, v64, v64 row_mirror row_mask:0xf bank_mask:0xf
	s_nop 1
	v_mov_b32_dpp v65, v64 row_bcast:15 row_mask:0xa bank_mask:0xf
	s_and_saveexec_b64 s[20:21], s[6:7]
	s_cbranch_execz .LBB0_1419
	v_add_f32_e32 v64, v64, v65
	ds_add_f32 v100, v64 offset:38560
.LBB0_1419:
	s_or_b64 exec, exec, s[20:21]
	v_or3_b32 v114, v102, v96, s30
	v_lshl_add_u64 v[66:67], v[114:115], 1, s[18:19]
	v_mov_b32_e32 v64, v228
	v_lshlrev_b32_e32 v64, 16, v64
	v_mul_f32_e32 v65, 0xbfb8aa3b, v64
	v_exp_f32_e32 v65, v65
	s_nop 0
	v_add_f32_e32 v65, 1.0, v65
	v_div_scale_f32 v68, s[20:21], v65, v65, v64
	v_rcp_f32_e32 v81, v68
	v_div_scale_f32 v82, vcc, v64, v65, v64
	v_fma_f32 v83, -v68, v81, 1.0
	v_fmac_f32_e32 v81, v83, v81
	v_mul_f32_e32 v83, v82, v81
	v_fma_f32 v84, -v68, v83, v82
	v_fmac_f32_e32 v83, v84, v81
	v_fma_f32 v68, -v68, v83, v82
	v_div_fmas_f32 v68, v68, v81, v83
	v_div_fixup_f32 v64, v68, v65, v64
	v_mul_f32_e32 v68, v69, v64
	v_mul_f32_e32 v64, v68, v68
	s_nop 1
	v_mov_b32_dpp v64, v64 quad_perm:[1,0,3,2] row_mask:0xf bank_mask:0xf
	v_bfe_u32 v69, v68, 16, 1
	v_fmac_f32_e32 v64, v68, v68
	s_nop 1
	v_add_f32_dpp v64, v64, v64 quad_perm:[2,3,0,1] row_mask:0xf bank_mask:0xf
	v_add3_u32 v68, v68, v69, s28
	global_store_short_d16_hi v[66:67], v68, off
	s_nop 1
	v_add_f32_dpp v64, v64, v64 row_half_mirror row_mask:0xf bank_mask:0xf
	s_nop 1
	v_add_f32_dpp v64, v64, v64 row_mirror row_mask:0xf bank_mask:0xf
	s_nop 1
	v_mov_b32_dpp v65, v64 row_bcast:15 row_mask:0xa bank_mask:0xf
	s_and_saveexec_b64 s[20:21], s[6:7]
	s_cbranch_execz .LBB0_1421
	v_add_f32_e32 v64, v64, v65
	ds_add_f32 v100, v64 offset:38564
; __device__ __forceinline__ float bf2f(bf16r h) { return __uint_as_float(((unsigned)h) << 16); }
; __device__ __forceinline__ float siluf(float x) { return x / (1.f + __expf(-x)); }
; __device__ __forceinline__ void phase_ssd_out(const Params& p, int layer, unsigned char* smem) {
;     ...
;         const int t2 = relaunder(tid);
;         const int lane = t2 & 63, hi = lane >> 5, cl = lane & 31, wm = t2 >> 7, wn = (t2 >> 6) & 1;
; #pragma unroll
;         for (int mt = 0; mt < 2; mt++)
; #pragma unroll
;           for (int i = 0; i < 16; i++) {
;             int row = wm * 64 + mt * 32 + (i & 3) + 8 * (i >> 2) + 4 * hi;
;             int col = wn * 32 + cl;
;             bf16r* ybb = yb + (size_t)c * 128 * 1024 + h * 64;
;             unsigned off = (unsigned)(row * 1024 + col);
;             float z = bf2f(ybb[off]);
;             float y = ay[mt][0][i] * siluf(z);
;             *(ybb + off) = f2bf(y);
;             float sq = y * y;
; #pragma unroll
;             for (int o = 16; o > 0; o >>= 1) sq += __shfl_xor(sq, o, 64);
;             if (cl == 0) atomicAdd(&sRow[row], sq);
;             if ((i & 3) == 3) __builtin_amdgcn_sched_barrier(0);
;           }
.LBB0_1421:
	s_or_b64 exec, exec, s[20:21]
	v_or3_b32 v114, v102, v96, s31
	v_lshl_add_u64 v[66:67], v[114:115], 1, s[18:19]
	v_mov_b32_e32 v64, v229
	v_lshlrev_b32_e32 v64, 16, v64
	v_mul_f32_e32 v65, 0xbfb8aa3b, v64
	v_exp_f32_e32 v65, v65
	s_nop 0
	v_add_f32_e32 v65, 1.0, v65
	v_div_scale_f32 v68, s[20:21], v65, v65, v64
	v_rcp_f32_e32 v69, v68
	v_div_scale_f32 v81, vcc, v64, v65, v64
	v_fma_f32 v82, -v68, v69, 1.0
	v_fmac_f32_e32 v69, v82, v69
	v_mul_f32_e32 v82, v81, v69
	v_fma_f32 v83, -v68, v82, v81
	v_fmac_f32_e32 v82, v83, v69
	v_fma_f32 v68, -v68, v82, v81
	v_div_fmas_f32 v68, v68, v69, v82
	v_div_fixup_f32 v64, v68, v65, v64
	v_mul_f32_e32 v68, v70, v64
	v_mul_f32_e32 v64, v68, v68
	s_nop 1
	v_mov_b32_dpp v64, v64 quad_perm:[1,0,3,2] row_mask:0xf bank_mask:0xf
	v_bfe_u32 v69, v68, 16, 1
	v_fmac_f32_e32 v64, v68, v68
	s_nop 1
	v_add_f32_dpp v64, v64, v64 quad_perm:[2,3,0,1] row_mask:0xf bank_mask:0xf
	v_add3_u32 v68, v68, v69, s28
	global_store_short_d16_hi v[66:67], v68, off
	s_nop 1
	v_add_f32_dpp v64, v64, v64 row_half_mirror row_mask:0xf bank_mask:0xf
	s_nop 1
	v_add_f32_dpp v64, v64, v64 row_mirror row_mask:0xf bank_mask:0xf
	s_nop 1
	v_mov_b32_dpp v65, v64 row_bcast:15 row_mask:0xa bank_mask:0xf
	s_and_saveexec_b64 s[20:21], s[6:7]
	s_cbranch_execz .LBB0_1423
	v_add_f32_e32 v64, v64, v65
	ds_add_f32 v100, v64 offset:38568
.LBB0_1423:
	s_or_b64 exec, exec, s[20:21]
	v_or3_b32 v114, v102, v96, s34
	v_lshl_add_u64 v[66:67], v[114:115], 1, s[18:19]
	v_mov_b32_e32 v64, v231
	v_lshlrev_b32_e32 v64, 16, v64
	v_mul_f32_e32 v65, 0xbfb8aa3b, v64
	v_exp_f32_e32 v65, v65
	s_nop 0
	v_add_f32_e32 v65, 1.0, v65
	v_div_scale_f32 v68, s[20:21], v65, v65, v64
	v_rcp_f32_e32 v69, v68
	v_div_scale_f32 v70, vcc, v64, v65, v64
	v_fma_f32 v81, -v68, v69, 1.0
	v_fmac_f32_e32 v69, v81, v69
	v_mul_f32_e32 v81, v70, v69
	v_fma_f32 v82, -v68, v81, v70
	v_fmac_f32_e32 v81, v82, v69
	v_fma_f32 v68, -v68, v81, v70
	v_div_fmas_f32 v68, v68, v69, v81
	v_div_fixup_f32 v64, v68, v65, v64
	v_mul_f32_e32 v68, v71, v64
	v_mul_f32_e32 v64, v68, v68
	s_nop 1
	v_mov_b32_dpp v64, v64 quad_perm:[1,0,3,2] row_mask:0xf bank_mask:0xf
	v_bfe_u32 v69, v68, 16, 1
	v_fmac_f32_e32 v64, v68, v68
	s_nop 1
	v_add_f32_dpp v64, v64, v64 quad_perm:[2,3,0,1] row_mask:0xf bank_mask:0xf
	v_add3_u32 v68, v68, v69, s28
	global_store_short_d16_hi v[66:67], v68, off
	s_nop 1
	v_add_f32_dpp v64, v64, v64 row_half_mirror row_mask:0xf bank_mask:0xf
	s_nop 1
	v_add_f32_dpp v64, v64, v64 row_mirror row_mask:0xf bank_mask:0xf
	s_nop 1
	v_mov_b32_dpp v65, v64 row_bcast:15 row_mask:0xa bank_mask:0xf
	s_and_saveexec_b64 s[20:21], s[6:7]
	s_cbranch_execz .LBB0_1425
	v_add_f32_e32 v64, v64, v65
	ds_add_f32 v100, v64 offset:38572
.LBB0_1425:
	s_or_b64 exec, exec, s[20:21]
	v_or3_b32 v114, v102, v96, s35
	v_lshl_add_u64 v[66:67], v[114:115], 1, s[18:19]
	v_mov_b32_e32 v64, v232
	v_lshlrev_b32_e32 v64, 16, v64
	v_mul_f32_e32 v65, 0xbfb8aa3b, v64
	v_exp_f32_e32 v65, v65
	s_nop 0
	v_add_f32_e32 v65, 1.0, v65
	v_div_scale_f32 v68, s[20:21], v65, v65, v64
	v_rcp_f32_e32 v69, v68
	v_div_scale_f32 v70, vcc, v64, v65, v64
	v_fma_f32 v71, -v68, v69, 1.0
	v_fmac_f32_e32 v69, v71, v69
	v_mul_f32_e32 v71, v70, v69
	v_fma_f32 v81, -v68, v71, v70
	v_fmac_f32_e32 v71, v81, v69
	v_fma_f32 v68, -v68, v71, v70
	v_div_fmas_f32 v68, v68, v69, v71
	v_div_fixup_f32 v64, v68, v65, v64
	v_mul_f32_e32 v68, v72, v64
	v_mul_f32_e32 v64, v68, v68
	s_nop 1
	v_mov_b32_dpp v64, v64 quad_perm:[1,0,3,2] row_mask:0xf bank_mask:0xf
	v_bfe_u32 v69, v68, 16, 1
	v_fmac_f32_e32 v64, v68, v68
	s_nop 1
	v_add_f32_dpp v64, v64, v64 quad_perm:[2,3,0,1] row_mask:0xf bank_mask:0xf
	v_add3_u32 v68, v68, v69, s28
	global_store_short_d16_hi v[66:67], v68, off
	s_nop 1
	v_add_f32_dpp v64, v64, v64 row_half_mirror row_mask:0xf bank_mask:0xf
	s_nop 1
	v_add_f32_dpp v64, v64, v64 row_mirror row_mask:0xf bank_mask:0xf
	s_nop 1
	v_mov_b32_dpp v65, v64 row_bcast:15 row_mask:0xa bank_mask:0xf
	s_and_saveexec_b64 s[20:21], s[6:7]
	s_cbranch_execz .LBB0_1427
	v_add_f32_e32 v64, v64, v65
	ds_add_f32 v100, v64 offset:38592
.LBB0_1427:
	s_or_b64 exec, exec, s[20:21]
	v_or3_b32 v114, v102, v96, s36
	v_lshl_add_u64 v[66:67], v[114:115], 1, s[18:19]
	v_mov_b32_e32 v64, v233
	v_lshlrev_b32_e32 v64, 16, v64
	v_mul_f32_e32 v65, 0xbfb8aa3b, v64
	v_exp_f32_e32 v65, v65
	s_nop 0
	v_add_f32_e32 v65, 1.0, v65
	v_div_scale_f32 v68, s[20:21], v65, v65, v64
	v_rcp_f32_e32 v69, v68
	v_div_scale_f32 v70, vcc, v64, v65, v64
	v_fma_f32 v71, -v68, v69, 1.0
	v_fmac_f32_e32 v69, v71, v69
	v_mul_f32_e32 v71, v70, v69
	v_fma_f32 v72, -v68, v71, v70
	v_fmac_f32_e32 v71, v72, v69
	v_fma_f32 v68, -v68, v71, v70
	v_div_fmas_f32 v68, v68, v69, v71
	v_div_fixup_f32 v64, v68, v65, v64
	v_mul_f32_e32 v68, v73, v64
	v_mul_f32_e32 v64, v68, v68
	s_nop 1
	v_mov_b32_dpp v64, v64 quad_perm:[1,0,3,2] row_mask:0xf bank_mask:0xf
	v_bfe_u32 v69, v68, 16, 1
	v_fmac_f32_e32 v64, v68, v68
	s_nop 1
	v_add_f32_dpp v64, v64, v64 quad_perm:[2,3,0,1] row_mask:0xf bank_mask:0xf
	v_add3_u32 v68, v68, v69, s28
	global_store_short_d16_hi v[66:67], v68, off
	s_nop 1
	v_add_f32_dpp v64, v64, v64 row_half_mirror row_mask:0xf bank_mask:0xf
	s_nop 1
	v_add_f32_dpp v64, v64, v64 row_mirror row_mask:0xf bank_mask:0xf
	s_nop 1
	v_mov_b32_dpp v65, v64 row_bcast:15 row_mask:0xa bank_mask:0xf
	s_and_saveexec_b64 s[20:21], s[6:7]
	s_cbranch_execz .LBB0_1429
	v_add_f32_e32 v64, v64, v65
	ds_add_f32 v100, v64 offset:38596
; __device__ __forceinline__ float bf2f(bf16r h) { return __uint_as_float(((unsigned)h) << 16); }
; __device__ __forceinline__ float siluf(float x) { return x / (1.f + __expf(-x)); }
; __device__ __forceinline__ void phase_ssd_out(const Params& p, int layer, unsigned char* smem) {
;     ...
;         const int t2 = relaunder(tid);
;         const int lane = t2 & 63, hi = lane >> 5, cl = lane & 31, wm = t2 >> 7, wn = (t2 >> 6) & 1;
; #pragma unroll
;         for (int mt = 0; mt < 2; mt++)
; #pragma unroll
;           for (int i = 0; i < 16; i++) {
;             int row = wm * 64 + mt * 32 + (i & 3) + 8 * (i >> 2) + 4 * hi;
;             int col = wn * 32 + cl;
;             bf16r* ybb = yb + (size_t)c * 128 * 1024 + h * 64;
;             unsigned off = (unsigned)(row * 1024 + col);
;             float z = bf2f(ybb[off]);
;             float y = ay[mt][0][i] * siluf(z);
;             *(ybb + off) = f2bf(y);
;             float sq = y * y;
; #pragma unroll
;             for (int o = 16; o > 0; o >>= 1) sq += __shfl_xor(sq, o, 64);
;             if (cl == 0) atomicAdd(&sRow[row], sq);
;             if ((i & 3) == 3) __builtin_amdgcn_sched_barrier(0);
;           }
.LBB0_1429:
	s_or_b64 exec, exec, s[20:21]
	v_or3_b32 v114, v102, v96, s37
	v_lshl_add_u64 v[66:67], v[114:115], 1, s[18:19]
	v_mov_b32_e32 v64, v234
	v_lshlrev_b32_e32 v64, 16, v64
	v_mul_f32_e32 v65, 0xbfb8aa3b, v64
	v_exp_f32_e32 v65, v65
	s_nop 0
	v_add_f32_e32 v65, 1.0, v65
	v_div_scale_f32 v68, s[20:21], v65, v65, v64
	v_rcp_f32_e32 v69, v68
	v_div_scale_f32 v70, vcc, v64, v65, v64
	v_fma_f32 v71, -v68, v69, 1.0
	v_fmac_f32_e32 v69, v71, v69
	v_mul_f32_e32 v71, v70, v69
	v_fma_f32 v72, -v68, v71, v70
	v_fmac_f32_e32 v71, v72, v69
	v_fma_f32 v68, -v68, v71, v70
	v_div_fmas_f32 v68, v68, v69, v71
	v_div_fixup_f32 v64, v68, v65, v64
	v_mul_f32_e32 v68, v74, v64
	v_mul_f32_e32 v64, v68, v68
	s_nop 1
	v_mov_b32_dpp v64, v64 quad_perm:[1,0,3,2] row_mask:0xf bank_mask:0xf
	v_bfe_u32 v69, v68, 16, 1
	v_fmac_f32_e32 v64, v68, v68
	s_nop 1
	v_add_f32_dpp v64, v64, v64 quad_perm:[2,3,0,1] row_mask:0xf bank_mask:0xf
	v_add3_u32 v68, v68, v69, s28
	global_store_short_d16_hi v[66:67], v68, off
	s_nop 1
	v_add_f32_dpp v64, v64, v64 row_half_mirror row_mask:0xf bank_mask:0xf
	s_nop 1
	v_add_f32_dpp v64, v64, v64 row_mirror row_mask:0xf bank_mask:0xf
	s_nop 1
	v_mov_b32_dpp v65, v64 row_bcast:15 row_mask:0xa bank_mask:0xf
	s_and_saveexec_b64 s[20:21], s[6:7]
	s_cbranch_execz .LBB0_1431
	v_add_f32_e32 v64, v64, v65
	ds_add_f32 v100, v64 offset:38600
.LBB0_1431:
	s_or_b64 exec, exec, s[20:21]
	v_or3_b32 v114, v102, v96, s38
	v_lshl_add_u64 v[66:67], v[114:115], 1, s[18:19]
	v_mov_b32_e32 v64, v235
	v_lshlrev_b32_e32 v64, 16, v64
	v_mul_f32_e32 v65, 0xbfb8aa3b, v64
	v_exp_f32_e32 v65, v65
	s_nop 0
	v_add_f32_e32 v65, 1.0, v65
	v_div_scale_f32 v68, s[20:21], v65, v65, v64
	v_rcp_f32_e32 v69, v68
	v_div_scale_f32 v70, vcc, v64, v65, v64
	v_fma_f32 v71, -v68, v69, 1.0
	v_fmac_f32_e32 v69, v71, v69
	v_mul_f32_e32 v71, v70, v69
	v_fma_f32 v72, -v68, v71, v70
	v_fmac_f32_e32 v71, v72, v69
	v_fma_f32 v68, -v68, v71, v70
	v_div_fmas_f32 v68, v68, v69, v71
	v_div_fixup_f32 v64, v68, v65, v64
	v_mul_f32_e32 v68, v75, v64
	v_mul_f32_e32 v64, v68, v68
	s_nop 1
	v_mov_b32_dpp v64, v64 quad_perm:[1,0,3,2] row_mask:0xf bank_mask:0xf
	v_bfe_u32 v69, v68, 16, 1
	v_fmac_f32_e32 v64, v68, v68
	s_nop 1
	v_add_f32_dpp v64, v64, v64 quad_perm:[2,3,0,1] row_mask:0xf bank_mask:0xf
	v_add3_u32 v68, v68, v69, s28
	global_store_short_d16_hi v[66:67], v68, off
	s_nop 1
	v_add_f32_dpp v64, v64, v64 row_half_mirror row_mask:0xf bank_mask:0xf
	s_nop 1
	v_add_f32_dpp v64, v64, v64 row_mirror row_mask:0xf bank_mask:0xf
	s_nop 1
	v_mov_b32_dpp v65, v64 row_bcast:15 row_mask:0xa bank_mask:0xf
	s_and_saveexec_b64 s[20:21], s[6:7]
	s_cbranch_execz .LBB0_1433
	v_add_f32_e32 v64, v64, v65
	ds_add_f32 v100, v64 offset:38604
.LBB0_1433:
	s_or_b64 exec, exec, s[20:21]
	v_or3_b32 v114, v102, v96, s39
	v_lshl_add_u64 v[66:67], v[114:115], 1, s[18:19]
	v_mov_b32_e32 v64, v236
	v_lshlrev_b32_e32 v64, 16, v64
	v_mul_f32_e32 v65, 0xbfb8aa3b, v64
	v_exp_f32_e32 v65, v65
	s_nop 0
	v_add_f32_e32 v65, 1.0, v65
	v_div_scale_f32 v68, s[20:21], v65, v65, v64
	v_rcp_f32_e32 v69, v68
	v_div_scale_f32 v70, vcc, v64, v65, v64
	v_fma_f32 v71, -v68, v69, 1.0
	v_fmac_f32_e32 v69, v71, v69
	v_mul_f32_e32 v71, v70, v69
	v_fma_f32 v72, -v68, v71, v70
	v_fmac_f32_e32 v71, v72, v69
	v_fma_f32 v68, -v68, v71, v70
	v_div_fmas_f32 v68, v68, v69, v71
	v_div_fixup_f32 v64, v68, v65, v64
	v_mul_f32_e32 v68, v76, v64
	v_mul_f32_e32 v64, v68, v68
	s_nop 1
	v_mov_b32_dpp v64, v64 quad_perm:[1,0,3,2] row_mask:0xf bank_mask:0xf
	v_bfe_u32 v69, v68, 16, 1
	v_fmac_f32_e32 v64, v68, v68
	s_nop 1
	v_add_f32_dpp v64, v64, v64 quad_perm:[2,3,0,1] row_mask:0xf bank_mask:0xf
	v_add3_u32 v68, v68, v69, s28
	global_store_short_d16_hi v[66:67], v68, off
	s_nop 1
	v_add_f32_dpp v64, v64, v64 row_half_mirror row_mask:0xf bank_mask:0xf
	s_nop 1
	v_add_f32_dpp v64, v64, v64 row_mirror row_mask:0xf bank_mask:0xf
	s_nop 1
	v_mov_b32_dpp v65, v64 row_bcast:15 row_mask:0xa bank_mask:0xf
	s_and_saveexec_b64 s[20:21], s[6:7]
	s_cbranch_execz .LBB0_1435
	v_add_f32_e32 v64, v64, v65
	ds_add_f32 v100, v64 offset:38624
; __device__ __forceinline__ float bf2f(bf16r h) { return __uint_as_float(((unsigned)h) << 16); }
; __device__ __forceinline__ float siluf(float x) { return x / (1.f + __expf(-x)); }
; __device__ __forceinline__ void phase_ssd_out(const Params& p, int layer, unsigned char* smem) {
;     ...
;         const int t2 = relaunder(tid);
;         const int lane = t2 & 63, hi = lane >> 5, cl = lane & 31, wm = t2 >> 7, wn = (t2 >> 6) & 1;
; #pragma unroll
;         for (int mt = 0; mt < 2; mt++)
; #pragma unroll
;           for (int i = 0; i < 16; i++) {
;             int row = wm * 64 + mt * 32 + (i & 3) + 8 * (i >> 2) + 4 * hi;
;             int col = wn * 32 + cl;
;             bf16r* ybb = yb + (size_t)c * 128 * 1024 + h * 64;
;             unsigned off = (unsigned)(row * 1024 + col);
;             float z = bf2f(ybb[off]);
;             float y = ay[mt][0][i] * siluf(z);
;             *(ybb + off) = f2bf(y);
;             float sq = y * y;
; #pragma unroll
;             for (int o = 16; o > 0; o >>= 1) sq += __shfl_xor(sq, o, 64);
;             if (cl == 0) atomicAdd(&sRow[row], sq);
;             if ((i & 3) == 3) __builtin_amdgcn_sched_barrier(0);
;           }
.LBB0_1435:
	s_or_b64 exec, exec, s[20:21]
	v_or3_b32 v114, v102, v96, s40
	v_lshl_add_u64 v[66:67], v[114:115], 1, s[18:19]
	v_mov_b32_e32 v64, v237
	v_lshlrev_b32_e32 v64, 16, v64
	v_mul_f32_e32 v65, 0xbfb8aa3b, v64
	v_exp_f32_e32 v65, v65
	s_nop 0
	v_add_f32_e32 v65, 1.0, v65
	v_div_scale_f32 v68, s[20:21], v65, v65, v64
	v_rcp_f32_e32 v69, v68
	v_div_scale_f32 v70, vcc, v64, v65, v64
	v_fma_f32 v71, -v68, v69, 1.0
	v_fmac_f32_e32 v69, v71, v69
	v_mul_f32_e32 v71, v70, v69
	v_fma_f32 v72, -v68, v71, v70
	v_fmac_f32_e32 v71, v72, v69
	v_fma_f32 v68, -v68, v71, v70
	v_div_fmas_f32 v68, v68, v69, v71
	v_div_fixup_f32 v64, v68, v65, v64
	v_mul_f32_e32 v68, v77, v64
	v_mul_f32_e32 v64, v68, v68
	s_nop 1
	v_mov_b32_dpp v64, v64 quad_perm:[1,0,3,2] row_mask:0xf bank_mask:0xf
	v_bfe_u32 v69, v68, 16, 1
	v_fmac_f32_e32 v64, v68, v68
	s_nop 1
	v_add_f32_dpp v64, v64, v64 quad_perm:[2,3,0,1] row_mask:0xf bank_mask:0xf
	v_add3_u32 v68, v68, v69, s28
	global_store_short_d16_hi v[66:67], v68, off
	s_nop 1
	v_add_f32_dpp v64, v64, v64 row_half_mirror row_mask:0xf bank_mask:0xf
	s_nop 1
	v_add_f32_dpp v64, v64, v64 row_mirror row_mask:0xf bank_mask:0xf
	s_nop 1
	v_mov_b32_dpp v65, v64 row_bcast:15 row_mask:0xa bank_mask:0xf
	s_and_saveexec_b64 s[20:21], s[6:7]
	s_cbranch_execz .LBB0_1437
	v_add_f32_e32 v64, v64, v65
	ds_add_f32 v100, v64 offset:38628
.LBB0_1437:
	s_or_b64 exec, exec, s[20:21]
	v_or3_b32 v114, v102, v96, s41
	v_lshl_add_u64 v[66:67], v[114:115], 1, s[18:19]
	v_mov_b32_e32 v64, v238
	v_lshlrev_b32_e32 v64, 16, v64
	v_mul_f32_e32 v65, 0xbfb8aa3b, v64
	v_exp_f32_e32 v65, v65
	s_nop 0
	v_add_f32_e32 v65, 1.0, v65
	v_div_scale_f32 v68, s[20:21], v65, v65, v64
	v_rcp_f32_e32 v69, v68
	v_div_scale_f32 v70, vcc, v64, v65, v64
	v_fma_f32 v71, -v68, v69, 1.0
	v_fmac_f32_e32 v69, v71, v69
	v_mul_f32_e32 v71, v70, v69
	v_fma_f32 v72, -v68, v71, v70
	v_fmac_f32_e32 v71, v72, v69
	v_fma_f32 v68, -v68, v71, v70
	v_div_fmas_f32 v68, v68, v69, v71
	v_div_fixup_f32 v64, v68, v65, v64
	v_mul_f32_e32 v68, v78, v64
	v_mul_f32_e32 v64, v68, v68
	s_nop 1
	v_mov_b32_dpp v64, v64 quad_perm:[1,0,3,2] row_mask:0xf bank_mask:0xf
	v_bfe_u32 v69, v68, 16, 1
	v_fmac_f32_e32 v64, v68, v68
	s_nop 1
	v_add_f32_dpp v64, v64, v64 quad_perm:[2,3,0,1] row_mask:0xf bank_mask:0xf
	v_add3_u32 v68, v68, v69, s28
	global_store_short_d16_hi v[66:67], v68, off
	s_nop 1
	v_add_f32_dpp v64, v64, v64 row_half_mirror row_mask:0xf bank_mask:0xf
	s_nop 1
	v_add_f32_dpp v64, v64, v64 row_mirror row_mask:0xf bank_mask:0xf
	s_nop 1
	v_mov_b32_dpp v65, v64 row_bcast:15 row_mask:0xa bank_mask:0xf
	s_and_saveexec_b64 s[20:21], s[6:7]
	s_cbranch_execz .LBB0_1439
	v_add_f32_e32 v64, v64, v65
	ds_add_f32 v100, v64 offset:38632
.LBB0_1439:
	s_or_b64 exec, exec, s[20:21]
	v_or3_b32 v114, v102, v96, s42
	v_lshl_add_u64 v[66:67], v[114:115], 1, s[18:19]
	v_mov_b32_e32 v64, v239
	v_lshlrev_b32_e32 v64, 16, v64
	v_mul_f32_e32 v65, 0xbfb8aa3b, v64
	v_exp_f32_e32 v65, v65
	s_nop 0
	v_add_f32_e32 v65, 1.0, v65
	v_div_scale_f32 v68, s[18:19], v65, v65, v64
	v_rcp_f32_e32 v69, v68
	v_div_scale_f32 v70, vcc, v64, v65, v64
	v_fma_f32 v71, -v68, v69, 1.0
	v_fmac_f32_e32 v69, v71, v69
	v_mul_f32_e32 v71, v70, v69
	v_fma_f32 v72, -v68, v71, v70
	v_fmac_f32_e32 v71, v72, v69
	v_fma_f32 v68, -v68, v71, v70
	v_div_fmas_f32 v68, v68, v69, v71
	v_div_fixup_f32 v64, v68, v65, v64
	v_mul_f32_e32 v68, v79, v64
	v_mul_f32_e32 v64, v68, v68
	s_nop 1
	v_mov_b32_dpp v64, v64 quad_perm:[1,0,3,2] row_mask:0xf bank_mask:0xf
	v_bfe_u32 v69, v68, 16, 1
	v_fmac_f32_e32 v64, v68, v68
	s_nop 1
	v_add_f32_dpp v64, v64, v64 quad_perm:[2,3,0,1] row_mask:0xf bank_mask:0xf
	v_add3_u32 v68, v68, v69, s28
	global_store_short_d16_hi v[66:67], v68, off
	s_nop 1
	v_add_f32_dpp v64, v64, v64 row_half_mirror row_mask:0xf bank_mask:0xf
	s_nop 1
	v_add_f32_dpp v64, v64, v64 row_mirror row_mask:0xf bank_mask:0xf
	s_nop 1
	v_mov_b32_dpp v65, v64 row_bcast:15 row_mask:0xa bank_mask:0xf
	s_and_saveexec_b64 s[18:19], s[6:7]
	s_cbranch_execz .LBB0_1238
	v_add_f32_e32 v64, v64, v65
	ds_add_f32 v100, v64 offset:38636
	s_waitcnt lgkmcnt(0)
	s_branch .LBB0_1238

; __device__ __forceinline__ void phase_ret_out(const Params& p, unsigned char* smem) {
;     ...
;         const int t2 = relaunder(tid);
;         const int lane = t2 & 63, hi = lane >> 5, cl = lane & 31, wm = t2 >> 7, wn = (t2 >> 6) & 1;
; #pragma unroll
;         for (int mt = 0; mt < 2; mt++)
; #pragma unroll
;           for (int i = 0; i < 16; i++) {
;             int row = wm * 64 + mt * 32 + (i & 3) + 8 * (i >> 2) + 4 * hi;
;             float s1 = 0.f, s2 = 0.f;
; #pragma unroll
;             for (int nt = 0; nt < 2; nt++) {
;               int col = wn * 64 + nt * 32 + cl;
;               float y = acc[mt][nt][i];
;               *(ypre + rowbase + et * 128 + (unsigned)(row * 1024 + col)) = f2bf(y);
;               s1 += y; s2 += y * y;
;             }
; #pragma unroll
;             for (int o = 16; o > 0; o >>= 1) { s1 += __shfl_xor(s1, o, 64); s2 += __shfl_xor(s2, o, 64); }
;             if (cl == 0) { atomicAdd(&sSum[row], s1); atomicAdd(&sSq[row], s2); }
;             if ((i & 3) == 3) __builtin_amdgcn_sched_barrier(0);
;           }
.LBB0_1503:
	v_and_b32_e32 v67, 64, v199
	v_add_u32_e32 v73, 64, v67
	v_add_f32_e32 v67, 0, v50
	v_add_f32_e32 v69, v34, v67
	v_xor_b32_e32 v67, 16, v199
	v_cmp_lt_i32_e32 vcc, v67, v73
	v_mul_f32_e32 v68, v50, v50
	v_fmac_f32_e32 v68, v34, v34
	v_cndmask_b32_e32 v67, v199, v67, vcc
	v_lshlrev_b32_e32 v67, 2, v67
	s_nop 1
	v_add_f32_dpp v69, v69, v69 quad_perm:[1,0,3,2] row_mask:0xf bank_mask:0xf
	s_nop 1
	v_mov_b32_dpp v72, v68 quad_perm:[1,0,3,2] row_mask:0xf bank_mask:0xf
	v_mov_b32_e32 v0, v176
	s_lshl_b64 s[6:7], s[6:7], 1
	s_waitcnt lgkmcnt(0)
	v_add_f32_e32 v70, v68, v72
	v_xor_b32_e32 v68, 8, v199
	v_cmp_lt_i32_e32 vcc, v68, v73
	v_lshrrev_b32_e32 v74, 3, v0
	v_ashrrev_i32_e32 v66, 1, v0
	v_cndmask_b32_e32 v68, v199, v68, vcc
	v_lshlrev_b32_e32 v68, 2, v68
	s_nop 1
	v_add_f32_dpp v72, v69, v69 quad_perm:[2,3,0,1] row_mask:0xf bank_mask:0xf
	v_and_b32_e32 v74, 4, v74
	v_and_or_b32 v66, v66, s26, v74
	s_nop 1
	v_add_f32_dpp v74, v70, v70 quad_perm:[2,3,0,1] row_mask:0xf bank_mask:0xf
	v_and_b32_e32 v71, 31, v0
	v_xor_b32_e32 v69, 4, v199
	v_cmp_lt_i32_e32 vcc, v69, v73
	s_add_u32 s14, s9, s6
	v_cndmask_b32_e32 v69, v199, v69, vcc
	v_lshlrev_b32_e32 v70, 2, v69
	s_nop 1
	v_add_f32_dpp v72, v72, v72 row_half_mirror row_mask:0xf bank_mask:0xf
	s_nop 1
	v_add_f32_dpp v74, v74, v74 row_half_mirror row_mask:0xf bank_mask:0xf
	v_cmp_eq_u32_e32 vcc, 16, v71
	v_xor_b32_e32 v71, 2, v199
	s_addc_u32 s15, s19, s7
	v_cmp_lt_i32_e64 s[6:7], v71, v73
	v_cndmask_b32_e64 v71, v199, v71, s[6:7]
	v_lshlrev_b32_e32 v71, 2, v71
	s_nop 1
	v_mov_b32_dpp v75, v72 row_mirror row_mask:0xf bank_mask:0xf
	s_nop 1
	v_mov_b32_dpp v78, v74 row_mirror row_mask:0xf bank_mask:0xf
	v_bfe_u32 v76, v50, 16, 1
	v_add3_u32 v79, v50, v76, s30
	v_xor_b32_e32 v50, 1, v199
	v_and_b32_e32 v69, 0x5f, v0
	v_cmp_lt_i32_e64 s[6:7], v50, v73
	v_lshl_or_b32 v0, v66, 10, v69
	v_lshl_add_u64 v[76:77], v[0:1], 1, s[14:15]
	v_cndmask_b32_e64 v50, v199, v50, s[6:7]
	v_add_f32_e32 v0, v72, v75
	v_add_f32_e32 v72, v74, v78
	v_lshlrev_b32_e32 v50, 2, v50
	s_nop 1
	v_mov_b32_dpp v73, v0 row_bcast:15 row_mask:0xa bank_mask:0xf
	s_nop 1
	v_mov_b32_dpp v74, v72 row_bcast:15 row_mask:0xa bank_mask:0xf
	v_bfe_u32 v75, v34, 16, 1
	v_add3_u32 v34, v34, v75, s30
	global_store_short_d16_hi v[76:77], v79, off
	global_store_short_d16_hi v[76:77], v34, off offset:64
	s_and_saveexec_b64 s[6:7], vcc
	s_cbranch_execz .LBB0_1505
	v_lshlrev_b32_e32 v34, 2, v66
	v_add_u32_e32 v75, 0x11800, v34
	v_add_f32_e32 v0, v0, v73
	v_add_u32_e32 v34, 0x11a00, v34
	v_add_f32_e32 v72, v72, v74
	ds_add_f32 v75, v0
	ds_add_f32 v34, v72
.LBB0_1505:
	s_or_b64 exec, exec, s[6:7]
	v_add_f32_e32 v0, 0, v51
	v_mul_f32_e32 v34, v51, v51
	v_add_f32_e32 v0, v35, v0
	v_fmac_f32_e32 v34, v35, v35
	s_nop 1
	v_add_f32_dpp v0, v0, v0 quad_perm:[1,0,3,2] row_mask:0xf bank_mask:0xf
	s_nop 1
	v_add_f32_dpp v34, v34, v34 quad_perm:[1,0,3,2] row_mask:0xf bank_mask:0xf
	v_bfe_u32 v75, v51, 16, 1
	v_add3_u32 v78, v51, v75, s30
	s_nop 1
	v_add_f32_dpp v0, v0, v0 quad_perm:[2,3,0,1] row_mask:0xf bank_mask:0xf
	s_nop 1
	v_mov_b32_dpp v73, v34 quad_perm:[2,3,0,1] row_mask:0xf bank_mask:0xf
	v_add_f32_e32 v72, v34, v73
	s_nop 1
	v_add_f32_dpp v73, v0, v0 row_half_mirror row_mask:0xf bank_mask:0xf
	s_nop 1
	v_mov_b32_dpp v74, v72 row_half_mirror row_mask:0xf bank_mask:0xf
	v_or_b32_e32 v34, 1, v66
	v_add_f32_e32 v72, v72, v74
	s_nop 1
	v_mov_b32_dpp v76, v73 row_mirror row_mask:0xf bank_mask:0xf
	s_nop 1
	v_add_f32_dpp v51, v72, v72 row_mirror row_mask:0xf bank_mask:0xf
	v_lshl_or_b32 v0, v34, 10, v69
	v_lshl_add_u64 v[74:75], v[0:1], 1, s[14:15]
	global_store_short_d16_hi v[74:75], v78, off
	v_add_f32_e32 v0, v73, v76
	s_nop 1
	v_mov_b32_dpp v72, v0 row_bcast:15 row_mask:0xa bank_mask:0xf
	s_nop 1
	v_mov_b32_dpp v73, v51 row_bcast:15 row_mask:0xa bank_mask:0xf
	v_bfe_u32 v76, v35, 16, 1
	v_add3_u32 v35, v35, v76, s30
	global_store_short_d16_hi v[74:75], v35, off offset:64
	s_and_saveexec_b64 s[6:7], vcc
	s_cbranch_execz .LBB0_1507
	v_lshlrev_b32_e32 v34, 2, v34
	v_add_u32_e32 v35, 0x11800, v34
	v_add_f32_e32 v0, v0, v72
	v_add_u32_e32 v34, 0x11a00, v34
	v_add_f32_e32 v51, v51, v73
	ds_add_f32 v35, v0
	ds_add_f32 v34, v51
.LBB0_1507:
	s_or_b64 exec, exec, s[6:7]
	v_add_f32_e32 v0, 0, v52
	v_mul_f32_e32 v34, v52, v52
	v_add_f32_e32 v0, v36, v0
	v_fmac_f32_e32 v34, v36, v36
	s_nop 1
	v_add_f32_dpp v0, v0, v0 quad_perm:[1,0,3,2] row_mask:0xf bank_mask:0xf
	s_nop 1
	v_add_f32_dpp v34, v34, v34 quad_perm:[1,0,3,2] row_mask:0xf bank_mask:0xf
	v_bfe_u32 v73, v52, 16, 1
	v_add3_u32 v76, v52, v73, s30
	s_nop 1
	v_add_f32_dpp v0, v0, v0 quad_perm:[2,3,0,1] row_mask:0xf bank_mask:0xf
	s_nop 1
	v_mov_b32_dpp v51, v34 quad_perm:[2,3,0,1] row_mask:0xf bank_mask:0xf
	v_add_f32_e32 v35, v34, v51
	s_nop 1
	v_add_f32_dpp v51, v0, v0 row_half_mirror row_mask:0xf bank_mask:0xf
	s_nop 1
	v_mov_b32_dpp v72, v35 row_half_mirror row_mask:0xf bank_mask:0xf
	v_or_b32_e32 v34, 2, v66
	v_add_f32_e32 v35, v35, v72
	s_nop 1
	v_mov_b32_dpp v74, v51 row_mirror row_mask:0xf bank_mask:0xf
	s_nop 1
	v_add_f32_dpp v35, v35, v35 row_mirror row_mask:0xf bank_mask:0xf
	v_lshl_or_b32 v0, v34, 10, v69
	v_lshl_add_u64 v[72:73], v[0:1], 1, s[14:15]
	global_store_short_d16_hi v[72:73], v76, off
	v_add_f32_e32 v0, v51, v74
	s_nop 1
	v_mov_b32_dpp v51, v0 row_bcast:15 row_mask:0xa bank_mask:0xf
	s_nop 1
	v_mov_b32_dpp v52, v35 row_bcast:15 row_mask:0xa bank_mask:0xf
	v_bfe_u32 v74, v36, 16, 1
	v_add3_u32 v36, v36, v74, s30
	global_store_short_d16_hi v[72:73], v36, off offset:64
	s_and_saveexec_b64 s[6:7], vcc
	s_cbranch_execz .LBB0_1509
	v_lshlrev_b32_e32 v34, 2, v34
	v_add_u32_e32 v36, 0x11800, v34
	v_add_f32_e32 v0, v0, v51
	v_add_u32_e32 v34, 0x11a00, v34
	v_add_f32_e32 v35, v35, v52
	ds_add_f32 v36, v0
	ds_add_f32 v34, v35
; __device__ __forceinline__ void phase_ret_out(const Params& p, unsigned char* smem) {
;     ...
;         const int t2 = relaunder(tid);
;         const int lane = t2 & 63, hi = lane >> 5, cl = lane & 31, wm = t2 >> 7, wn = (t2 >> 6) & 1;
; #pragma unroll
;         for (int mt = 0; mt < 2; mt++)
; #pragma unroll
;           for (int i = 0; i < 16; i++) {
;             int row = wm * 64 + mt * 32 + (i & 3) + 8 * (i >> 2) + 4 * hi;
;             float s1 = 0.f, s2 = 0.f;
; #pragma unroll
;             for (int nt = 0; nt < 2; nt++) {
;               int col = wn * 64 + nt * 32 + cl;
;               float y = acc[mt][nt][i];
;               *(ypre + rowbase + et * 128 + (unsigned)(row * 1024 + col)) = f2bf(y);
;               s1 += y; s2 += y * y;
;             }
; #pragma unroll
;             for (int o = 16; o > 0; o >>= 1) { s1 += __shfl_xor(s1, o, 64); s2 += __shfl_xor(s2, o, 64); }
;             if (cl == 0) { atomicAdd(&sSum[row], s1); atomicAdd(&sSq[row], s2); }
;             if ((i & 3) == 3) __builtin_amdgcn_sched_barrier(0);
;           }
.LBB0_1509:
	s_or_b64 exec, exec, s[6:7]
	v_add_f32_e32 v0, 0, v53
	v_mul_f32_e32 v34, v53, v53
	v_add_f32_e32 v0, v37, v0
	v_fmac_f32_e32 v34, v37, v37
	s_nop 1
	v_add_f32_dpp v0, v0, v0 quad_perm:[1,0,3,2] row_mask:0xf bank_mask:0xf
	s_nop 1
	v_add_f32_dpp v34, v34, v34 quad_perm:[1,0,3,2] row_mask:0xf bank_mask:0xf
	v_bfe_u32 v52, v53, 16, 1
	v_add3_u32 v73, v53, v52, s30
	s_nop 1
	v_add_f32_dpp v0, v0, v0 quad_perm:[2,3,0,1] row_mask:0xf bank_mask:0xf
	s_nop 1
	v_mov_b32_dpp v36, v34 quad_perm:[2,3,0,1] row_mask:0xf bank_mask:0xf
	v_add_f32_e32 v35, v34, v36
	s_nop 1
	v_add_f32_dpp v36, v0, v0 row_half_mirror row_mask:0xf bank_mask:0xf
	s_nop 1
	v_add_f32_dpp v35, v35, v35 row_half_mirror row_mask:0xf bank_mask:0xf
	v_or_b32_e32 v34, 3, v66
	s_nop 1
	v_mov_b32_dpp v51, v36 row_mirror row_mask:0xf bank_mask:0xf
	s_nop 1
	v_add_f32_dpp v35, v35, v35 row_mirror row_mask:0xf bank_mask:0xf
	v_lshl_or_b32 v0, v34, 10, v69
	v_lshl_add_u64 v[52:53], v[0:1], 1, s[14:15]
	global_store_short_d16_hi v[52:53], v73, off
	v_add_f32_e32 v0, v36, v51
	s_nop 1
	v_mov_b32_dpp v36, v0 row_bcast:15 row_mask:0xa bank_mask:0xf
	s_nop 1
	v_mov_b32_dpp v51, v35 row_bcast:15 row_mask:0xa bank_mask:0xf
	v_bfe_u32 v72, v37, 16, 1
	v_add3_u32 v37, v37, v72, s30
	global_store_short_d16_hi v[52:53], v37, off offset:64
	s_and_saveexec_b64 s[6:7], vcc
	s_cbranch_execz .LBB0_1511
	v_lshlrev_b32_e32 v34, 2, v34
	v_add_u32_e32 v37, 0x11800, v34
	v_add_f32_e32 v0, v0, v36
	v_add_u32_e32 v34, 0x11a00, v34
	v_add_f32_e32 v35, v35, v51
	ds_add_f32 v37, v0
	ds_add_f32 v34, v35
.LBB0_1511:
	s_or_b64 exec, exec, s[6:7]
	v_add_f32_e32 v0, 0, v54
	v_mul_f32_e32 v34, v54, v54
	v_add_f32_e32 v0, v38, v0
	v_fmac_f32_e32 v34, v38, v38
	s_nop 1
	v_add_f32_dpp v0, v0, v0 quad_perm:[1,0,3,2] row_mask:0xf bank_mask:0xf
	s_nop 1
	v_add_f32_dpp v34, v34, v34 quad_perm:[1,0,3,2] row_mask:0xf bank_mask:0xf
	v_bfe_u32 v51, v54, 16, 1
	v_add3_u32 v51, v54, v51, s30
	s_nop 1
	v_add_f32_dpp v0, v0, v0 quad_perm:[2,3,0,1] row_mask:0xf bank_mask:0xf
	s_nop 1
	v_mov_b32_dpp v36, v34 quad_perm:[2,3,0,1] row_mask:0xf bank_mask:0xf
	v_add_f32_e32 v35, v34, v36
	s_nop 1
	v_add_f32_dpp v36, v0, v0 row_half_mirror row_mask:0xf bank_mask:0xf
	s_nop 1
	v_add_f32_dpp v35, v35, v35 row_half_mirror row_mask:0xf bank_mask:0xf
	v_or_b32_e32 v34, 8, v66
	s_nop 1
	v_mov_b32_dpp v37, v36 row_mirror row_mask:0xf bank_mask:0xf
	s_nop 1
	v_add_f32_dpp v35, v35, v35 row_mirror row_mask:0xf bank_mask:0xf
	v_lshl_or_b32 v0, v34, 10, v69
	v_lshl_add_u64 v[52:53], v[0:1], 1, s[14:15]
	global_store_short_d16_hi v[52:53], v51, off
	v_add_f32_e32 v0, v36, v37
	s_nop 1
	v_mov_b32_dpp v36, v0 row_bcast:15 row_mask:0xa bank_mask:0xf
	s_nop 1
	v_mov_b32_dpp v37, v35 row_bcast:15 row_mask:0xa bank_mask:0xf
	v_bfe_u32 v51, v38, 16, 1
	v_add3_u32 v38, v38, v51, s30
	global_store_short_d16_hi v[52:53], v38, off offset:64
	s_and_saveexec_b64 s[6:7], vcc
	s_cbranch_execz .LBB0_1513
	v_lshlrev_b32_e32 v34, 2, v34
	v_add_u32_e32 v38, 0x11800, v34
	v_add_f32_e32 v0, v0, v36
	v_add_u32_e32 v34, 0x11a00, v34
	v_add_f32_e32 v35, v35, v37
	ds_add_f32 v38, v0
	ds_add_f32 v34, v35
.LBB0_1513:
	s_or_b64 exec, exec, s[6:7]
	v_add_f32_e32 v0, 0, v55
	v_mul_f32_e32 v34, v55, v55
	v_add_f32_e32 v0, v39, v0
	v_fmac_f32_e32 v34, v39, v39
	s_nop 1
	v_add_f32_dpp v0, v0, v0 quad_perm:[1,0,3,2] row_mask:0xf bank_mask:0xf
	s_nop 1
	v_add_f32_dpp v34, v34, v34 quad_perm:[1,0,3,2] row_mask:0xf bank_mask:0xf
	v_bfe_u32 v38, v55, 16, 1
	v_add3_u32 v38, v55, v38, s30
	s_nop 1
	v_add_f32_dpp v0, v0, v0 quad_perm:[2,3,0,1] row_mask:0xf bank_mask:0xf
	s_nop 1
	v_mov_b32_dpp v36, v34 quad_perm:[2,3,0,1] row_mask:0xf bank_mask:0xf
	v_add_f32_e32 v35, v34, v36
	s_nop 1
	v_add_f32_dpp v36, v0, v0 row_half_mirror row_mask:0xf bank_mask:0xf
	s_nop 1
	v_add_f32_dpp v35, v35, v35 row_half_mirror row_mask:0xf bank_mask:0xf
	v_or_b32_e32 v34, 9, v66
	s_nop 1
	v_mov_b32_dpp v37, v36 row_mirror row_mask:0xf bank_mask:0xf
	s_nop 1
	v_add_f32_dpp v35, v35, v35 row_mirror row_mask:0xf bank_mask:0xf
	v_lshl_or_b32 v0, v34, 10, v69
	v_lshl_add_u64 v[52:53], v[0:1], 1, s[14:15]
	global_store_short_d16_hi v[52:53], v38, off
	v_add_f32_e32 v0, v36, v37
	s_nop 1
	v_mov_b32_dpp v36, v0 row_bcast:15 row_mask:0xa bank_mask:0xf
	s_nop 1
	v_mov_b32_dpp v37, v35 row_bcast:15 row_mask:0xa bank_mask:0xf
	v_bfe_u32 v38, v39, 16, 1
	v_add3_u32 v38, v39, v38, s30
	global_store_short_d16_hi v[52:53], v38, off offset:64
	s_and_saveexec_b64 s[6:7], vcc
	s_cbranch_execz .LBB0_1515
	v_lshlrev_b32_e32 v34, 2, v34
	v_add_u32_e32 v38, 0x11800, v34
	v_add_f32_e32 v0, v0, v36
	v_add_u32_e32 v34, 0x11a00, v34
	v_add_f32_e32 v35, v35, v37
	ds_add_f32 v38, v0
	ds_add_f32 v34, v35
.LBB0_1515:
	s_or_b64 exec, exec, s[6:7]
	v_add_f32_e32 v0, 0, v56
	v_mul_f32_e32 v34, v56, v56
	v_add_f32_e32 v0, v40, v0
	v_fmac_f32_e32 v34, v40, v40
	s_nop 1
	v_add_f32_dpp v0, v0, v0 quad_perm:[1,0,3,2] row_mask:0xf bank_mask:0xf
	s_nop 1
	v_add_f32_dpp v34, v34, v34 quad_perm:[1,0,3,2] row_mask:0xf bank_mask:0xf
	v_bfe_u32 v38, v56, 16, 1
	v_add3_u32 v52, v56, v38, s30
	s_nop 1
	v_add_f32_dpp v0, v0, v0 quad_perm:[2,3,0,1] row_mask:0xf bank_mask:0xf
	s_nop 1
	v_mov_b32_dpp v36, v34 quad_perm:[2,3,0,1] row_mask:0xf bank_mask:0xf
	v_add_f32_e32 v35, v34, v36
	s_nop 1
	v_add_f32_dpp v36, v0, v0 row_half_mirror row_mask:0xf bank_mask:0xf
	s_nop 1
	v_add_f32_dpp v35, v35, v35 row_half_mirror row_mask:0xf bank_mask:0xf
	v_or_b32_e32 v34, 10, v66
	s_nop 1
	v_mov_b32_dpp v37, v36 row_mirror row_mask:0xf bank_mask:0xf
	s_nop 1
	v_add_f32_dpp v35, v35, v35 row_mirror row_mask:0xf bank_mask:0xf
	v_lshl_or_b32 v0, v34, 10, v69
	v_lshl_add_u64 v[38:39], v[0:1], 1, s[14:15]
	global_store_short_d16_hi v[38:39], v52, off
	v_add_f32_e32 v0, v36, v37
	s_nop 1
	v_mov_b32_dpp v36, v0 row_bcast:15 row_mask:0xa bank_mask:0xf
	s_nop 1
	v_mov_b32_dpp v37, v35 row_bcast:15 row_mask:0xa bank_mask:0xf
	v_bfe_u32 v51, v40, 16, 1
	v_add3_u32 v40, v40, v51, s30
	global_store_short_d16_hi v[38:39], v40, off offset:64
	s_and_saveexec_b64 s[6:7], vcc
	s_cbranch_execz .LBB0_1517
	v_lshlrev_b32_e32 v34, 2, v34
	v_add_u32_e32 v38, 0x11800, v34
	v_add_f32_e32 v0, v0, v36
	v_add_u32_e32 v34, 0x11a00, v34
	v_add_f32_e32 v35, v35, v37
	ds_add_f32 v38, v0
	ds_add_f32 v34, v35
; __device__ __forceinline__ void phase_ret_out(const Params& p, unsigned char* smem) {
;     ...
;         const int t2 = relaunder(tid);
;         const int lane = t2 & 63, hi = lane >> 5, cl = lane & 31, wm = t2 >> 7, wn = (t2 >> 6) & 1;
; #pragma unroll
;         for (int mt = 0; mt < 2; mt++)
; #pragma unroll
;           for (int i = 0; i < 16; i++) {
;             int row = wm * 64 + mt * 32 + (i & 3) + 8 * (i >> 2) + 4 * hi;
;             float s1 = 0.f, s2 = 0.f;
; #pragma unroll
;             for (int nt = 0; nt < 2; nt++) {
;               int col = wn * 64 + nt * 32 + cl;
;               float y = acc[mt][nt][i];
;               *(ypre + rowbase + et * 128 + (unsigned)(row * 1024 + col)) = f2bf(y);
;               s1 += y; s2 += y * y;
;             }
; #pragma unroll
;             for (int o = 16; o > 0; o >>= 1) { s1 += __shfl_xor(s1, o, 64); s2 += __shfl_xor(s2, o, 64); }
;             if (cl == 0) { atomicAdd(&sSum[row], s1); atomicAdd(&sSq[row], s2); }
;             if ((i & 3) == 3) __builtin_amdgcn_sched_barrier(0);
;           }
.LBB0_1517:
	s_or_b64 exec, exec, s[6:7]
	v_add_f32_e32 v0, 0, v57
	v_mul_f32_e32 v34, v57, v57
	v_add_f32_e32 v0, v41, v0
	v_fmac_f32_e32 v34, v41, v41
	s_nop 1
	v_add_f32_dpp v0, v0, v0 quad_perm:[1,0,3,2] row_mask:0xf bank_mask:0xf
	s_nop 1
	v_add_f32_dpp v34, v34, v34 quad_perm:[1,0,3,2] row_mask:0xf bank_mask:0xf
	v_bfe_u32 v38, v57, 16, 1
	v_add3_u32 v51, v57, v38, s30
	s_nop 1
	v_add_f32_dpp v0, v0, v0 quad_perm:[2,3,0,1] row_mask:0xf bank_mask:0xf
	s_nop 1
	v_mov_b32_dpp v36, v34 quad_perm:[2,3,0,1] row_mask:0xf bank_mask:0xf
	v_add_f32_e32 v35, v34, v36
	s_nop 1
	v_add_f32_dpp v36, v0, v0 row_half_mirror row_mask:0xf bank_mask:0xf
	s_nop 1
	v_add_f32_dpp v35, v35, v35 row_half_mirror row_mask:0xf bank_mask:0xf
	v_or_b32_e32 v34, 11, v66
	s_nop 1
	v_mov_b32_dpp v37, v36 row_mirror row_mask:0xf bank_mask:0xf
	s_nop 1
	v_add_f32_dpp v35, v35, v35 row_mirror row_mask:0xf bank_mask:0xf
	v_lshl_or_b32 v0, v34, 10, v69
	v_lshl_add_u64 v[38:39], v[0:1], 1, s[14:15]
	global_store_short_d16_hi v[38:39], v51, off
	v_add_f32_e32 v0, v36, v37
	s_nop 1
	v_mov_b32_dpp v36, v0 row_bcast:15 row_mask:0xa bank_mask:0xf
	s_nop 1
	v_mov_b32_dpp v37, v35 row_bcast:15 row_mask:0xa bank_mask:0xf
	v_bfe_u32 v40, v41, 16, 1
	v_add3_u32 v40, v41, v40, s30
	global_store_short_d16_hi v[38:39], v40, off offset:64
	s_and_saveexec_b64 s[6:7], vcc
	s_cbranch_execz .LBB0_1519
	v_lshlrev_b32_e32 v34, 2, v34
	v_add_u32_e32 v38, 0x11800, v34
	v_add_f32_e32 v0, v0, v36
	v_add_u32_e32 v34, 0x11a00, v34
	v_add_f32_e32 v35, v35, v37
	ds_add_f32 v38, v0
	ds_add_f32 v34, v35
.LBB0_1519:
	s_or_b64 exec, exec, s[6:7]
	v_add_f32_e32 v0, 0, v58
	v_mul_f32_e32 v34, v58, v58
	v_add_f32_e32 v0, v42, v0
	v_fmac_f32_e32 v34, v42, v42
	s_nop 1
	v_add_f32_dpp v0, v0, v0 quad_perm:[1,0,3,2] row_mask:0xf bank_mask:0xf
	s_nop 1
	v_add_f32_dpp v34, v34, v34 quad_perm:[1,0,3,2] row_mask:0xf bank_mask:0xf
	v_bfe_u32 v38, v58, 16, 1
	v_add3_u32 v41, v58, v38, s30
	s_nop 1
	v_add_f32_dpp v0, v0, v0 quad_perm:[2,3,0,1] row_mask:0xf bank_mask:0xf
	s_nop 1
	v_mov_b32_dpp v36, v34 quad_perm:[2,3,0,1] row_mask:0xf bank_mask:0xf
	v_add_f32_e32 v35, v34, v36
	s_nop 1
	v_add_f32_dpp v36, v0, v0 row_half_mirror row_mask:0xf bank_mask:0xf
	s_nop 1
	v_add_f32_dpp v35, v35, v35 row_half_mirror row_mask:0xf bank_mask:0xf
	v_or_b32_e32 v34, 16, v66
	s_nop 1
	v_mov_b32_dpp v37, v36 row_mirror row_mask:0xf bank_mask:0xf
	s_nop 1
	v_add_f32_dpp v35, v35, v35 row_mirror row_mask:0xf bank_mask:0xf
	v_lshl_or_b32 v0, v34, 10, v69
	v_lshl_add_u64 v[38:39], v[0:1], 1, s[14:15]
	global_store_short_d16_hi v[38:39], v41, off
	v_add_f32_e32 v0, v36, v37
	s_nop 1
	v_mov_b32_dpp v36, v0 row_bcast:15 row_mask:0xa bank_mask:0xf
	s_nop 1
	v_mov_b32_dpp v37, v35 row_bcast:15 row_mask:0xa bank_mask:0xf
	v_bfe_u32 v40, v42, 16, 1
	v_add3_u32 v40, v42, v40, s30
	global_store_short_d16_hi v[38:39], v40, off offset:64
	s_and_saveexec_b64 s[6:7], vcc
	s_cbranch_execz .LBB0_1521
	v_lshlrev_b32_e32 v34, 2, v34
	v_add_u32_e32 v38, 0x11800, v34
	v_add_f32_e32 v0, v0, v36
	v_add_u32_e32 v34, 0x11a00, v34
	v_add_f32_e32 v35, v35, v37
	ds_add_f32 v38, v0
	ds_add_f32 v34, v35
.LBB0_1521:
	s_or_b64 exec, exec, s[6:7]
	v_add_f32_e32 v0, 0, v59
	v_mul_f32_e32 v34, v59, v59
	v_add_f32_e32 v0, v43, v0
	v_fmac_f32_e32 v34, v43, v43
	s_nop 1
	v_add_f32_dpp v0, v0, v0 quad_perm:[1,0,3,2] row_mask:0xf bank_mask:0xf
	s_nop 1
	v_add_f32_dpp v34, v34, v34 quad_perm:[1,0,3,2] row_mask:0xf bank_mask:0xf
	v_bfe_u32 v38, v59, 16, 1
	v_add3_u32 v41, v59, v38, s30
	s_nop 1
	v_add_f32_dpp v0, v0, v0 quad_perm:[2,3,0,1] row_mask:0xf bank_mask:0xf
	s_nop 1
	v_mov_b32_dpp v36, v34 quad_perm:[2,3,0,1] row_mask:0xf bank_mask:0xf
	v_add_f32_e32 v35, v34, v36
	s_nop 1
	v_add_f32_dpp v36, v0, v0 row_half_mirror row_mask:0xf bank_mask:0xf
	s_nop 1
	v_add_f32_dpp v35, v35, v35 row_half_mirror row_mask:0xf bank_mask:0xf
	v_or_b32_e32 v34, 17, v66
	s_nop 1
	v_mov_b32_dpp v37, v36 row_mirror row_mask:0xf bank_mask:0xf
	s_nop 1
	v_add_f32_dpp v35, v35, v35 row_mirror row_mask:0xf bank_mask:0xf
	v_lshl_or_b32 v0, v34, 10, v69
	v_lshl_add_u64 v[38:39], v[0:1], 1, s[14:15]
	global_store_short_d16_hi v[38:39], v41, off
	v_add_f32_e32 v0, v36, v37
	s_nop 1
	v_mov_b32_dpp v36, v0 row_bcast:15 row_mask:0xa bank_mask:0xf
	s_nop 1
	v_mov_b32_dpp v37, v35 row_bcast:15 row_mask:0xa bank_mask:0xf
	v_bfe_u32 v40, v43, 16, 1
	v_add3_u32 v40, v43, v40, s30
	global_store_short_d16_hi v[38:39], v40, off offset:64
	s_and_saveexec_b64 s[6:7], vcc
	s_cbranch_execz .LBB0_1523
	v_lshlrev_b32_e32 v34, 2, v34
	v_add_u32_e32 v38, 0x11800, v34
	v_add_f32_e32 v0, v0, v36
	v_add_u32_e32 v34, 0x11a00, v34
	v_add_f32_e32 v35, v35, v37
	ds_add_f32 v38, v0
	ds_add_f32 v34, v35
.LBB0_1523:
	s_or_b64 exec, exec, s[6:7]
	v_add_f32_e32 v0, 0, v60
	v_mul_f32_e32 v34, v60, v60
	v_add_f32_e32 v0, v44, v0
	v_fmac_f32_e32 v34, v44, v44
	s_nop 1
	v_add_f32_dpp v0, v0, v0 quad_perm:[1,0,3,2] row_mask:0xf bank_mask:0xf
	s_nop 1
	v_add_f32_dpp v34, v34, v34 quad_perm:[1,0,3,2] row_mask:0xf bank_mask:0xf
	v_bfe_u32 v38, v60, 16, 1
	v_add3_u32 v41, v60, v38, s30
	s_nop 1
	v_add_f32_dpp v0, v0, v0 quad_perm:[2,3,0,1] row_mask:0xf bank_mask:0xf
	s_nop 1
	v_mov_b32_dpp v36, v34 quad_perm:[2,3,0,1] row_mask:0xf bank_mask:0xf
	v_add_f32_e32 v35, v34, v36
	s_nop 1
	v_add_f32_dpp v36, v0, v0 row_half_mirror row_mask:0xf bank_mask:0xf
	s_nop 1
	v_add_f32_dpp v35, v35, v35 row_half_mirror row_mask:0xf bank_mask:0xf
	v_or_b32_e32 v34, 18, v66
	s_nop 1
	v_mov_b32_dpp v37, v36 row_mirror row_mask:0xf bank_mask:0xf
	s_nop 1
	v_add_f32_dpp v35, v35, v35 row_mirror row_mask:0xf bank_mask:0xf
	v_lshl_or_b32 v0, v34, 10, v69
	v_lshl_add_u64 v[38:39], v[0:1], 1, s[14:15]
	global_store_short_d16_hi v[38:39], v41, off
	v_add_f32_e32 v0, v36, v37
	s_nop 1
	v_mov_b32_dpp v36, v0 row_bcast:15 row_mask:0xa bank_mask:0xf
	s_nop 1
	v_mov_b32_dpp v37, v35 row_bcast:15 row_mask:0xa bank_mask:0xf
	v_bfe_u32 v40, v44, 16, 1
	v_add3_u32 v40, v44, v40, s30
	global_store_short_d16_hi v[38:39], v40, off offset:64
	s_and_saveexec_b64 s[6:7], vcc
	s_cbranch_execz .LBB0_1525
	v_lshlrev_b32_e32 v34, 2, v34
	v_add_u32_e32 v38, 0x11800, v34
	v_add_f32_e32 v0, v0, v36
	v_add_u32_e32 v34, 0x11a00, v34
	v_add_f32_e32 v35, v35, v37
	ds_add_f32 v38, v0
	ds_add_f32 v34, v35
; __device__ __forceinline__ void phase_ret_out(const Params& p, unsigned char* smem) {
;     ...
;         const int t2 = relaunder(tid);
;         const int lane = t2 & 63, hi = lane >> 5, cl = lane & 31, wm = t2 >> 7, wn = (t2 >> 6) & 1;
; #pragma unroll
;         for (int mt = 0; mt < 2; mt++)
; #pragma unroll
;           for (int i = 0; i < 16; i++) {
;             int row = wm * 64 + mt * 32 + (i & 3) + 8 * (i >> 2) + 4 * hi;
;             float s1 = 0.f, s2 = 0.f;
; #pragma unroll
;             for (int nt = 0; nt < 2; nt++) {
;               int col = wn * 64 + nt * 32 + cl;
;               float y = acc[mt][nt][i];
;               *(ypre + rowbase + et * 128 + (unsigned)(row * 1024 + col)) = f2bf(y);
;               s1 += y; s2 += y * y;
;             }
; #pragma unroll
;             for (int o = 16; o > 0; o >>= 1) { s1 += __shfl_xor(s1, o, 64); s2 += __shfl_xor(s2, o, 64); }
;             if (cl == 0) { atomicAdd(&sSum[row], s1); atomicAdd(&sSq[row], s2); }
;             if ((i & 3) == 3) __builtin_amdgcn_sched_barrier(0);
;           }
.LBB0_1525:
	s_or_b64 exec, exec, s[6:7]
	v_add_f32_e32 v0, 0, v61
	v_mul_f32_e32 v34, v61, v61
	v_add_f32_e32 v0, v45, v0
	v_fmac_f32_e32 v34, v45, v45
	s_nop 1
	v_add_f32_dpp v0, v0, v0 quad_perm:[1,0,3,2] row_mask:0xf bank_mask:0xf
	s_nop 1
	v_add_f32_dpp v34, v34, v34 quad_perm:[1,0,3,2] row_mask:0xf bank_mask:0xf
	v_bfe_u32 v38, v61, 16, 1
	v_add3_u32 v41, v61, v38, s30
	s_nop 1
	v_add_f32_dpp v0, v0, v0 quad_perm:[2,3,0,1] row_mask:0xf bank_mask:0xf
	s_nop 1
	v_mov_b32_dpp v36, v34 quad_perm:[2,3,0,1] row_mask:0xf bank_mask:0xf
	v_add_f32_e32 v35, v34, v36
	s_nop 1
	v_add_f32_dpp v36, v0, v0 row_half_mirror row_mask:0xf bank_mask:0xf
	s_nop 1
	v_add_f32_dpp v35, v35, v35 row_half_mirror row_mask:0xf bank_mask:0xf
	v_or_b32_e32 v34, 19, v66
	s_nop 1
	v_mov_b32_dpp v37, v36 row_mirror row_mask:0xf bank_mask:0xf
	s_nop 1
	v_add_f32_dpp v35, v35, v35 row_mirror row_mask:0xf bank_mask:0xf
	v_lshl_or_b32 v0, v34, 10, v69
	v_lshl_add_u64 v[38:39], v[0:1], 1, s[14:15]
	global_store_short_d16_hi v[38:39], v41, off
	v_add_f32_e32 v0, v36, v37
	s_nop 1
	v_mov_b32_dpp v36, v0 row_bcast:15 row_mask:0xa bank_mask:0xf
	s_nop 1
	v_mov_b32_dpp v37, v35 row_bcast:15 row_mask:0xa bank_mask:0xf
	v_bfe_u32 v40, v45, 16, 1
	v_add3_u32 v40, v45, v40, s30
	global_store_short_d16_hi v[38:39], v40, off offset:64
	s_and_saveexec_b64 s[6:7], vcc
	s_cbranch_execz .LBB0_1527
	v_lshlrev_b32_e32 v34, 2, v34
	v_add_u32_e32 v38, 0x11800, v34
	v_add_f32_e32 v0, v0, v36
	v_add_u32_e32 v34, 0x11a00, v34
	v_add_f32_e32 v35, v35, v37
	ds_add_f32 v38, v0
	ds_add_f32 v34, v35
.LBB0_1527:
	s_or_b64 exec, exec, s[6:7]
	v_add_f32_e32 v0, 0, v62
	v_mul_f32_e32 v34, v62, v62
	v_add_f32_e32 v0, v46, v0
	v_fmac_f32_e32 v34, v46, v46
	s_nop 1
	v_add_f32_dpp v0, v0, v0 quad_perm:[1,0,3,2] row_mask:0xf bank_mask:0xf
	s_nop 1
	v_add_f32_dpp v34, v34, v34 quad_perm:[1,0,3,2] row_mask:0xf bank_mask:0xf
	v_bfe_u32 v38, v62, 16, 1
	v_add3_u32 v41, v62, v38, s30
	s_nop 1
	v_add_f32_dpp v0, v0, v0 quad_perm:[2,3,0,1] row_mask:0xf bank_mask:0xf
	s_nop 1
	v_mov_b32_dpp v36, v34 quad_perm:[2,3,0,1] row_mask:0xf bank_mask:0xf
	v_add_f32_e32 v35, v34, v36
	s_nop 1
	v_add_f32_dpp v36, v0, v0 row_half_mirror row_mask:0xf bank_mask:0xf
	s_nop 1
	v_add_f32_dpp v35, v35, v35 row_half_mirror row_mask:0xf bank_mask:0xf
	v_or_b32_e32 v34, 24, v66
	s_nop 1
	v_mov_b32_dpp v37, v36 row_mirror row_mask:0xf bank_mask:0xf
	s_nop 1
	v_add_f32_dpp v35, v35, v35 row_mirror row_mask:0xf bank_mask:0xf
	v_lshl_or_b32 v0, v34, 10, v69
	v_lshl_add_u64 v[38:39], v[0:1], 1, s[14:15]
	global_store_short_d16_hi v[38:39], v41, off
	v_add_f32_e32 v0, v36, v37
	s_nop 1
	v_mov_b32_dpp v36, v0 row_bcast:15 row_mask:0xa bank_mask:0xf
	s_nop 1
	v_mov_b32_dpp v37, v35 row_bcast:15 row_mask:0xa bank_mask:0xf
	v_bfe_u32 v40, v46, 16, 1
	v_add3_u32 v40, v46, v40, s30
	global_store_short_d16_hi v[38:39], v40, off offset:64
	s_and_saveexec_b64 s[6:7], vcc
	s_cbranch_execz .LBB0_1529
	v_lshlrev_b32_e32 v34, 2, v34
	v_add_u32_e32 v38, 0x11800, v34
	v_add_f32_e32 v0, v0, v36
	v_add_u32_e32 v34, 0x11a00, v34
	v_add_f32_e32 v35, v35, v37
	ds_add_f32 v38, v0
	ds_add_f32 v34, v35
.LBB0_1529:
	s_or_b64 exec, exec, s[6:7]
	v_add_f32_e32 v0, 0, v63
	v_mul_f32_e32 v34, v63, v63
	v_add_f32_e32 v0, v47, v0
	v_fmac_f32_e32 v34, v47, v47
	s_nop 1
	v_add_f32_dpp v0, v0, v0 quad_perm:[1,0,3,2] row_mask:0xf bank_mask:0xf
	s_nop 1
	v_add_f32_dpp v34, v34, v34 quad_perm:[1,0,3,2] row_mask:0xf bank_mask:0xf
	v_bfe_u32 v38, v63, 16, 1
	v_add3_u32 v41, v63, v38, s30
	s_nop 1
	v_add_f32_dpp v0, v0, v0 quad_perm:[2,3,0,1] row_mask:0xf bank_mask:0xf
	s_nop 1
	v_mov_b32_dpp v36, v34 quad_perm:[2,3,0,1] row_mask:0xf bank_mask:0xf
	v_add_f32_e32 v35, v34, v36
	s_nop 1
	v_add_f32_dpp v36, v0, v0 row_half_mirror row_mask:0xf bank_mask:0xf
	s_nop 1
	v_add_f32_dpp v35, v35, v35 row_half_mirror row_mask:0xf bank_mask:0xf
	v_or_b32_e32 v34, 25, v66
	s_nop 1
	v_mov_b32_dpp v37, v36 row_mirror row_mask:0xf bank_mask:0xf
	s_nop 1
	v_add_f32_dpp v35, v35, v35 row_mirror row_mask:0xf bank_mask:0xf
	v_lshl_or_b32 v0, v34, 10, v69
	v_lshl_add_u64 v[38:39], v[0:1], 1, s[14:15]
	global_store_short_d16_hi v[38:39], v41, off
	v_add_f32_e32 v0, v36, v37
	s_nop 1
	v_mov_b32_dpp v36, v0 row_bcast:15 row_mask:0xa bank_mask:0xf
	s_nop 1
	v_mov_b32_dpp v37, v35 row_bcast:15 row_mask:0xa bank_mask:0xf
	v_bfe_u32 v40, v47, 16, 1
	v_add3_u32 v40, v47, v40, s30
	global_store_short_d16_hi v[38:39], v40, off offset:64
	s_and_saveexec_b64 s[6:7], vcc
	s_cbranch_execz .LBB0_1531
	v_lshlrev_b32_e32 v34, 2, v34
	v_add_u32_e32 v38, 0x11800, v34
	v_add_f32_e32 v0, v0, v36
	v_add_u32_e32 v34, 0x11a00, v34
	v_add_f32_e32 v35, v35, v37
	ds_add_f32 v38, v0
	ds_add_f32 v34, v35
.LBB0_1531:
	s_or_b64 exec, exec, s[6:7]
	v_add_f32_e32 v0, 0, v64
	v_mul_f32_e32 v34, v64, v64
	v_add_f32_e32 v0, v48, v0
	v_fmac_f32_e32 v34, v48, v48
	s_nop 1
	v_add_f32_dpp v0, v0, v0 quad_perm:[1,0,3,2] row_mask:0xf bank_mask:0xf
	s_nop 1
	v_add_f32_dpp v34, v34, v34 quad_perm:[1,0,3,2] row_mask:0xf bank_mask:0xf
	v_bfe_u32 v38, v64, 16, 1
	v_add3_u32 v41, v64, v38, s30
	s_nop 1
	v_add_f32_dpp v0, v0, v0 quad_perm:[2,3,0,1] row_mask:0xf bank_mask:0xf
	s_nop 1
	v_mov_b32_dpp v36, v34 quad_perm:[2,3,0,1] row_mask:0xf bank_mask:0xf
	v_add_f32_e32 v35, v34, v36
	s_nop 1
	v_add_f32_dpp v36, v0, v0 row_half_mirror row_mask:0xf bank_mask:0xf
	s_nop 1
	v_add_f32_dpp v35, v35, v35 row_half_mirror row_mask:0xf bank_mask:0xf
	v_or_b32_e32 v34, 26, v66
	s_nop 1
	v_mov_b32_dpp v37, v36 row_mirror row_mask:0xf bank_mask:0xf
	s_nop 1
	v_add_f32_dpp v35, v35, v35 row_mirror row_mask:0xf bank_mask:0xf
	v_lshl_or_b32 v0, v34, 10, v69
	v_lshl_add_u64 v[38:39], v[0:1], 1, s[14:15]
	global_store_short_d16_hi v[38:39], v41, off
	v_add_f32_e32 v0, v36, v37
	s_nop 1
	v_mov_b32_dpp v36, v0 row_bcast:15 row_mask:0xa bank_mask:0xf
	s_nop 1
	v_mov_b32_dpp v37, v35 row_bcast:15 row_mask:0xa bank_mask:0xf
	v_bfe_u32 v40, v48, 16, 1
	v_add3_u32 v40, v48, v40, s30
	global_store_short_d16_hi v[38:39], v40, off offset:64
	s_and_saveexec_b64 s[6:7], vcc
	s_cbranch_execz .LBB0_1533
	v_lshlrev_b32_e32 v34, 2, v34
	v_add_u32_e32 v38, 0x11800, v34
	v_add_f32_e32 v0, v0, v36
	v_add_u32_e32 v34, 0x11a00, v34
	v_add_f32_e32 v35, v35, v37
	ds_add_f32 v38, v0
	ds_add_f32 v34, v35
; __device__ __forceinline__ void phase_ret_out(const Params& p, unsigned char* smem) {
;     ...
;         const int t2 = relaunder(tid);
;         const int lane = t2 & 63, hi = lane >> 5, cl = lane & 31, wm = t2 >> 7, wn = (t2 >> 6) & 1;
; #pragma unroll
;         for (int mt = 0; mt < 2; mt++)
; #pragma unroll
;           for (int i = 0; i < 16; i++) {
;             int row = wm * 64 + mt * 32 + (i & 3) + 8 * (i >> 2) + 4 * hi;
;             float s1 = 0.f, s2 = 0.f;
; #pragma unroll
;             for (int nt = 0; nt < 2; nt++) {
;               int col = wn * 64 + nt * 32 + cl;
;               float y = acc[mt][nt][i];
;               *(ypre + rowbase + et * 128 + (unsigned)(row * 1024 + col)) = f2bf(y);
;               s1 += y; s2 += y * y;
;             }
; #pragma unroll
;             for (int o = 16; o > 0; o >>= 1) { s1 += __shfl_xor(s1, o, 64); s2 += __shfl_xor(s2, o, 64); }
;             if (cl == 0) { atomicAdd(&sSum[row], s1); atomicAdd(&sSq[row], s2); }
;             if ((i & 3) == 3) __builtin_amdgcn_sched_barrier(0);
;           }
.LBB0_1533:
	s_or_b64 exec, exec, s[6:7]
	v_add_f32_e32 v0, 0, v65
	v_mul_f32_e32 v34, v65, v65
	v_add_f32_e32 v0, v49, v0
	v_fmac_f32_e32 v34, v49, v49
	s_nop 1
	v_add_f32_dpp v0, v0, v0 quad_perm:[1,0,3,2] row_mask:0xf bank_mask:0xf
	s_nop 1
	v_add_f32_dpp v34, v34, v34 quad_perm:[1,0,3,2] row_mask:0xf bank_mask:0xf
	v_bfe_u32 v38, v65, 16, 1
	v_add3_u32 v41, v65, v38, s30
	s_nop 1
	v_add_f32_dpp v0, v0, v0 quad_perm:[2,3,0,1] row_mask:0xf bank_mask:0xf
	s_nop 1
	v_mov_b32_dpp v36, v34 quad_perm:[2,3,0,1] row_mask:0xf bank_mask:0xf
	v_add_f32_e32 v35, v34, v36
	s_nop 1
	v_add_f32_dpp v36, v0, v0 row_half_mirror row_mask:0xf bank_mask:0xf
	s_nop 1
	v_add_f32_dpp v35, v35, v35 row_half_mirror row_mask:0xf bank_mask:0xf
	v_or_b32_e32 v34, 27, v66
	s_nop 1
	v_mov_b32_dpp v37, v36 row_mirror row_mask:0xf bank_mask:0xf
	s_nop 1
	v_add_f32_dpp v35, v35, v35 row_mirror row_mask:0xf bank_mask:0xf
	v_lshl_or_b32 v0, v34, 10, v69
	v_lshl_add_u64 v[38:39], v[0:1], 1, s[14:15]
	global_store_short_d16_hi v[38:39], v41, off
	v_add_f32_e32 v0, v36, v37
	s_nop 1
	v_mov_b32_dpp v36, v0 row_bcast:15 row_mask:0xa bank_mask:0xf
	s_nop 1
	v_mov_b32_dpp v37, v35 row_bcast:15 row_mask:0xa bank_mask:0xf
	v_bfe_u32 v40, v49, 16, 1
	v_add3_u32 v40, v49, v40, s30
	global_store_short_d16_hi v[38:39], v40, off offset:64
	s_and_saveexec_b64 s[6:7], vcc
	s_cbranch_execz .LBB0_1535
	v_lshlrev_b32_e32 v34, 2, v34
	v_add_u32_e32 v38, 0x11800, v34
	v_add_f32_e32 v0, v0, v36
	v_add_u32_e32 v34, 0x11a00, v34
	v_add_f32_e32 v35, v35, v37
	ds_add_f32 v38, v0
	ds_add_f32 v34, v35
.LBB0_1535:
	s_or_b64 exec, exec, s[6:7]
	v_add_f32_e32 v0, 0, v18
	v_mul_f32_e32 v34, v2, v2
	v_add_f32_e32 v0, v0, v2
	v_fmac_f32_e32 v34, v18, v18
	s_nop 1
	v_add_f32_dpp v0, v0, v0 quad_perm:[1,0,3,2] row_mask:0xf bank_mask:0xf
	s_nop 1
	v_add_f32_dpp v34, v34, v34 quad_perm:[1,0,3,2] row_mask:0xf bank_mask:0xf
	v_bfe_u32 v38, v18, 16, 1
	v_add3_u32 v41, v18, v38, s30
	s_nop 1
	v_add_f32_dpp v0, v0, v0 quad_perm:[2,3,0,1] row_mask:0xf bank_mask:0xf
	s_nop 1
	v_mov_b32_dpp v36, v34 quad_perm:[2,3,0,1] row_mask:0xf bank_mask:0xf
	v_add_f32_e32 v35, v34, v36
	s_nop 1
	v_add_f32_dpp v36, v0, v0 row_half_mirror row_mask:0xf bank_mask:0xf
	s_nop 1
	v_add_f32_dpp v35, v35, v35 row_half_mirror row_mask:0xf bank_mask:0xf
	v_or_b32_e32 v34, 32, v66
	s_nop 1
	v_mov_b32_dpp v37, v36 row_mirror row_mask:0xf bank_mask:0xf
	s_nop 1
	v_add_f32_dpp v18, v35, v35 row_mirror row_mask:0xf bank_mask:0xf
	v_lshl_or_b32 v0, v34, 10, v69
	v_lshl_add_u64 v[38:39], v[0:1], 1, s[14:15]
	global_store_short_d16_hi v[38:39], v41, off
	v_add_f32_e32 v0, v36, v37
	s_nop 1
	v_mov_b32_dpp v35, v0 row_bcast:15 row_mask:0xa bank_mask:0xf
	s_nop 1
	v_mov_b32_dpp v36, v18 row_bcast:15 row_mask:0xa bank_mask:0xf
	v_bfe_u32 v37, v2, 16, 1
	v_add3_u32 v2, v2, v37, s30
	global_store_short_d16_hi v[38:39], v2, off offset:64
	s_and_saveexec_b64 s[6:7], vcc
	s_cbranch_execz .LBB0_1537
	v_lshlrev_b32_e32 v2, 2, v34
	v_add_u32_e32 v34, 0x11800, v2
	v_add_f32_e32 v0, v0, v35
	v_add_u32_e32 v2, 0x11a00, v2
	v_add_f32_e32 v18, v18, v36
	ds_add_f32 v34, v0
	ds_add_f32 v2, v18
.LBB0_1537:
	s_or_b64 exec, exec, s[6:7]
	v_add_f32_e32 v0, 0, v19
	v_mul_f32_e32 v2, v3, v3
	v_add_f32_e32 v0, v0, v3
	v_fmac_f32_e32 v2, v19, v19
	s_nop 1
	v_add_f32_dpp v0, v0, v0 quad_perm:[1,0,3,2] row_mask:0xf bank_mask:0xf
	s_nop 1
	v_add_f32_dpp v2, v2, v2 quad_perm:[1,0,3,2] row_mask:0xf bank_mask:0xf
	v_bfe_u32 v36, v19, 16, 1
	v_add3_u32 v39, v19, v36, s30
	s_nop 1
	v_add_f32_dpp v0, v0, v0 quad_perm:[2,3,0,1] row_mask:0xf bank_mask:0xf
	s_nop 1
	v_mov_b32_dpp v34, v2 quad_perm:[2,3,0,1] row_mask:0xf bank_mask:0xf
	v_add_f32_e32 v18, v2, v34
	s_nop 1
	v_add_f32_dpp v34, v0, v0 row_half_mirror row_mask:0xf bank_mask:0xf
	s_nop 1
	v_add_f32_dpp v18, v18, v18 row_half_mirror row_mask:0xf bank_mask:0xf
	v_or_b32_e32 v2, 33, v66
	s_nop 1
	v_mov_b32_dpp v35, v34 row_mirror row_mask:0xf bank_mask:0xf
	s_nop 1
	v_add_f32_dpp v18, v18, v18 row_mirror row_mask:0xf bank_mask:0xf
	v_lshl_or_b32 v0, v2, 10, v69
	v_lshl_add_u64 v[36:37], v[0:1], 1, s[14:15]
	global_store_short_d16_hi v[36:37], v39, off
	v_add_f32_e32 v0, v34, v35
	s_nop 1
	v_mov_b32_dpp v19, v0 row_bcast:15 row_mask:0xa bank_mask:0xf
	s_nop 1
	v_mov_b32_dpp v34, v18 row_bcast:15 row_mask:0xa bank_mask:0xf
	v_bfe_u32 v35, v3, 16, 1
	v_add3_u32 v3, v3, v35, s30
	global_store_short_d16_hi v[36:37], v3, off offset:64
	s_and_saveexec_b64 s[6:7], vcc
	s_cbranch_execz .LBB0_1539
	v_lshlrev_b32_e32 v2, 2, v2
	v_add_u32_e32 v3, 0x11800, v2
	v_add_f32_e32 v0, v0, v19
	v_add_u32_e32 v2, 0x11a00, v2
	v_add_f32_e32 v18, v18, v34
	ds_add_f32 v3, v0
	ds_add_f32 v2, v18
.LBB0_1539:
	s_or_b64 exec, exec, s[6:7]
	v_add_f32_e32 v0, 0, v20
	v_mul_f32_e32 v2, v4, v4
	v_add_f32_e32 v0, v0, v4
	v_fmac_f32_e32 v2, v20, v20
	s_nop 1
	v_add_f32_dpp v0, v0, v0 quad_perm:[1,0,3,2] row_mask:0xf bank_mask:0xf
	s_nop 1
	v_add_f32_dpp v2, v2, v2 quad_perm:[1,0,3,2] row_mask:0xf bank_mask:0xf
	v_bfe_u32 v34, v20, 16, 1
	v_add3_u32 v20, v20, v34, s30
	s_nop 1
	v_add_f32_dpp v0, v0, v0 quad_perm:[2,3,0,1] row_mask:0xf bank_mask:0xf
	s_nop 1
	v_mov_b32_dpp v18, v2 quad_perm:[2,3,0,1] row_mask:0xf bank_mask:0xf
	v_add_f32_e32 v3, v2, v18
	s_nop 1
	v_add_f32_dpp v18, v0, v0 row_half_mirror row_mask:0xf bank_mask:0xf
	s_nop 1
	v_add_f32_dpp v3, v3, v3 row_half_mirror row_mask:0xf bank_mask:0xf
	v_or_b32_e32 v2, 34, v66
	s_nop 1
	v_mov_b32_dpp v19, v18 row_mirror row_mask:0xf bank_mask:0xf
	s_nop 1
	v_add_f32_dpp v3, v3, v3 row_mirror row_mask:0xf bank_mask:0xf
	v_lshl_or_b32 v0, v2, 10, v69
	v_lshl_add_u64 v[34:35], v[0:1], 1, s[14:15]
	global_store_short_d16_hi v[34:35], v20, off
	v_add_f32_e32 v0, v18, v19
	s_nop 1
	v_mov_b32_dpp v18, v0 row_bcast:15 row_mask:0xa bank_mask:0xf
	s_nop 1
	v_mov_b32_dpp v19, v3 row_bcast:15 row_mask:0xa bank_mask:0xf
	v_bfe_u32 v20, v4, 16, 1
	v_add3_u32 v4, v4, v20, s30
	global_store_short_d16_hi v[34:35], v4, off offset:64
	s_and_saveexec_b64 s[6:7], vcc
	s_cbranch_execz .LBB0_1541
	v_lshlrev_b32_e32 v2, 2, v2
	v_add_u32_e32 v4, 0x11800, v2
	v_add_f32_e32 v0, v0, v18
	v_add_u32_e32 v2, 0x11a00, v2
	v_add_f32_e32 v3, v3, v19
	ds_add_f32 v4, v0
	ds_add_f32 v2, v3
; __device__ __forceinline__ void phase_ret_out(const Params& p, unsigned char* smem) {
;     ...
;         const int t2 = relaunder(tid);
;         const int lane = t2 & 63, hi = lane >> 5, cl = lane & 31, wm = t2 >> 7, wn = (t2 >> 6) & 1;
; #pragma unroll
;         for (int mt = 0; mt < 2; mt++)
; #pragma unroll
;           for (int i = 0; i < 16; i++) {
;             int row = wm * 64 + mt * 32 + (i & 3) + 8 * (i >> 2) + 4 * hi;
;             float s1 = 0.f, s2 = 0.f;
; #pragma unroll
;             for (int nt = 0; nt < 2; nt++) {
;               int col = wn * 64 + nt * 32 + cl;
;               float y = acc[mt][nt][i];
;               *(ypre + rowbase + et * 128 + (unsigned)(row * 1024 + col)) = f2bf(y);
;               s1 += y; s2 += y * y;
;             }
; #pragma unroll
;             for (int o = 16; o > 0; o >>= 1) { s1 += __shfl_xor(s1, o, 64); s2 += __shfl_xor(s2, o, 64); }
;             if (cl == 0) { atomicAdd(&sSum[row], s1); atomicAdd(&sSq[row], s2); }
;             if ((i & 3) == 3) __builtin_amdgcn_sched_barrier(0);
;           }
.LBB0_1541:
	s_or_b64 exec, exec, s[6:7]
	v_add_f32_e32 v0, 0, v21
	v_mul_f32_e32 v2, v5, v5
	v_add_f32_e32 v0, v0, v5
	v_fmac_f32_e32 v2, v21, v21
	s_nop 1
	v_add_f32_dpp v0, v0, v0 quad_perm:[1,0,3,2] row_mask:0xf bank_mask:0xf
	s_nop 1
	v_add_f32_dpp v2, v2, v2 quad_perm:[1,0,3,2] row_mask:0xf bank_mask:0xf
	v_bfe_u32 v19, v21, 16, 1
	v_add3_u32 v19, v21, v19, s30
	s_nop 1
	v_add_f32_dpp v0, v0, v0 quad_perm:[2,3,0,1] row_mask:0xf bank_mask:0xf
	s_nop 1
	v_mov_b32_dpp v4, v2 quad_perm:[2,3,0,1] row_mask:0xf bank_mask:0xf
	v_add_f32_e32 v3, v2, v4
	s_nop 1
	v_add_f32_dpp v4, v0, v0 row_half_mirror row_mask:0xf bank_mask:0xf
	s_nop 1
	v_add_f32_dpp v3, v3, v3 row_half_mirror row_mask:0xf bank_mask:0xf
	v_or_b32_e32 v2, 35, v66
	s_nop 1
	v_mov_b32_dpp v18, v4 row_mirror row_mask:0xf bank_mask:0xf
	s_nop 1
	v_add_f32_dpp v3, v3, v3 row_mirror row_mask:0xf bank_mask:0xf
	v_lshl_or_b32 v0, v2, 10, v69
	v_lshl_add_u64 v[20:21], v[0:1], 1, s[14:15]
	global_store_short_d16_hi v[20:21], v19, off
	v_add_f32_e32 v0, v4, v18
	s_nop 1
	v_mov_b32_dpp v4, v0 row_bcast:15 row_mask:0xa bank_mask:0xf
	s_nop 1
	v_mov_b32_dpp v18, v3 row_bcast:15 row_mask:0xa bank_mask:0xf
	v_bfe_u32 v19, v5, 16, 1
	v_add3_u32 v5, v5, v19, s30
	global_store_short_d16_hi v[20:21], v5, off offset:64
	s_and_saveexec_b64 s[6:7], vcc
	s_cbranch_execz .LBB0_1543
	v_lshlrev_b32_e32 v2, 2, v2
	v_add_u32_e32 v5, 0x11800, v2
	v_add_f32_e32 v0, v0, v4
	v_add_u32_e32 v2, 0x11a00, v2
	v_add_f32_e32 v3, v3, v18
	ds_add_f32 v5, v0
	ds_add_f32 v2, v3
.LBB0_1543:
	s_or_b64 exec, exec, s[6:7]
	v_add_f32_e32 v0, 0, v22
	v_mul_f32_e32 v2, v6, v6
	v_add_f32_e32 v0, v0, v6
	v_fmac_f32_e32 v2, v22, v22
	s_nop 1
	v_add_f32_dpp v0, v0, v0 quad_perm:[1,0,3,2] row_mask:0xf bank_mask:0xf
	s_nop 1
	v_add_f32_dpp v2, v2, v2 quad_perm:[1,0,3,2] row_mask:0xf bank_mask:0xf
	v_bfe_u32 v18, v22, 16, 1
	v_add3_u32 v21, v22, v18, s30
	s_nop 1
	v_add_f32_dpp v0, v0, v0 quad_perm:[2,3,0,1] row_mask:0xf bank_mask:0xf
	s_nop 1
	v_mov_b32_dpp v4, v2 quad_perm:[2,3,0,1] row_mask:0xf bank_mask:0xf
	v_add_f32_e32 v3, v2, v4
	s_nop 1
	v_add_f32_dpp v4, v0, v0 row_half_mirror row_mask:0xf bank_mask:0xf
	s_nop 1
	v_add_f32_dpp v3, v3, v3 row_half_mirror row_mask:0xf bank_mask:0xf
	v_or_b32_e32 v2, 40, v66
	s_nop 1
	v_mov_b32_dpp v5, v4 row_mirror row_mask:0xf bank_mask:0xf
	s_nop 1
	v_add_f32_dpp v3, v3, v3 row_mirror row_mask:0xf bank_mask:0xf
	v_lshl_or_b32 v0, v2, 10, v69
	v_lshl_add_u64 v[18:19], v[0:1], 1, s[14:15]
	global_store_short_d16_hi v[18:19], v21, off
	v_add_f32_e32 v0, v4, v5
	s_nop 1
	v_mov_b32_dpp v4, v0 row_bcast:15 row_mask:0xa bank_mask:0xf
	s_nop 1
	v_mov_b32_dpp v5, v3 row_bcast:15 row_mask:0xa bank_mask:0xf
	v_bfe_u32 v20, v6, 16, 1
	v_add3_u32 v6, v6, v20, s30
	global_store_short_d16_hi v[18:19], v6, off offset:64
	s_and_saveexec_b64 s[6:7], vcc
	s_cbranch_execz .LBB0_1545
	v_lshlrev_b32_e32 v2, 2, v2
	v_add_u32_e32 v6, 0x11800, v2
	v_add_f32_e32 v0, v0, v4
	v_add_u32_e32 v2, 0x11a00, v2
	v_add_f32_e32 v3, v3, v5
	ds_add_f32 v6, v0
	ds_add_f32 v2, v3
.LBB0_1545:
	s_or_b64 exec, exec, s[6:7]
	v_add_f32_e32 v0, 0, v23
	v_mul_f32_e32 v2, v7, v7
	v_add_f32_e32 v0, v0, v7
	v_fmac_f32_e32 v2, v23, v23
	s_nop 1
	v_add_f32_dpp v0, v0, v0 quad_perm:[1,0,3,2] row_mask:0xf bank_mask:0xf
	s_nop 1
	v_add_f32_dpp v2, v2, v2 quad_perm:[1,0,3,2] row_mask:0xf bank_mask:0xf
	v_bfe_u32 v6, v23, 16, 1
	v_add3_u32 v6, v23, v6, s30
	s_nop 1
	v_add_f32_dpp v0, v0, v0 quad_perm:[2,3,0,1] row_mask:0xf bank_mask:0xf
	s_nop 1
	v_mov_b32_dpp v4, v2 quad_perm:[2,3,0,1] row_mask:0xf bank_mask:0xf
	v_add_f32_e32 v3, v2, v4
	s_nop 1
	v_add_f32_dpp v4, v0, v0 row_half_mirror row_mask:0xf bank_mask:0xf
	s_nop 1
	v_add_f32_dpp v3, v3, v3 row_half_mirror row_mask:0xf bank_mask:0xf
	v_or_b32_e32 v2, 41, v66
	s_nop 1
	v_mov_b32_dpp v5, v4 row_mirror row_mask:0xf bank_mask:0xf
	s_nop 1
	v_add_f32_dpp v3, v3, v3 row_mirror row_mask:0xf bank_mask:0xf
	v_lshl_or_b32 v0, v2, 10, v69
	v_lshl_add_u64 v[18:19], v[0:1], 1, s[14:15]
	global_store_short_d16_hi v[18:19], v6, off
	v_add_f32_e32 v0, v4, v5
	s_nop 1
	v_mov_b32_dpp v4, v0 row_bcast:15 row_mask:0xa bank_mask:0xf
	s_nop 1
	v_mov_b32_dpp v5, v3 row_bcast:15 row_mask:0xa bank_mask:0xf
	v_bfe_u32 v6, v7, 16, 1
	v_add3_u32 v6, v7, v6, s30
	global_store_short_d16_hi v[18:19], v6, off offset:64
	s_and_saveexec_b64 s[6:7], vcc
	s_cbranch_execz .LBB0_1547
	v_lshlrev_b32_e32 v2, 2, v2
	v_add_u32_e32 v6, 0x11800, v2
	v_add_f32_e32 v0, v0, v4
	v_add_u32_e32 v2, 0x11a00, v2
	v_add_f32_e32 v3, v3, v5
	ds_add_f32 v6, v0
	ds_add_f32 v2, v3
.LBB0_1547:
	s_or_b64 exec, exec, s[6:7]
	v_add_f32_e32 v0, 0, v24
	v_mul_f32_e32 v2, v8, v8
	v_add_f32_e32 v0, v0, v8
	v_fmac_f32_e32 v2, v24, v24
	s_nop 1
	v_add_f32_dpp v0, v0, v0 quad_perm:[1,0,3,2] row_mask:0xf bank_mask:0xf
	s_nop 1
	v_add_f32_dpp v2, v2, v2 quad_perm:[1,0,3,2] row_mask:0xf bank_mask:0xf
	v_bfe_u32 v6, v24, 16, 1
	v_add3_u32 v19, v24, v6, s30
	s_nop 1
	v_add_f32_dpp v0, v0, v0 quad_perm:[2,3,0,1] row_mask:0xf bank_mask:0xf
	s_nop 1
	v_mov_b32_dpp v4, v2 quad_perm:[2,3,0,1] row_mask:0xf bank_mask:0xf
	v_add_f32_e32 v3, v2, v4
	s_nop 1
	v_add_f32_dpp v4, v0, v0 row_half_mirror row_mask:0xf bank_mask:0xf
	s_nop 1
	v_add_f32_dpp v3, v3, v3 row_half_mirror row_mask:0xf bank_mask:0xf
	v_or_b32_e32 v2, 42, v66
	s_nop 1
	v_mov_b32_dpp v5, v4 row_mirror row_mask:0xf bank_mask:0xf
	s_nop 1
	v_add_f32_dpp v3, v3, v3 row_mirror row_mask:0xf bank_mask:0xf
	v_lshl_or_b32 v0, v2, 10, v69
	v_lshl_add_u64 v[6:7], v[0:1], 1, s[14:15]
	global_store_short_d16_hi v[6:7], v19, off
	v_add_f32_e32 v0, v4, v5
	s_nop 1
	v_mov_b32_dpp v4, v0 row_bcast:15 row_mask:0xa bank_mask:0xf
	s_nop 1
	v_mov_b32_dpp v5, v3 row_bcast:15 row_mask:0xa bank_mask:0xf
	v_bfe_u32 v18, v8, 16, 1
	v_add3_u32 v8, v8, v18, s30
	global_store_short_d16_hi v[6:7], v8, off offset:64
	s_and_saveexec_b64 s[6:7], vcc
	s_cbranch_execz .LBB0_1549
	v_lshlrev_b32_e32 v2, 2, v2
	v_add_u32_e32 v6, 0x11800, v2
	v_add_f32_e32 v0, v0, v4
	v_add_u32_e32 v2, 0x11a00, v2
	v_add_f32_e32 v3, v3, v5
	ds_add_f32 v6, v0
	ds_add_f32 v2, v3
; __device__ __forceinline__ void phase_ret_out(const Params& p, unsigned char* smem) {
;     ...
;         const int t2 = relaunder(tid);
;         const int lane = t2 & 63, hi = lane >> 5, cl = lane & 31, wm = t2 >> 7, wn = (t2 >> 6) & 1;
; #pragma unroll
;         for (int mt = 0; mt < 2; mt++)
; #pragma unroll
;           for (int i = 0; i < 16; i++) {
;             int row = wm * 64 + mt * 32 + (i & 3) + 8 * (i >> 2) + 4 * hi;
;             float s1 = 0.f, s2 = 0.f;
; #pragma unroll
;             for (int nt = 0; nt < 2; nt++) {
;               int col = wn * 64 + nt * 32 + cl;
;               float y = acc[mt][nt][i];
;               *(ypre + rowbase + et * 128 + (unsigned)(row * 1024 + col)) = f2bf(y);
;               s1 += y; s2 += y * y;
;             }
; #pragma unroll
;             for (int o = 16; o > 0; o >>= 1) { s1 += __shfl_xor(s1, o, 64); s2 += __shfl_xor(s2, o, 64); }
;             if (cl == 0) { atomicAdd(&sSum[row], s1); atomicAdd(&sSq[row], s2); }
;             if ((i & 3) == 3) __builtin_amdgcn_sched_barrier(0);
;           }
.LBB0_1549:
	s_or_b64 exec, exec, s[6:7]
	v_add_f32_e32 v0, 0, v25
	v_mul_f32_e32 v2, v9, v9
	v_add_f32_e32 v0, v0, v9
	v_fmac_f32_e32 v2, v25, v25
	s_nop 1
	v_add_f32_dpp v0, v0, v0 quad_perm:[1,0,3,2] row_mask:0xf bank_mask:0xf
	s_nop 1
	v_add_f32_dpp v2, v2, v2 quad_perm:[1,0,3,2] row_mask:0xf bank_mask:0xf
	v_bfe_u32 v6, v25, 16, 1
	v_add3_u32 v18, v25, v6, s30
	s_nop 1
	v_add_f32_dpp v0, v0, v0 quad_perm:[2,3,0,1] row_mask:0xf bank_mask:0xf
	s_nop 1
	v_mov_b32_dpp v4, v2 quad_perm:[2,3,0,1] row_mask:0xf bank_mask:0xf
	v_add_f32_e32 v3, v2, v4
	s_nop 1
	v_add_f32_dpp v4, v0, v0 row_half_mirror row_mask:0xf bank_mask:0xf
	s_nop 1
	v_add_f32_dpp v3, v3, v3 row_half_mirror row_mask:0xf bank_mask:0xf
	v_or_b32_e32 v2, 43, v66
	s_nop 1
	v_mov_b32_dpp v5, v4 row_mirror row_mask:0xf bank_mask:0xf
	s_nop 1
	v_add_f32_dpp v3, v3, v3 row_mirror row_mask:0xf bank_mask:0xf
	v_lshl_or_b32 v0, v2, 10, v69
	v_lshl_add_u64 v[6:7], v[0:1], 1, s[14:15]
	global_store_short_d16_hi v[6:7], v18, off
	v_add_f32_e32 v0, v4, v5
	s_nop 1
	v_mov_b32_dpp v4, v0 row_bcast:15 row_mask:0xa bank_mask:0xf
	s_nop 1
	v_mov_b32_dpp v5, v3 row_bcast:15 row_mask:0xa bank_mask:0xf
	v_bfe_u32 v8, v9, 16, 1
	v_add3_u32 v8, v9, v8, s30
	global_store_short_d16_hi v[6:7], v8, off offset:64
	s_and_saveexec_b64 s[6:7], vcc
	s_cbranch_execz .LBB0_1551
	v_lshlrev_b32_e32 v2, 2, v2
	v_add_u32_e32 v6, 0x11800, v2
	v_add_f32_e32 v0, v0, v4
	v_add_u32_e32 v2, 0x11a00, v2
	v_add_f32_e32 v3, v3, v5
	ds_add_f32 v6, v0
	ds_add_f32 v2, v3
.LBB0_1551:
	s_or_b64 exec, exec, s[6:7]
	v_add_f32_e32 v0, 0, v26
	v_mul_f32_e32 v2, v10, v10
	v_add_f32_e32 v0, v0, v10
	v_fmac_f32_e32 v2, v26, v26
	s_nop 1
	v_add_f32_dpp v0, v0, v0 quad_perm:[1,0,3,2] row_mask:0xf bank_mask:0xf
	s_nop 1
	v_add_f32_dpp v2, v2, v2 quad_perm:[1,0,3,2] row_mask:0xf bank_mask:0xf
	v_bfe_u32 v6, v26, 16, 1
	v_add3_u32 v9, v26, v6, s30
	s_nop 1
	v_add_f32_dpp v0, v0, v0 quad_perm:[2,3,0,1] row_mask:0xf bank_mask:0xf
	s_nop 1
	v_mov_b32_dpp v4, v2 quad_perm:[2,3,0,1] row_mask:0xf bank_mask:0xf
	v_add_f32_e32 v3, v2, v4
	s_nop 1
	v_add_f32_dpp v4, v0, v0 row_half_mirror row_mask:0xf bank_mask:0xf
	s_nop 1
	v_add_f32_dpp v3, v3, v3 row_half_mirror row_mask:0xf bank_mask:0xf
	v_or_b32_e32 v2, 48, v66
	s_nop 1
	v_mov_b32_dpp v5, v4 row_mirror row_mask:0xf bank_mask:0xf
	s_nop 1
	v_add_f32_dpp v3, v3, v3 row_mirror row_mask:0xf bank_mask:0xf
	v_lshl_or_b32 v0, v2, 10, v69
	v_lshl_add_u64 v[6:7], v[0:1], 1, s[14:15]
	global_store_short_d16_hi v[6:7], v9, off
	v_add_f32_e32 v0, v4, v5
	s_nop 1
	v_mov_b32_dpp v4, v0 row_bcast:15 row_mask:0xa bank_mask:0xf
	s_nop 1
	v_mov_b32_dpp v5, v3 row_bcast:15 row_mask:0xa bank_mask:0xf
	v_bfe_u32 v8, v10, 16, 1
	v_add3_u32 v8, v10, v8, s30
	global_store_short_d16_hi v[6:7], v8, off offset:64
	s_and_saveexec_b64 s[6:7], vcc
	s_cbranch_execz .LBB0_1553
	v_lshlrev_b32_e32 v2, 2, v2
	v_add_u32_e32 v6, 0x11800, v2
	v_add_f32_e32 v0, v0, v4
	v_add_u32_e32 v2, 0x11a00, v2
	v_add_f32_e32 v3, v3, v5
	ds_add_f32 v6, v0
	ds_add_f32 v2, v3
.LBB0_1553:
	s_or_b64 exec, exec, s[6:7]
	v_add_f32_e32 v0, 0, v27
	v_mul_f32_e32 v2, v11, v11
	v_add_f32_e32 v0, v0, v11
	v_fmac_f32_e32 v2, v27, v27
	s_nop 1
	v_add_f32_dpp v0, v0, v0 quad_perm:[1,0,3,2] row_mask:0xf bank_mask:0xf
	s_nop 1
	v_add_f32_dpp v2, v2, v2 quad_perm:[1,0,3,2] row_mask:0xf bank_mask:0xf
	v_bfe_u32 v6, v27, 16, 1
	v_add3_u32 v9, v27, v6, s30
	s_nop 1
	v_add_f32_dpp v0, v0, v0 quad_perm:[2,3,0,1] row_mask:0xf bank_mask:0xf
	s_nop 1
	v_mov_b32_dpp v4, v2 quad_perm:[2,3,0,1] row_mask:0xf bank_mask:0xf
	v_add_f32_e32 v3, v2, v4
	s_nop 1
	v_add_f32_dpp v4, v0, v0 row_half_mirror row_mask:0xf bank_mask:0xf
	s_nop 1
	v_add_f32_dpp v3, v3, v3 row_half_mirror row_mask:0xf bank_mask:0xf
	v_or_b32_e32 v2, 49, v66
	s_nop 1
	v_mov_b32_dpp v5, v4 row_mirror row_mask:0xf bank_mask:0xf
	s_nop 1
	v_add_f32_dpp v3, v3, v3 row_mirror row_mask:0xf bank_mask:0xf
	v_lshl_or_b32 v0, v2, 10, v69
	v_lshl_add_u64 v[6:7], v[0:1], 1, s[14:15]
	global_store_short_d16_hi v[6:7], v9, off
	v_add_f32_e32 v0, v4, v5
	s_nop 1
	v_mov_b32_dpp v4, v0 row_bcast:15 row_mask:0xa bank_mask:0xf
	s_nop 1
	v_mov_b32_dpp v5, v3 row_bcast:15 row_mask:0xa bank_mask:0xf
	v_bfe_u32 v8, v11, 16, 1
	v_add3_u32 v8, v11, v8, s30
	global_store_short_d16_hi v[6:7], v8, off offset:64
	s_and_saveexec_b64 s[6:7], vcc
	s_cbranch_execz .LBB0_1555
	v_lshlrev_b32_e32 v2, 2, v2
	v_add_u32_e32 v6, 0x11800, v2
	v_add_f32_e32 v0, v0, v4
	v_add_u32_e32 v2, 0x11a00, v2
	v_add_f32_e32 v3, v3, v5
	ds_add_f32 v6, v0
	ds_add_f32 v2, v3
.LBB0_1555:
	s_or_b64 exec, exec, s[6:7]
	v_add_f32_e32 v0, 0, v28
	v_mul_f32_e32 v2, v12, v12
	v_add_f32_e32 v0, v0, v12
	v_fmac_f32_e32 v2, v28, v28
	s_nop 1
	v_add_f32_dpp v0, v0, v0 quad_perm:[1,0,3,2] row_mask:0xf bank_mask:0xf
	s_nop 1
	v_add_f32_dpp v2, v2, v2 quad_perm:[1,0,3,2] row_mask:0xf bank_mask:0xf
	v_bfe_u32 v6, v28, 16, 1
	v_add3_u32 v9, v28, v6, s30
	s_nop 1
	v_add_f32_dpp v0, v0, v0 quad_perm:[2,3,0,1] row_mask:0xf bank_mask:0xf
	s_nop 1
	v_mov_b32_dpp v4, v2 quad_perm:[2,3,0,1] row_mask:0xf bank_mask:0xf
	v_add_f32_e32 v3, v2, v4
	s_nop 1
	v_add_f32_dpp v4, v0, v0 row_half_mirror row_mask:0xf bank_mask:0xf
	s_nop 1
	v_add_f32_dpp v3, v3, v3 row_half_mirror row_mask:0xf bank_mask:0xf
	v_or_b32_e32 v2, 50, v66
	s_nop 1
	v_mov_b32_dpp v5, v4 row_mirror row_mask:0xf bank_mask:0xf
	s_nop 1
	v_add_f32_dpp v3, v3, v3 row_mirror row_mask:0xf bank_mask:0xf
	v_lshl_or_b32 v0, v2, 10, v69
	v_lshl_add_u64 v[6:7], v[0:1], 1, s[14:15]
	global_store_short_d16_hi v[6:7], v9, off
	v_add_f32_e32 v0, v4, v5
	s_nop 1
	v_mov_b32_dpp v4, v0 row_bcast:15 row_mask:0xa bank_mask:0xf
	s_nop 1
	v_mov_b32_dpp v5, v3 row_bcast:15 row_mask:0xa bank_mask:0xf
	v_bfe_u32 v8, v12, 16, 1
	v_add3_u32 v8, v12, v8, s30
	global_store_short_d16_hi v[6:7], v8, off offset:64
	s_and_saveexec_b64 s[6:7], vcc
	s_cbranch_execz .LBB0_1557
	v_lshlrev_b32_e32 v2, 2, v2
	v_add_u32_e32 v6, 0x11800, v2
	v_add_f32_e32 v0, v0, v4
	v_add_u32_e32 v2, 0x11a00, v2
	v_add_f32_e32 v3, v3, v5
	ds_add_f32 v6, v0
	ds_add_f32 v2, v3
; __device__ __forceinline__ void phase_ret_out(const Params& p, unsigned char* smem) {
;     ...
;         const int t2 = relaunder(tid);
;         const int lane = t2 & 63, hi = lane >> 5, cl = lane & 31, wm = t2 >> 7, wn = (t2 >> 6) & 1;
; #pragma unroll
;         for (int mt = 0; mt < 2; mt++)
; #pragma unroll
;           for (int i = 0; i < 16; i++) {
;             int row = wm * 64 + mt * 32 + (i & 3) + 8 * (i >> 2) + 4 * hi;
;             float s1 = 0.f, s2 = 0.f;
; #pragma unroll
;             for (int nt = 0; nt < 2; nt++) {
;               int col = wn * 64 + nt * 32 + cl;
;               float y = acc[mt][nt][i];
;               *(ypre + rowbase + et * 128 + (unsigned)(row * 1024 + col)) = f2bf(y);
;               s1 += y; s2 += y * y;
;             }
; #pragma unroll
;             for (int o = 16; o > 0; o >>= 1) { s1 += __shfl_xor(s1, o, 64); s2 += __shfl_xor(s2, o, 64); }
;             if (cl == 0) { atomicAdd(&sSum[row], s1); atomicAdd(&sSq[row], s2); }
;             if ((i & 3) == 3) __builtin_amdgcn_sched_barrier(0);
;           }
.LBB0_1557:
	s_or_b64 exec, exec, s[6:7]
	v_add_f32_e32 v0, 0, v29
	v_mul_f32_e32 v2, v13, v13
	v_add_f32_e32 v0, v0, v13
	v_fmac_f32_e32 v2, v29, v29
	s_nop 1
	v_add_f32_dpp v0, v0, v0 quad_perm:[1,0,3,2] row_mask:0xf bank_mask:0xf
	s_nop 1
	v_add_f32_dpp v2, v2, v2 quad_perm:[1,0,3,2] row_mask:0xf bank_mask:0xf
	v_bfe_u32 v6, v29, 16, 1
	v_add3_u32 v9, v29, v6, s30
	s_nop 1
	v_add_f32_dpp v0, v0, v0 quad_perm:[2,3,0,1] row_mask:0xf bank_mask:0xf
	s_nop 1
	v_mov_b32_dpp v4, v2 quad_perm:[2,3,0,1] row_mask:0xf bank_mask:0xf
	v_add_f32_e32 v3, v2, v4
	s_nop 1
	v_add_f32_dpp v4, v0, v0 row_half_mirror row_mask:0xf bank_mask:0xf
	s_nop 1
	v_add_f32_dpp v3, v3, v3 row_half_mirror row_mask:0xf bank_mask:0xf
	v_or_b32_e32 v2, 51, v66
	s_nop 1
	v_mov_b32_dpp v5, v4 row_mirror row_mask:0xf bank_mask:0xf
	s_nop 1
	v_add_f32_dpp v3, v3, v3 row_mirror row_mask:0xf bank_mask:0xf
	v_lshl_or_b32 v0, v2, 10, v69
	v_lshl_add_u64 v[6:7], v[0:1], 1, s[14:15]
	global_store_short_d16_hi v[6:7], v9, off
	v_add_f32_e32 v0, v4, v5
	s_nop 1
	v_mov_b32_dpp v4, v0 row_bcast:15 row_mask:0xa bank_mask:0xf
	s_nop 1
	v_mov_b32_dpp v5, v3 row_bcast:15 row_mask:0xa bank_mask:0xf
	v_bfe_u32 v8, v13, 16, 1
	v_add3_u32 v8, v13, v8, s30
	global_store_short_d16_hi v[6:7], v8, off offset:64
	s_and_saveexec_b64 s[6:7], vcc
	s_cbranch_execz .LBB0_1559
	v_lshlrev_b32_e32 v2, 2, v2
	v_add_u32_e32 v6, 0x11800, v2
	v_add_f32_e32 v0, v0, v4
	v_add_u32_e32 v2, 0x11a00, v2
	v_add_f32_e32 v3, v3, v5
	ds_add_f32 v6, v0
	ds_add_f32 v2, v3
.LBB0_1559:
	s_or_b64 exec, exec, s[6:7]
	v_add_f32_e32 v0, 0, v30
	v_mul_f32_e32 v2, v14, v14
	v_add_f32_e32 v0, v0, v14
	v_fmac_f32_e32 v2, v30, v30
	s_nop 1
	v_add_f32_dpp v0, v0, v0 quad_perm:[1,0,3,2] row_mask:0xf bank_mask:0xf
	s_nop 1
	v_add_f32_dpp v2, v2, v2 quad_perm:[1,0,3,2] row_mask:0xf bank_mask:0xf
	v_bfe_u32 v6, v30, 16, 1
	v_add3_u32 v9, v30, v6, s30
	s_nop 1
	v_add_f32_dpp v0, v0, v0 quad_perm:[2,3,0,1] row_mask:0xf bank_mask:0xf
	s_nop 1
	v_mov_b32_dpp v4, v2 quad_perm:[2,3,0,1] row_mask:0xf bank_mask:0xf
	v_add_f32_e32 v3, v2, v4
	s_nop 1
	v_add_f32_dpp v4, v0, v0 row_half_mirror row_mask:0xf bank_mask:0xf
	s_nop 1
	v_add_f32_dpp v3, v3, v3 row_half_mirror row_mask:0xf bank_mask:0xf
	v_or_b32_e32 v2, 56, v66
	s_nop 1
	v_mov_b32_dpp v5, v4 row_mirror row_mask:0xf bank_mask:0xf
	s_nop 1
	v_add_f32_dpp v3, v3, v3 row_mirror row_mask:0xf bank_mask:0xf
	v_lshl_or_b32 v0, v2, 10, v69
	v_lshl_add_u64 v[6:7], v[0:1], 1, s[14:15]
	global_store_short_d16_hi v[6:7], v9, off
	v_add_f32_e32 v0, v4, v5
	s_nop 1
	v_mov_b32_dpp v4, v0 row_bcast:15 row_mask:0xa bank_mask:0xf
	s_nop 1
	v_mov_b32_dpp v5, v3 row_bcast:15 row_mask:0xa bank_mask:0xf
	v_bfe_u32 v8, v14, 16, 1
	v_add3_u32 v8, v14, v8, s30
	global_store_short_d16_hi v[6:7], v8, off offset:64
	s_and_saveexec_b64 s[6:7], vcc
	s_cbranch_execz .LBB0_1561
	v_lshlrev_b32_e32 v2, 2, v2
	v_add_u32_e32 v6, 0x11800, v2
	v_add_f32_e32 v0, v0, v4
	v_add_u32_e32 v2, 0x11a00, v2
	v_add_f32_e32 v3, v3, v5
	ds_add_f32 v6, v0
	ds_add_f32 v2, v3
.LBB0_1561:
	s_or_b64 exec, exec, s[6:7]
	v_add_f32_e32 v0, 0, v31
	v_mul_f32_e32 v2, v15, v15
	v_add_f32_e32 v0, v0, v15
	v_fmac_f32_e32 v2, v31, v31
	s_nop 1
	v_add_f32_dpp v0, v0, v0 quad_perm:[1,0,3,2] row_mask:0xf bank_mask:0xf
	s_nop 1
	v_add_f32_dpp v2, v2, v2 quad_perm:[1,0,3,2] row_mask:0xf bank_mask:0xf
	v_bfe_u32 v6, v31, 16, 1
	v_add3_u32 v9, v31, v6, s30
	s_nop 1
	v_add_f32_dpp v0, v0, v0 quad_perm:[2,3,0,1] row_mask:0xf bank_mask:0xf
	s_nop 1
	v_mov_b32_dpp v4, v2 quad_perm:[2,3,0,1] row_mask:0xf bank_mask:0xf
	v_add_f32_e32 v3, v2, v4
	s_nop 1
	v_add_f32_dpp v4, v0, v0 row_half_mirror row_mask:0xf bank_mask:0xf
	s_nop 1
	v_add_f32_dpp v3, v3, v3 row_half_mirror row_mask:0xf bank_mask:0xf
	v_or_b32_e32 v2, 57, v66
	s_nop 1
	v_mov_b32_dpp v5, v4 row_mirror row_mask:0xf bank_mask:0xf
	s_nop 1
	v_add_f32_dpp v3, v3, v3 row_mirror row_mask:0xf bank_mask:0xf
	v_lshl_or_b32 v0, v2, 10, v69
	v_lshl_add_u64 v[6:7], v[0:1], 1, s[14:15]
	global_store_short_d16_hi v[6:7], v9, off
	v_add_f32_e32 v0, v4, v5
	s_nop 1
	v_mov_b32_dpp v4, v0 row_bcast:15 row_mask:0xa bank_mask:0xf
	s_nop 1
	v_mov_b32_dpp v5, v3 row_bcast:15 row_mask:0xa bank_mask:0xf
	v_bfe_u32 v8, v15, 16, 1
	v_add3_u32 v8, v15, v8, s30
	global_store_short_d16_hi v[6:7], v8, off offset:64
	s_and_saveexec_b64 s[6:7], vcc
	s_cbranch_execz .LBB0_1563
	v_lshlrev_b32_e32 v2, 2, v2
	v_add_u32_e32 v6, 0x11800, v2
	v_add_f32_e32 v0, v0, v4
	v_add_u32_e32 v2, 0x11a00, v2
	v_add_f32_e32 v3, v3, v5
	ds_add_f32 v6, v0
	ds_add_f32 v2, v3
; __device__ __forceinline__ void phase_ret_out(const Params& p, unsigned char* smem) {
;     ...
;       {
;         const int t2 = relaunder(tid);
;         const int lane = t2 & 63, hi = lane >> 5, cl = lane & 31, wm = t2 >> 7, wn = (t2 >> 6) & 1;
; #pragma unroll
;         for (int mt = 0; mt < 2; mt++)
; #pragma unroll
;           for (int i = 0; i < 16; i++) {
;             int row = wm * 64 + mt * 32 + (i & 3) + 8 * (i >> 2) + 4 * hi;
;             float s1 = 0.f, s2 = 0.f;
; #pragma unroll
;             for (int nt = 0; nt < 2; nt++) {
;               int col = wn * 64 + nt * 32 + cl;
;               float y = acc[mt][nt][i];
;               *(ypre + rowbase + et * 128 + (unsigned)(row * 1024 + col)) = f2bf(y);
;               s1 += y; s2 += y * y;
;             }
; #pragma unroll
;             for (int o = 16; o > 0; o >>= 1) { s1 += __shfl_xor(s1, o, 64); s2 += __shfl_xor(s2, o, 64); }
;             if (cl == 0) { atomicAdd(&sSum[row], s1); atomicAdd(&sSq[row], s2); }
;             if ((i & 3) == 3) __builtin_amdgcn_sched_barrier(0);
;           }
;       }
.LBB0_1563:
	s_or_b64 exec, exec, s[6:7]
	v_add_f32_e32 v0, 0, v32
	v_mul_f32_e32 v2, v16, v16
	v_add_f32_e32 v0, v0, v16
	v_fmac_f32_e32 v2, v32, v32
	s_nop 1
	v_add_f32_dpp v0, v0, v0 quad_perm:[1,0,3,2] row_mask:0xf bank_mask:0xf
	s_nop 1
	v_add_f32_dpp v2, v2, v2 quad_perm:[1,0,3,2] row_mask:0xf bank_mask:0xf
	v_bfe_u32 v6, v32, 16, 1
	v_add3_u32 v9, v32, v6, s30
	s_nop 1
	v_add_f32_dpp v0, v0, v0 quad_perm:[2,3,0,1] row_mask:0xf bank_mask:0xf
	s_nop 1
	v_mov_b32_dpp v4, v2 quad_perm:[2,3,0,1] row_mask:0xf bank_mask:0xf
	v_add_f32_e32 v3, v2, v4
	s_nop 1
	v_add_f32_dpp v4, v0, v0 row_half_mirror row_mask:0xf bank_mask:0xf
	s_nop 1
	v_add_f32_dpp v3, v3, v3 row_half_mirror row_mask:0xf bank_mask:0xf
	v_or_b32_e32 v2, 58, v66
	s_nop 1
	v_mov_b32_dpp v5, v4 row_mirror row_mask:0xf bank_mask:0xf
	s_nop 1
	v_add_f32_dpp v3, v3, v3 row_mirror row_mask:0xf bank_mask:0xf
	v_lshl_or_b32 v0, v2, 10, v69
	v_lshl_add_u64 v[6:7], v[0:1], 1, s[14:15]
	global_store_short_d16_hi v[6:7], v9, off
	v_add_f32_e32 v0, v4, v5
	s_nop 1
	v_mov_b32_dpp v4, v0 row_bcast:15 row_mask:0xa bank_mask:0xf
	s_nop 1
	v_mov_b32_dpp v5, v3 row_bcast:15 row_mask:0xa bank_mask:0xf
	v_bfe_u32 v8, v16, 16, 1
	v_add3_u32 v8, v16, v8, s30
	global_store_short_d16_hi v[6:7], v8, off offset:64
	s_and_saveexec_b64 s[6:7], vcc
	s_cbranch_execz .LBB0_1565
	v_lshlrev_b32_e32 v2, 2, v2
	v_add_u32_e32 v6, 0x11800, v2
	v_add_f32_e32 v0, v0, v4
	v_add_u32_e32 v2, 0x11a00, v2
	v_add_f32_e32 v3, v3, v5
	ds_add_f32 v6, v0
	ds_add_f32 v2, v3
.LBB0_1565:
	s_or_b64 exec, exec, s[6:7]
	v_add_f32_e32 v0, 0, v33
	v_mul_f32_e32 v2, v17, v17
	v_add_f32_e32 v0, v0, v17
	v_fmac_f32_e32 v2, v33, v33
	s_nop 1
	v_add_f32_dpp v0, v0, v0 quad_perm:[1,0,3,2] row_mask:0xf bank_mask:0xf
	s_nop 1
	v_add_f32_dpp v2, v2, v2 quad_perm:[1,0,3,2] row_mask:0xf bank_mask:0xf
	v_bfe_u32 v6, v33, 16, 1
	v_add3_u32 v9, v33, v6, s30
	s_nop 1
	v_add_f32_dpp v0, v0, v0 quad_perm:[2,3,0,1] row_mask:0xf bank_mask:0xf
	s_nop 1
	v_mov_b32_dpp v4, v2 quad_perm:[2,3,0,1] row_mask:0xf bank_mask:0xf
	v_add_f32_e32 v3, v2, v4
	s_nop 1
	v_add_f32_dpp v4, v0, v0 row_half_mirror row_mask:0xf bank_mask:0xf
	s_nop 1
	v_add_f32_dpp v3, v3, v3 row_half_mirror row_mask:0xf bank_mask:0xf
	v_or_b32_e32 v2, 59, v66
	s_nop 1
	v_mov_b32_dpp v5, v4 row_mirror row_mask:0xf bank_mask:0xf
	s_nop 1
	v_add_f32_dpp v3, v3, v3 row_mirror row_mask:0xf bank_mask:0xf
	v_lshl_or_b32 v0, v2, 10, v69
	v_lshl_add_u64 v[6:7], v[0:1], 1, s[14:15]
	global_store_short_d16_hi v[6:7], v9, off
	v_add_f32_e32 v0, v4, v5
	s_nop 1
	v_mov_b32_dpp v4, v0 row_bcast:15 row_mask:0xa bank_mask:0xf
	s_nop 1
	v_mov_b32_dpp v5, v3 row_bcast:15 row_mask:0xa bank_mask:0xf
	v_bfe_u32 v8, v17, 16, 1
	v_add3_u32 v8, v17, v8, s30
	global_store_short_d16_hi v[6:7], v8, off offset:64
	s_and_saveexec_b64 s[6:7], vcc
	s_cbranch_execz .LBB0_1496
	v_lshlrev_b32_e32 v2, 2, v2
	v_add_u32_e32 v6, 0x11800, v2
	v_add_f32_e32 v0, v0, v4
	v_add_u32_e32 v2, 0x11a00, v2
	v_add_f32_e32 v3, v3, v5
	ds_add_f32 v6, v0
	ds_add_f32 v2, v3
	s_waitcnt lgkmcnt(0)
	s_branch .LBB0_1496

; __device__ __forceinline__ float bf2f(bf16r h) { return __uint_as_float(((unsigned)h) << 16); }
; __device__ __forceinline__ float softplusf(float x) { return fmaxf(x, 0.f) + __logf(1.f + __expf(-fabsf(x))); }
; __device__ __forceinline__ void phase_sb(const Params& p, unsigned char* smem) {
;     ...
;       __syncthreads();
;       if (*sFlag) break;
;       int s0 = kb * 64;
;       stage_copy<64>(tid, sKV, 136, sk + (size_t)s0 * 1024 + h * 128, 1024);
;       stage_copy<64>(tid, sKV + 64, 136, sk + (size_t)s0 * 1024 + h * 128 + 64, 1024);
;       __syncthreads();
;       const int t2 = relaunder(tid);
;       const int hi = (t2 >> 5) & 1, cl = t2 & 31, wm = t2 >> 7, wn = (t2 >> 6) & 1;
;       f32x16 az[1][1];
;       zero_acc(az);
;       mma<1, 1, 8>(tid, az, sQ + wm * 32 * 136, 136, sKV + wn * 32 * 136, 136);
;       float logsig[16];
;       unsigned mbits = 0;
; #pragma unroll
;       for (int i = 0; i < 16; i++) {
;         int row = wm * 32 + (i & 3) + 8 * (i >> 2) + 4 * hi;
;         int col = wn * 32 + cl;
;         int t = t0 + row, key = s0 + col;
;         bool m = (key < t) && (key >= NPADR);
;         float z = az[0][0][i] * scale;
;         float sp = softplusf(z);
;         float ln = m ? -sp : 0.f;
;         logsig[i] = z - sp;
;         if (m) mbits |= (1u << i);
;         bf16r hb = f2bf(ln);
;         sHi[row * 72 + col] = hb;
;         sLo[row * 72 + col] = f2bf(ln - bf2f(hb));
;         float rsum = ln;
; #pragma unroll
;         for (int o = 16; o > 0; o >>= 1) rsum += __shfl_xor(rsum, o, 64);
;         if (cl == 0) atomicAdd(&sBlk[row], rsum);
;         if ((i & 3) == 3) __builtin_amdgcn_sched_barrier(0);
;       }
.LBB0_1892:
	s_waitcnt lgkmcnt(0)
	s_barrier
	ds_read_b32 v1, v141
	s_waitcnt lgkmcnt(0)
	v_cmp_ne_u32_e32 vcc, 0, v1
	s_cbranch_vccnz .LBB0_1891
	s_lshl_b64 s[8:9], s[16:17], 11
	v_lshl_add_u64 v[6:7], v[108:109], 0, s[8:9]
	v_lshl_add_u64 v[10:11], v[80:81], 1, v[6:7]
	v_lshl_add_u64 v[14:15], v[84:85], 1, v[6:7]
	global_load_dwordx4 v[2:5], v[10:11], off
	global_load_dwordx4 v[6:9], v[14:15], off
	s_nop 0
	global_load_dwordx4 v[10:13], v[10:11], off offset:128
	s_nop 0
	global_load_dwordx4 v[48:51], v[14:15], off offset:128
	v_mov_b32_e32 v70, v89
	v_cmp_lt_i32_e32 vcc, v144, v143
	s_waitcnt vmcnt(3)
	ds_write_b128 v82, v[2:5] offset:17408
	s_waitcnt vmcnt(2)
	ds_write_b128 v86, v[6:9] offset:17408
	s_waitcnt vmcnt(1)
	ds_write_b128 v82, v[10:13] offset:17536
	s_waitcnt vmcnt(0)
	ds_write_b128 v86, v[48:51] offset:17536
	s_waitcnt lgkmcnt(0)
	s_barrier
	s_nop 0
	v_ashrrev_i32_e32 v1, 2, v70
	v_and_b32_e32 v2, 0xffffffe0, v1
	v_mad_u64_u32 v[68:69], s[8:9], v2, s2, v[88:89]
	ds_read_b128 v[4:7], v68
	s_movk_i32 s8, 0x2200
	v_bfe_u32 v1, v70, 6, 1
	v_mad_u32_u24 v3, v1, s8, v88
	ds_read_b128 v[8:11], v3 offset:17408
	ds_read_b128 v[12:15], v3 offset:17440
	ds_read_b128 v[64:67], v68 offset:32
	s_waitcnt lgkmcnt(2)
	v_mfma_f32_32x32x16_bf16 v[48:63], v[4:7], v[8:11], 0
	v_cndmask_b32_e32 v69, v142, v144, vcc
	v_cmp_lt_i32_e32 vcc, v145, v143
	s_movk_i32 s8, 0x6f
	s_waitcnt lgkmcnt(0)
	v_mfma_f32_32x32x16_bf16 v[48:63], v[64:67], v[12:15], v[48:63]
	ds_read_b128 v[4:7], v68 offset:64
	ds_read_b128 v[8:11], v3 offset:17472
	ds_read_b128 v[12:15], v3 offset:17504
	ds_read_b128 v[64:67], v68 offset:96
	s_waitcnt lgkmcnt(2)
	v_mfma_f32_32x32x16_bf16 v[48:63], v[4:7], v[8:11], v[48:63]
	s_waitcnt lgkmcnt(0)
	v_mfma_f32_32x32x16_bf16 v[48:63], v[64:67], v[12:15], v[48:63]
	ds_read_b128 v[4:7], v68 offset:128
	ds_read_b128 v[8:11], v3 offset:17536
	ds_read_b128 v[12:15], v3 offset:17568
	ds_read_b128 v[64:67], v68 offset:160
	s_waitcnt lgkmcnt(2)
	v_mfma_f32_32x32x16_bf16 v[48:63], v[4:7], v[8:11], v[48:63]
	ds_read_b128 v[4:7], v68 offset:192
	ds_read_b128 v[8:11], v3 offset:17600
	s_waitcnt lgkmcnt(2)
	v_mfma_f32_32x32x16_bf16 v[48:63], v[64:67], v[12:15], v[48:63]
	ds_read_b128 v[12:15], v3 offset:17632
	ds_read_b128 v[64:67], v68 offset:224
	v_cndmask_b32_e32 v3, v142, v145, vcc
	s_waitcnt lgkmcnt(2)
	v_mfma_f32_32x32x16_bf16 v[48:63], v[4:7], v[8:11], v[48:63]
	v_lshrrev_b32_e32 v5, 3, v70
	v_and_or_b32 v11, v5, 4, v2
	v_and_b32_e32 v9, 31, v70
	v_lshlrev_b32_e32 v10, 5, v1
	v_or_b32_e32 v8, v10, v9
	v_add_u32_e32 v6, s20, v11
	v_lshlrev_b32_e32 v4, 2, v69
	s_waitcnt lgkmcnt(0)
	v_mfma_f32_32x32x16_bf16 v[48:63], v[64:67], v[12:15], v[48:63]
	s_nop 11
	v_mul_f32_e32 v12, 0x3db504f3, v48
	v_mul_f32_e64 v5, |v12|, s33
	v_exp_f32_e32 v5, v5
	v_add_u32_e32 v48, s16, v8
	v_cmp_lt_u32_e64 s[8:9], s8, v48
	v_cmp_lt_i32_e64 s[10:11], v48, v6
	v_add_f32_e32 v5, 1.0, v5
	v_cmp_gt_f32_e32 vcc, s76, v5
	v_max_f32_e32 v6, 0, v12
	s_and_b64 s[22:23], s[8:9], s[10:11]
	v_cndmask_b32_e64 v7, 0, 32, vcc
	v_ldexp_f32 v5, v5, v7
	v_log_f32_e32 v5, v5
	v_cndmask_b32_e32 v7, 0, v154, vcc
	s_movk_i32 s10, 0x48
	v_mul_f32_e32 v13, 0x3f317217, v5
	v_fma_f32 v13, v5, s77, -v13
	v_fmac_f32_e32 v13, 0x3377d1cf, v5
	v_fmac_f32_e32 v13, 0x3f317217, v5
	v_cmp_lt_f32_e64 vcc, |v5|, s78
	s_nop 1
	v_cndmask_b32_e32 v5, v5, v13, vcc
	v_sub_f32_e32 v5, v5, v7
	v_add_f32_e32 v13, v6, v5
	v_cndmask_b32_e64 v64, 0, -v13, s[22:23]
	s_nop 1
	v_mov_b32_dpp v6, v64 quad_perm:[1,0,3,2] row_mask:0xf bank_mask:0xf
	v_lshlrev_b32_e32 v5, 2, v3
	v_cmp_lt_i32_e32 vcc, v146, v143
	s_waitcnt lgkmcnt(0)
	v_add_f32_e32 v3, v64, v6
	s_nop 1
	v_add_f32_dpp v15, v3, v3 quad_perm:[2,3,0,1] row_mask:0xf bank_mask:0xf
	v_cndmask_b32_e32 v7, v142, v146, vcc
	v_lshlrev_b32_e32 v6, 2, v7
	v_cmp_lt_i32_e32 vcc, v147, v143
	s_nop 1
	v_mov_b32_dpp v66, v15 row_half_mirror row_mask:0xf bank_mask:0xf
	v_cndmask_b32_e32 v14, v142, v147, vcc
	v_mul_lo_u32 v3, v11, s10
	v_lshlrev_b32_e32 v7, 2, v14
	v_add_lshl_u32 v3, v3, v8, 1
	v_add_f32_e32 v8, v15, v66
	s_nop 1
	v_add_f32_dpp v14, v8, v8 row_mirror row_mask:0xf bank_mask:0xf
	v_cmp_lt_i32_e32 vcc, v148, v143
	v_bfe_u32 v15, v64, 16, 1
	v_add3_u32 v15, v64, v15, s79
	v_cndmask_b32_e32 v65, v142, v148, vcc
	v_lshlrev_b32_e32 v8, 2, v65
	ds_write_b16_d16_hi v3, v15 offset:35840
	v_and_b32_e32 v66, 0xffff0000, v15
	s_nop 1
	v_mov_b32_dpp v15, v14 row_bcast:15 row_mask:0xa bank_mask:0xf
	v_sub_f32_e32 v64, v64, v66
	v_bfe_u32 v65, v64, 16, 1
	v_cmp_eq_u32_e32 vcc, 16, v9
	v_add3_u32 v64, v64, v65, s79
	ds_write_b16_d16_hi v3, v64 offset:45056
	s_and_saveexec_b64 s[10:11], vcc
	s_cbranch_execz .LBB0_1895
	v_lshl_add_u32 v64, v11, 2, v155
	v_add_f32_e32 v14, v14, v15
	ds_add_f32 v64, v14
.LBB0_1895:
	s_or_b64 exec, exec, s[10:11]
	v_mul_f32_e32 v14, 0x3db504f3, v49
	v_mul_f32_e64 v15, |v14|, s33
	v_exp_f32_e32 v49, v15
	v_or_b32_e32 v15, 1, v11
	v_max_f32_e32 v65, 0, v14
	v_add_f32_e32 v49, 1.0, v49
	v_cmp_gt_f32_e64 s[10:11], s76, v49
	s_nop 1
	v_cndmask_b32_e64 v64, 0, 32, s[10:11]
	v_ldexp_f32 v49, v49, v64
	v_log_f32_e32 v49, v49
	v_add_u32_e32 v64, s20, v15
	v_cmp_lt_i32_e64 s[12:13], v48, v64
	s_and_b64 s[24:25], s[8:9], s[12:13]
	v_mul_f32_e32 v64, 0x3f317217, v49
	v_fma_f32 v64, v49, s77, -v64
	v_fmac_f32_e32 v64, 0x3377d1cf, v49
	v_fmac_f32_e32 v64, 0x3f317217, v49
	v_cmp_lt_f32_e64 s[14:15], |v49|, s78
	s_nop 1
	v_cndmask_b32_e64 v49, v49, v64, s[14:15]
	v_cndmask_b32_e64 v64, 0, v154, s[10:11]
	v_sub_f32_e32 v49, v49, v64
	v_add_f32_e32 v64, v65, v49
	v_cndmask_b32_e64 v66, 0, -v64, s[24:25]
	s_nop 1
	v_add_f32_dpp v49, v66, v66 quad_perm:[1,0,3,2] row_mask:0xf bank_mask:0xf
	v_bfe_u32 v67, v66, 16, 1
	v_add3_u32 v67, v66, v67, s79
	ds_write_b16_d16_hi v3, v67 offset:35984
	v_and_b32_e32 v67, 0xffff0000, v67
	s_nop 1
	v_add_f32_dpp v49, v49, v49 quad_perm:[2,3,0,1] row_mask:0xf bank_mask:0xf
	v_sub_f32_e32 v66, v66, v67
	v_bfe_u32 v67, v66, 16, 1
	v_add3_u32 v66, v66, v67, s79
	ds_write_b16_d16_hi v3, v66 offset:45200
	s_nop 1
	v_add_f32_dpp v49, v49, v49 row_half_mirror row_mask:0xf bank_mask:0xf
	s_nop 1
	v_add_f32_dpp v49, v49, v49 row_mirror row_mask:0xf bank_mask:0xf
	s_nop 1
	v_mov_b32_dpp v65, v49 row_bcast:15 row_mask:0xa bank_mask:0xf
	s_and_saveexec_b64 s[10:11], vcc
	s_cbranch_execz .LBB0_1897
	v_lshl_add_u32 v66, v15, 2, v155
	v_add_f32_e32 v49, v49, v65
	ds_add_f32 v66, v49
; __device__ __forceinline__ float bf2f(bf16r h) { return __uint_as_float(((unsigned)h) << 16); }
; __device__ __forceinline__ float softplusf(float x) { return fmaxf(x, 0.f) + __logf(1.f + __expf(-fabsf(x))); }
; __device__ __forceinline__ void phase_sb(const Params& p, unsigned char* smem) {
;     ...
;       for (int i = 0; i < 16; i++) {
;         int row = wm * 32 + (i & 3) + 8 * (i >> 2) + 4 * hi;
;         int col = wn * 32 + cl;
;         int t = t0 + row, key = s0 + col;
;         bool m = (key < t) && (key >= NPADR);
;         float z = az[0][0][i] * scale;
;         float sp = softplusf(z);
;         float ln = m ? -sp : 0.f;
;         logsig[i] = z - sp;
;         if (m) mbits |= (1u << i);
;         bf16r hb = f2bf(ln);
;         sHi[row * 72 + col] = hb;
;         sLo[row * 72 + col] = f2bf(ln - bf2f(hb));
;         float rsum = ln;
; #pragma unroll
;         for (int o = 16; o > 0; o >>= 1) rsum += __shfl_xor(rsum, o, 64);
;         if (cl == 0) atomicAdd(&sBlk[row], rsum);
;         if ((i & 3) == 3) __builtin_amdgcn_sched_barrier(0);
;       }
.LBB0_1897:
	s_or_b64 exec, exec, s[10:11]
	v_mul_f32_e32 v65, 0x3db504f3, v50
	v_mul_f32_e64 v49, |v65|, s33
	v_exp_f32_e32 v49, v49
	v_or_b32_e32 v66, 2, v11
	v_max_f32_e32 v67, 0, v65
	v_add_f32_e32 v49, 1.0, v49
	v_cmp_gt_f32_e64 s[10:11], s76, v49
	s_nop 1
	v_cndmask_b32_e64 v50, 0, 32, s[10:11]
	v_ldexp_f32 v49, v49, v50
	v_log_f32_e32 v49, v49
	v_add_u32_e32 v50, s20, v66
	v_cmp_lt_i32_e64 s[12:13], v48, v50
	s_and_b64 s[26:27], s[8:9], s[12:13]
	v_mul_f32_e32 v50, 0x3f317217, v49
	v_fma_f32 v50, v49, s77, -v50
	v_fmac_f32_e32 v50, 0x3377d1cf, v49
	v_fmac_f32_e32 v50, 0x3f317217, v49
	v_cmp_lt_f32_e64 s[14:15], |v49|, s78
	s_nop 1
	v_cndmask_b32_e64 v49, v49, v50, s[14:15]
	v_cndmask_b32_e64 v50, 0, v154, s[10:11]
	v_sub_f32_e32 v49, v49, v50
	v_add_f32_e32 v67, v67, v49
	v_cndmask_b32_e64 v68, 0, -v67, s[26:27]
	s_nop 1
	v_add_f32_dpp v49, v68, v68 quad_perm:[1,0,3,2] row_mask:0xf bank_mask:0xf
	v_bfe_u32 v69, v68, 16, 1
	v_add3_u32 v69, v68, v69, s79
	ds_write_b16_d16_hi v3, v69 offset:36128
	v_and_b32_e32 v69, 0xffff0000, v69
	s_nop 1
	v_add_f32_dpp v49, v49, v49 quad_perm:[2,3,0,1] row_mask:0xf bank_mask:0xf
	v_sub_f32_e32 v68, v68, v69
	v_bfe_u32 v69, v68, 16, 1
	v_add3_u32 v68, v68, v69, s79
	ds_write_b16_d16_hi v3, v68 offset:45344
	s_nop 1
	v_add_f32_dpp v49, v49, v49 row_half_mirror row_mask:0xf bank_mask:0xf
	s_nop 1
	v_add_f32_dpp v49, v49, v49 row_mirror row_mask:0xf bank_mask:0xf
	s_nop 1
	v_mov_b32_dpp v50, v49 row_bcast:15 row_mask:0xa bank_mask:0xf
	s_and_saveexec_b64 s[10:11], vcc
	s_cbranch_execz .LBB0_1899
	v_lshl_add_u32 v68, v66, 2, v155
	v_add_f32_e32 v49, v49, v50
	ds_add_f32 v68, v49
.LBB0_1899:
	s_or_b64 exec, exec, s[10:11]
	v_mul_f32_e32 v68, 0x3db504f3, v51
	v_mul_f32_e64 v49, |v68|, s33
	v_exp_f32_e32 v49, v49
	v_or_b32_e32 v69, 3, v11
	v_max_f32_e32 v51, 0, v68
	v_add_f32_e32 v49, 1.0, v49
	v_cmp_gt_f32_e64 s[10:11], s76, v49
	s_nop 0
	v_cndmask_b32_e64 v50, 0, 32, s[10:11]
	v_ldexp_f32 v49, v49, v50
	v_log_f32_e32 v49, v49
	v_add_u32_e32 v50, s20, v69
	v_cmp_lt_i32_e64 s[12:13], v48, v50
	s_and_b64 s[28:29], s[8:9], s[12:13]
	v_mul_f32_e32 v50, 0x3f317217, v49
	v_fma_f32 v50, v49, s77, -v50
	v_fmac_f32_e32 v50, 0x3377d1cf, v49
	v_fmac_f32_e32 v50, 0x3f317217, v49
	v_cmp_lt_f32_e64 s[14:15], |v49|, s78
	s_nop 1
	v_cndmask_b32_e64 v49, v49, v50, s[14:15]
	v_cndmask_b32_e64 v50, 0, v154, s[10:11]
	v_sub_f32_e32 v49, v49, v50
	v_add_f32_e32 v70, v51, v49
	v_cndmask_b32_e64 v51, 0, -v70, s[28:29]
	s_nop 1
	v_add_f32_dpp v49, v51, v51 quad_perm:[1,0,3,2] row_mask:0xf bank_mask:0xf
	v_bfe_u32 v71, v51, 16, 1
	v_add3_u32 v71, v51, v71, s79
	ds_write_b16_d16_hi v3, v71 offset:36272
	v_and_b32_e32 v71, 0xffff0000, v71
	s_nop 1
	v_add_f32_dpp v49, v49, v49 quad_perm:[2,3,0,1] row_mask:0xf bank_mask:0xf
	v_sub_f32_e32 v51, v51, v71
	v_bfe_u32 v71, v51, 16, 1
	v_add3_u32 v51, v51, v71, s79
	ds_write_b16_d16_hi v3, v51 offset:45488
	s_nop 1
	v_add_f32_dpp v49, v49, v49 row_half_mirror row_mask:0xf bank_mask:0xf
	s_nop 1
	v_add_f32_dpp v49, v49, v49 row_mirror row_mask:0xf bank_mask:0xf
	s_nop 1
	v_mov_b32_dpp v50, v49 row_bcast:15 row_mask:0xa bank_mask:0xf
	s_and_saveexec_b64 s[10:11], vcc
	s_cbranch_execz .LBB0_1901
	v_lshl_add_u32 v51, v69, 2, v155
	v_add_f32_e32 v49, v49, v50
	ds_add_f32 v51, v49
.LBB0_1901:
	s_or_b64 exec, exec, s[10:11]
	v_mul_f32_e32 v71, 0x3db504f3, v52
	v_mul_f32_e64 v49, |v71|, s33
	v_exp_f32_e32 v49, v49
	v_or_b32_e32 v72, 8, v11
	v_max_f32_e32 v51, 0, v71
	v_add_f32_e32 v49, 1.0, v49
	v_cmp_gt_f32_e64 s[10:11], s76, v49
	s_nop 0
	v_cndmask_b32_e64 v50, 0, 32, s[10:11]
	v_ldexp_f32 v49, v49, v50
	v_log_f32_e32 v49, v49
	v_add_u32_e32 v50, s20, v72
	v_cmp_lt_i32_e64 s[12:13], v48, v50
	s_and_b64 s[30:31], s[8:9], s[12:13]
	v_mul_f32_e32 v50, 0x3f317217, v49
	v_fma_f32 v50, v49, s77, -v50
	v_fmac_f32_e32 v50, 0x3377d1cf, v49
	v_fmac_f32_e32 v50, 0x3f317217, v49
	v_cmp_lt_f32_e64 s[14:15], |v49|, s78
	s_nop 1
	v_cndmask_b32_e64 v49, v49, v50, s[14:15]
	v_cndmask_b32_e64 v50, 0, v154, s[10:11]
	v_sub_f32_e32 v49, v49, v50
	v_add_f32_e32 v73, v51, v49
	v_cndmask_b32_e64 v51, 0, -v73, s[30:31]
	s_nop 1
	v_add_f32_dpp v49, v51, v51 quad_perm:[1,0,3,2] row_mask:0xf bank_mask:0xf
	v_bfe_u32 v52, v51, 16, 1
	v_add3_u32 v52, v51, v52, s79
	ds_write_b16_d16_hi v3, v52 offset:36992
	v_and_b32_e32 v52, 0xffff0000, v52
	s_nop 1
	v_add_f32_dpp v49, v49, v49 quad_perm:[2,3,0,1] row_mask:0xf bank_mask:0xf
	v_sub_f32_e32 v51, v51, v52
	v_bfe_u32 v52, v51, 16, 1
	v_add3_u32 v51, v51, v52, s79
	ds_write_b16_d16_hi v3, v51 offset:46208
	s_nop 1
	v_add_f32_dpp v49, v49, v49 row_half_mirror row_mask:0xf bank_mask:0xf
	s_nop 1
	v_add_f32_dpp v49, v49, v49 row_mirror row_mask:0xf bank_mask:0xf
	s_nop 1
	v_mov_b32_dpp v50, v49 row_bcast:15 row_mask:0xa bank_mask:0xf
	s_and_saveexec_b64 s[10:11], vcc
	s_cbranch_execz .LBB0_1903
	v_lshl_add_u32 v51, v72, 2, v155
	v_add_f32_e32 v49, v49, v50
	ds_add_f32 v51, v49
; __device__ __forceinline__ float bf2f(bf16r h) { return __uint_as_float(((unsigned)h) << 16); }
; __device__ __forceinline__ float softplusf(float x) { return fmaxf(x, 0.f) + __logf(1.f + __expf(-fabsf(x))); }
; __device__ __forceinline__ void phase_sb(const Params& p, unsigned char* smem) {
;     ...
;       for (int i = 0; i < 16; i++) {
;         int row = wm * 32 + (i & 3) + 8 * (i >> 2) + 4 * hi;
;         int col = wn * 32 + cl;
;         int t = t0 + row, key = s0 + col;
;         bool m = (key < t) && (key >= NPADR);
;         float z = az[0][0][i] * scale;
;         float sp = softplusf(z);
;         float ln = m ? -sp : 0.f;
;         logsig[i] = z - sp;
;         if (m) mbits |= (1u << i);
;         bf16r hb = f2bf(ln);
;         sHi[row * 72 + col] = hb;
;         sLo[row * 72 + col] = f2bf(ln - bf2f(hb));
;         float rsum = ln;
; #pragma unroll
;         for (int o = 16; o > 0; o >>= 1) rsum += __shfl_xor(rsum, o, 64);
;         if (cl == 0) atomicAdd(&sBlk[row], rsum);
;         if ((i & 3) == 3) __builtin_amdgcn_sched_barrier(0);
;       }
.LBB0_1903:
	s_or_b64 exec, exec, s[10:11]
	v_mul_f32_e32 v74, 0x3db504f3, v53
	v_mul_f32_e64 v49, |v74|, s33
	v_exp_f32_e32 v49, v49
	v_or_b32_e32 v75, 9, v11
	v_max_f32_e32 v51, 0, v74
	v_add_f32_e32 v49, 1.0, v49
	v_cmp_gt_f32_e64 s[10:11], s76, v49
	s_nop 0
	v_cndmask_b32_e64 v50, 0, 32, s[10:11]
	v_ldexp_f32 v49, v49, v50
	v_log_f32_e32 v49, v49
	v_add_u32_e32 v50, s20, v75
	v_cmp_lt_i32_e64 s[12:13], v48, v50
	s_and_b64 s[34:35], s[8:9], s[12:13]
	v_mul_f32_e32 v50, 0x3f317217, v49
	v_fma_f32 v50, v49, s77, -v50
	v_fmac_f32_e32 v50, 0x3377d1cf, v49
	v_fmac_f32_e32 v50, 0x3f317217, v49
	v_cmp_lt_f32_e64 s[14:15], |v49|, s78
	s_nop 1
	v_cndmask_b32_e64 v49, v49, v50, s[14:15]
	v_cndmask_b32_e64 v50, 0, v154, s[10:11]
	v_sub_f32_e32 v49, v49, v50
	v_add_f32_e32 v76, v51, v49
	v_cndmask_b32_e64 v51, 0, -v76, s[34:35]
	s_nop 1
	v_add_f32_dpp v49, v51, v51 quad_perm:[1,0,3,2] row_mask:0xf bank_mask:0xf
	v_bfe_u32 v52, v51, 16, 1
	v_add3_u32 v52, v51, v52, s79
	ds_write_b16_d16_hi v3, v52 offset:37136
	v_and_b32_e32 v52, 0xffff0000, v52
	s_nop 1
	v_add_f32_dpp v49, v49, v49 quad_perm:[2,3,0,1] row_mask:0xf bank_mask:0xf
	v_sub_f32_e32 v51, v51, v52
	v_bfe_u32 v52, v51, 16, 1
	v_add3_u32 v51, v51, v52, s79
	ds_write_b16_d16_hi v3, v51 offset:46352
	s_nop 1
	v_add_f32_dpp v49, v49, v49 row_half_mirror row_mask:0xf bank_mask:0xf
	s_nop 1
	v_add_f32_dpp v49, v49, v49 row_mirror row_mask:0xf bank_mask:0xf
	s_nop 1
	v_mov_b32_dpp v50, v49 row_bcast:15 row_mask:0xa bank_mask:0xf
	s_and_saveexec_b64 s[10:11], vcc
	s_cbranch_execz .LBB0_1905
	v_lshl_add_u32 v51, v75, 2, v155
	v_add_f32_e32 v49, v49, v50
	ds_add_f32 v51, v49
.LBB0_1905:
	s_or_b64 exec, exec, s[10:11]
	v_mul_f32_e32 v77, 0x3db504f3, v54
	v_mul_f32_e64 v49, |v77|, s33
	v_exp_f32_e32 v49, v49
	v_or_b32_e32 v78, 10, v11
	v_max_f32_e32 v51, 0, v77
	v_add_f32_e32 v49, 1.0, v49
	v_cmp_gt_f32_e64 s[10:11], s76, v49
	s_nop 0
	v_cndmask_b32_e64 v50, 0, 32, s[10:11]
	v_ldexp_f32 v49, v49, v50
	v_log_f32_e32 v49, v49
	v_add_u32_e32 v50, s20, v78
	v_cmp_lt_i32_e64 s[12:13], v48, v50
	s_and_b64 s[36:37], s[8:9], s[12:13]
	v_mul_f32_e32 v50, 0x3f317217, v49
	v_fma_f32 v50, v49, s77, -v50
	v_fmac_f32_e32 v50, 0x3377d1cf, v49
	v_fmac_f32_e32 v50, 0x3f317217, v49
	v_cmp_lt_f32_e64 s[14:15], |v49|, s78
	s_nop 1
	v_cndmask_b32_e64 v49, v49, v50, s[14:15]
	v_cndmask_b32_e64 v50, 0, v154, s[10:11]
	v_sub_f32_e32 v49, v49, v50
	v_add_f32_e32 v79, v51, v49
	v_cndmask_b32_e64 v51, 0, -v79, s[36:37]
	s_nop 1
	v_add_f32_dpp v49, v51, v51 quad_perm:[1,0,3,2] row_mask:0xf bank_mask:0xf
	v_bfe_u32 v52, v51, 16, 1
	v_add3_u32 v52, v51, v52, s79
	ds_write_b16_d16_hi v3, v52 offset:37280
	v_and_b32_e32 v52, 0xffff0000, v52
	s_nop 1
	v_add_f32_dpp v49, v49, v49 quad_perm:[2,3,0,1] row_mask:0xf bank_mask:0xf
	v_sub_f32_e32 v51, v51, v52
	v_bfe_u32 v52, v51, 16, 1
	v_add3_u32 v51, v51, v52, s79
	ds_write_b16_d16_hi v3, v51 offset:46496
	s_nop 1
	v_add_f32_dpp v49, v49, v49 row_half_mirror row_mask:0xf bank_mask:0xf
	s_nop 1
	v_add_f32_dpp v49, v49, v49 row_mirror row_mask:0xf bank_mask:0xf
	s_nop 1
	v_mov_b32_dpp v50, v49 row_bcast:15 row_mask:0xa bank_mask:0xf
	s_and_saveexec_b64 s[10:11], vcc
	s_cbranch_execz .LBB0_1907
	v_lshl_add_u32 v51, v78, 2, v155
	v_add_f32_e32 v49, v49, v50
	ds_add_f32 v51, v49
.LBB0_1907:
	s_or_b64 exec, exec, s[10:11]
	v_mul_f32_e32 v158, 0x3db504f3, v55
	v_mul_f32_e64 v49, |v158|, s33
	v_exp_f32_e32 v49, v49
	v_or_b32_e32 v159, 11, v11
	v_max_f32_e32 v51, 0, v158
	v_add_f32_e32 v49, 1.0, v49
	v_cmp_gt_f32_e64 s[10:11], s76, v49
	s_nop 0
	v_cndmask_b32_e64 v50, 0, 32, s[10:11]
	v_ldexp_f32 v49, v49, v50
	v_log_f32_e32 v49, v49
	v_add_u32_e32 v50, s20, v159
	v_cmp_lt_i32_e64 s[12:13], v48, v50
	v_mul_f32_e32 v50, 0x3f317217, v49
	v_fma_f32 v50, v49, s77, -v50
	v_fmac_f32_e32 v50, 0x3377d1cf, v49
	v_fmac_f32_e32 v50, 0x3f317217, v49
	v_cmp_lt_f32_e64 s[14:15], |v49|, s78
	s_nop 1
	v_cndmask_b32_e64 v49, v49, v50, s[14:15]
	v_cndmask_b32_e64 v50, 0, v154, s[10:11]
	v_sub_f32_e32 v49, v49, v50
	v_add_f32_e32 v160, v51, v49
	s_and_b64 s[14:15], s[8:9], s[12:13]
	v_cndmask_b32_e64 v51, 0, -v160, s[14:15]
	s_nop 1
	v_add_f32_dpp v49, v51, v51 quad_perm:[1,0,3,2] row_mask:0xf bank_mask:0xf
	v_bfe_u32 v52, v51, 16, 1
	v_add3_u32 v52, v51, v52, s79
	ds_write_b16_d16_hi v3, v52 offset:37424
	v_and_b32_e32 v52, 0xffff0000, v52
	s_nop 1
	v_add_f32_dpp v49, v49, v49 quad_perm:[2,3,0,1] row_mask:0xf bank_mask:0xf
	v_sub_f32_e32 v51, v51, v52
	v_bfe_u32 v52, v51, 16, 1
	v_add3_u32 v51, v51, v52, s79
	ds_write_b16_d16_hi v3, v51 offset:46640
	s_nop 1
	v_add_f32_dpp v49, v49, v49 row_half_mirror row_mask:0xf bank_mask:0xf
	s_nop 1
	v_add_f32_dpp v49, v49, v49 row_mirror row_mask:0xf bank_mask:0xf
	s_nop 1
	v_mov_b32_dpp v50, v49 row_bcast:15 row_mask:0xa bank_mask:0xf
	s_and_saveexec_b64 s[10:11], vcc
	s_cbranch_execz .LBB0_1909
	v_lshl_add_u32 v51, v159, 2, v155
	v_add_f32_e32 v49, v49, v50
	ds_add_f32 v51, v49
; __device__ __forceinline__ float bf2f(bf16r h) { return __uint_as_float(((unsigned)h) << 16); }
; __device__ __forceinline__ float softplusf(float x) { return fmaxf(x, 0.f) + __logf(1.f + __expf(-fabsf(x))); }
; __device__ __forceinline__ void phase_sb(const Params& p, unsigned char* smem) {
;     ...
;       for (int i = 0; i < 16; i++) {
;         int row = wm * 32 + (i & 3) + 8 * (i >> 2) + 4 * hi;
;         int col = wn * 32 + cl;
;         int t = t0 + row, key = s0 + col;
;         bool m = (key < t) && (key >= NPADR);
;         float z = az[0][0][i] * scale;
;         float sp = softplusf(z);
;         float ln = m ? -sp : 0.f;
;         logsig[i] = z - sp;
;         if (m) mbits |= (1u << i);
;         bf16r hb = f2bf(ln);
;         sHi[row * 72 + col] = hb;
;         sLo[row * 72 + col] = f2bf(ln - bf2f(hb));
;         float rsum = ln;
; #pragma unroll
;         for (int o = 16; o > 0; o >>= 1) rsum += __shfl_xor(rsum, o, 64);
;         if (cl == 0) atomicAdd(&sBlk[row], rsum);
;         if ((i & 3) == 3) __builtin_amdgcn_sched_barrier(0);
;       }
.LBB0_1909:
	s_or_b64 exec, exec, s[10:11]
	v_mul_f32_e32 v162, 0x3db504f3, v56
	v_mul_f32_e64 v50, |v162|, s33
	v_exp_f32_e32 v50, v50
	v_or_b32_e32 v161, 16, v11
	v_add_u32_e32 v49, s20, v161
	v_cmp_lt_i32_e64 s[10:11], v48, v49
	v_add_f32_e32 v50, 1.0, v50
	s_and_b64 s[38:39], s[8:9], s[10:11]
	v_cmp_gt_f32_e64 s[10:11], s76, v50
	v_max_f32_e32 v49, 0, v162
	s_nop 0
	v_cndmask_b32_e64 v51, 0, 32, s[10:11]
	v_ldexp_f32 v50, v50, v51
	v_log_f32_e32 v50, v50
	s_nop 0
	v_mul_f32_e32 v51, 0x3f317217, v50
	v_fma_f32 v51, v50, s77, -v51
	v_fmac_f32_e32 v51, 0x3377d1cf, v50
	v_fmac_f32_e32 v51, 0x3f317217, v50
	v_cmp_lt_f32_e64 s[12:13], |v50|, s78
	s_nop 1
	v_cndmask_b32_e64 v50, v50, v51, s[12:13]
	v_cndmask_b32_e64 v51, 0, v154, s[10:11]
	v_sub_f32_e32 v50, v50, v51
	v_add_f32_e32 v163, v49, v50
	v_cndmask_b32_e64 v49, 0, -v163, s[38:39]
	v_bfe_u32 v50, v49, 16, 1
	v_add3_u32 v50, v49, v50, s79
	ds_write_b16_d16_hi v3, v50 offset:38144
	v_and_b32_e32 v50, 0xffff0000, v50
	v_sub_f32_e32 v50, v49, v50
	v_bfe_u32 v51, v50, 16, 1
	v_add3_u32 v50, v50, v51, s79
	ds_write_b16_d16_hi v3, v50 offset:47360
	s_nop 1
	v_add_f32_dpp v49, v49, v49 quad_perm:[1,0,3,2] row_mask:0xf bank_mask:0xf
	s_nop 1
	v_add_f32_dpp v49, v49, v49 quad_perm:[2,3,0,1] row_mask:0xf bank_mask:0xf
	s_nop 1
	v_add_f32_dpp v49, v49, v49 row_half_mirror row_mask:0xf bank_mask:0xf
	s_nop 1
	v_add_f32_dpp v49, v49, v49 row_mirror row_mask:0xf bank_mask:0xf
	s_nop 1
	v_mov_b32_dpp v50, v49 row_bcast:15 row_mask:0xa bank_mask:0xf
	s_and_saveexec_b64 s[10:11], vcc
	s_cbranch_execz .LBB0_1911
	v_lshl_add_u32 v51, v161, 2, v155
	v_add_f32_e32 v49, v49, v50
	ds_add_f32 v51, v49
.LBB0_1911:
	s_or_b64 exec, exec, s[10:11]
	v_mul_f32_e32 v165, 0x3db504f3, v57
	v_mul_f32_e64 v50, |v165|, s33
	v_exp_f32_e32 v50, v50
	v_or_b32_e32 v164, 17, v11
	v_add_u32_e32 v49, s20, v164
	v_cmp_lt_i32_e64 s[10:11], v48, v49
	v_add_f32_e32 v50, 1.0, v50
	s_and_b64 s[40:41], s[8:9], s[10:11]
	v_cmp_gt_f32_e64 s[10:11], s76, v50
	v_max_f32_e32 v49, 0, v165
	s_nop 0
	v_cndmask_b32_e64 v51, 0, 32, s[10:11]
	v_ldexp_f32 v50, v50, v51
	v_log_f32_e32 v50, v50
	s_nop 0
	v_mul_f32_e32 v51, 0x3f317217, v50
	v_fma_f32 v51, v50, s77, -v51
	v_fmac_f32_e32 v51, 0x3377d1cf, v50
	v_fmac_f32_e32 v51, 0x3f317217, v50
	v_cmp_lt_f32_e64 s[12:13], |v50|, s78
	s_nop 1
	v_cndmask_b32_e64 v50, v50, v51, s[12:13]
	v_cndmask_b32_e64 v51, 0, v154, s[10:11]
	v_sub_f32_e32 v50, v50, v51
	v_add_f32_e32 v166, v49, v50
	v_cndmask_b32_e64 v49, 0, -v166, s[40:41]
	v_bfe_u32 v50, v49, 16, 1
	v_add3_u32 v50, v49, v50, s79
	ds_write_b16_d16_hi v3, v50 offset:38288
	v_and_b32_e32 v50, 0xffff0000, v50
	v_sub_f32_e32 v50, v49, v50
	v_bfe_u32 v51, v50, 16, 1
	v_add3_u32 v50, v50, v51, s79
	ds_write_b16_d16_hi v3, v50 offset:47504
	s_nop 1
	v_add_f32_dpp v49, v49, v49 quad_perm:[1,0,3,2] row_mask:0xf bank_mask:0xf
	s_nop 1
	v_add_f32_dpp v49, v49, v49 quad_perm:[2,3,0,1] row_mask:0xf bank_mask:0xf
	s_nop 1
	v_add_f32_dpp v49, v49, v49 row_half_mirror row_mask:0xf bank_mask:0xf
	s_nop 1
	v_add_f32_dpp v49, v49, v49 row_mirror row_mask:0xf bank_mask:0xf
	s_nop 1
	v_mov_b32_dpp v50, v49 row_bcast:15 row_mask:0xa bank_mask:0xf
	s_and_saveexec_b64 s[10:11], vcc
	s_cbranch_execz .LBB0_1913
	v_lshl_add_u32 v51, v164, 2, v155
	v_add_f32_e32 v49, v49, v50
	ds_add_f32 v51, v49
.LBB0_1913:
	s_or_b64 exec, exec, s[10:11]
	v_mul_f32_e32 v168, 0x3db504f3, v58
	v_mul_f32_e64 v50, |v168|, s33
	v_exp_f32_e32 v50, v50
	v_or_b32_e32 v167, 18, v11
	v_add_u32_e32 v49, s20, v167
	v_cmp_lt_i32_e64 s[10:11], v48, v49
	v_add_f32_e32 v50, 1.0, v50
	s_and_b64 s[42:43], s[8:9], s[10:11]
	v_cmp_gt_f32_e64 s[10:11], s76, v50
	v_max_f32_e32 v49, 0, v168
	s_nop 0
	v_cndmask_b32_e64 v51, 0, 32, s[10:11]
	v_ldexp_f32 v50, v50, v51
	v_log_f32_e32 v50, v50
	s_nop 0
	v_mul_f32_e32 v51, 0x3f317217, v50
	v_fma_f32 v51, v50, s77, -v51
	v_fmac_f32_e32 v51, 0x3377d1cf, v50
	v_fmac_f32_e32 v51, 0x3f317217, v50
	v_cmp_lt_f32_e64 s[12:13], |v50|, s78
	s_nop 1
	v_cndmask_b32_e64 v50, v50, v51, s[12:13]
	v_cndmask_b32_e64 v51, 0, v154, s[10:11]
	v_sub_f32_e32 v50, v50, v51
	v_add_f32_e32 v169, v49, v50
	v_cndmask_b32_e64 v49, 0, -v169, s[42:43]
	v_bfe_u32 v50, v49, 16, 1
	v_add3_u32 v50, v49, v50, s79
	ds_write_b16_d16_hi v3, v50 offset:38432
	v_and_b32_e32 v50, 0xffff0000, v50
	v_sub_f32_e32 v50, v49, v50
	v_bfe_u32 v51, v50, 16, 1
	v_add3_u32 v50, v50, v51, s79
	ds_write_b16_d16_hi v3, v50 offset:47648
	s_nop 1
	v_add_f32_dpp v49, v49, v49 quad_perm:[1,0,3,2] row_mask:0xf bank_mask:0xf
	s_nop 1
	v_add_f32_dpp v49, v49, v49 quad_perm:[2,3,0,1] row_mask:0xf bank_mask:0xf
	s_nop 1
	v_add_f32_dpp v49, v49, v49 row_half_mirror row_mask:0xf bank_mask:0xf
	s_nop 1
	v_add_f32_dpp v49, v49, v49 row_mirror row_mask:0xf bank_mask:0xf
	s_nop 1
	v_mov_b32_dpp v50, v49 row_bcast:15 row_mask:0xa bank_mask:0xf
	s_and_saveexec_b64 s[10:11], vcc
	s_cbranch_execz .LBB0_1915
	v_lshl_add_u32 v51, v167, 2, v155
	v_add_f32_e32 v49, v49, v50
	ds_add_f32 v51, v49
; __device__ __forceinline__ float bf2f(bf16r h) { return __uint_as_float(((unsigned)h) << 16); }
; __device__ __forceinline__ float softplusf(float x) { return fmaxf(x, 0.f) + __logf(1.f + __expf(-fabsf(x))); }
; __device__ __forceinline__ void phase_sb(const Params& p, unsigned char* smem) {
;     ...
;       for (int i = 0; i < 16; i++) {
;         int row = wm * 32 + (i & 3) + 8 * (i >> 2) + 4 * hi;
;         int col = wn * 32 + cl;
;         int t = t0 + row, key = s0 + col;
;         bool m = (key < t) && (key >= NPADR);
;         float z = az[0][0][i] * scale;
;         float sp = softplusf(z);
;         float ln = m ? -sp : 0.f;
;         logsig[i] = z - sp;
;         if (m) mbits |= (1u << i);
;         bf16r hb = f2bf(ln);
;         sHi[row * 72 + col] = hb;
;         sLo[row * 72 + col] = f2bf(ln - bf2f(hb));
;         float rsum = ln;
; #pragma unroll
;         for (int o = 16; o > 0; o >>= 1) rsum += __shfl_xor(rsum, o, 64);
;         if (cl == 0) atomicAdd(&sBlk[row], rsum);
;         if ((i & 3) == 3) __builtin_amdgcn_sched_barrier(0);
;       }
.LBB0_1915:
	s_or_b64 exec, exec, s[10:11]
	v_mul_f32_e32 v171, 0x3db504f3, v59
	v_mul_f32_e64 v50, |v171|, s33
	v_exp_f32_e32 v50, v50
	v_or_b32_e32 v170, 19, v11
	v_add_u32_e32 v49, s20, v170
	v_cmp_lt_i32_e64 s[10:11], v48, v49
	v_add_f32_e32 v50, 1.0, v50
	s_and_b64 s[62:63], s[8:9], s[10:11]
	v_cmp_gt_f32_e64 s[10:11], s76, v50
	v_max_f32_e32 v49, 0, v171
	s_nop 0
	v_cndmask_b32_e64 v51, 0, 32, s[10:11]
	v_ldexp_f32 v50, v50, v51
	v_log_f32_e32 v50, v50
	s_nop 0
	v_mul_f32_e32 v51, 0x3f317217, v50
	v_fma_f32 v51, v50, s77, -v51
	v_fmac_f32_e32 v51, 0x3377d1cf, v50
	v_fmac_f32_e32 v51, 0x3f317217, v50
	v_cmp_lt_f32_e64 s[12:13], |v50|, s78
	s_nop 1
	v_cndmask_b32_e64 v50, v50, v51, s[12:13]
	v_cndmask_b32_e64 v51, 0, v154, s[10:11]
	v_sub_f32_e32 v50, v50, v51
	v_add_f32_e32 v172, v49, v50
	v_cndmask_b32_e64 v49, 0, -v172, s[62:63]
	v_bfe_u32 v50, v49, 16, 1
	v_add3_u32 v50, v49, v50, s79
	ds_write_b16_d16_hi v3, v50 offset:38576
	v_and_b32_e32 v50, 0xffff0000, v50
	v_sub_f32_e32 v50, v49, v50
	v_bfe_u32 v51, v50, 16, 1
	v_add3_u32 v50, v50, v51, s79
	ds_write_b16_d16_hi v3, v50 offset:47792
	s_nop 1
	v_add_f32_dpp v49, v49, v49 quad_perm:[1,0,3,2] row_mask:0xf bank_mask:0xf
	s_nop 1
	v_add_f32_dpp v49, v49, v49 quad_perm:[2,3,0,1] row_mask:0xf bank_mask:0xf
	s_nop 1
	v_add_f32_dpp v49, v49, v49 row_half_mirror row_mask:0xf bank_mask:0xf
	s_nop 1
	v_add_f32_dpp v49, v49, v49 row_mirror row_mask:0xf bank_mask:0xf
	s_nop 1
	v_mov_b32_dpp v50, v49 row_bcast:15 row_mask:0xa bank_mask:0xf
	s_and_saveexec_b64 s[10:11], vcc
	s_cbranch_execz .LBB0_1917
	v_lshl_add_u32 v51, v170, 2, v155
	v_add_f32_e32 v49, v49, v50
	ds_add_f32 v51, v49
.LBB0_1917:
	s_or_b64 exec, exec, s[10:11]
	v_mul_f32_e32 v174, 0x3db504f3, v60
	v_mul_f32_e64 v50, |v174|, s33
	v_exp_f32_e32 v50, v50
	v_or_b32_e32 v173, 24, v11
	v_add_u32_e32 v49, s20, v173
	v_cmp_lt_i32_e64 s[10:11], v48, v49
	v_add_f32_e32 v50, 1.0, v50
	s_and_b64 s[84:85], s[8:9], s[10:11]
	v_cmp_gt_f32_e64 s[10:11], s76, v50
	v_max_f32_e32 v49, 0, v174
	s_nop 0
	v_cndmask_b32_e64 v51, 0, 32, s[10:11]
	v_ldexp_f32 v50, v50, v51
	v_log_f32_e32 v50, v50
	s_nop 0
	v_mul_f32_e32 v51, 0x3f317217, v50
	v_fma_f32 v51, v50, s77, -v51
	v_fmac_f32_e32 v51, 0x3377d1cf, v50
	v_fmac_f32_e32 v51, 0x3f317217, v50
	v_cmp_lt_f32_e64 s[12:13], |v50|, s78
	s_nop 1
	v_cndmask_b32_e64 v50, v50, v51, s[12:13]
	v_cndmask_b32_e64 v51, 0, v154, s[10:11]
	v_sub_f32_e32 v50, v50, v51
	v_add_f32_e32 v175, v49, v50
	v_cndmask_b32_e64 v49, 0, -v175, s[84:85]
	v_bfe_u32 v50, v49, 16, 1
	v_add3_u32 v50, v49, v50, s79
	ds_write_b16_d16_hi v3, v50 offset:39296
	v_and_b32_e32 v50, 0xffff0000, v50
	v_sub_f32_e32 v50, v49, v50
	v_bfe_u32 v51, v50, 16, 1
	v_add3_u32 v50, v50, v51, s79
	ds_write_b16_d16_hi v3, v50 offset:48512
	s_nop 1
	v_add_f32_dpp v49, v49, v49 quad_perm:[1,0,3,2] row_mask:0xf bank_mask:0xf
	s_nop 1
	v_add_f32_dpp v49, v49, v49 quad_perm:[2,3,0,1] row_mask:0xf bank_mask:0xf
	s_nop 1
	v_add_f32_dpp v49, v49, v49 row_half_mirror row_mask:0xf bank_mask:0xf
	s_nop 1
	v_add_f32_dpp v49, v49, v49 row_mirror row_mask:0xf bank_mask:0xf
	s_nop 1
	v_mov_b32_dpp v50, v49 row_bcast:15 row_mask:0xa bank_mask:0xf
	s_and_saveexec_b64 s[10:11], vcc
	s_cbranch_execz .LBB0_1919
	v_lshl_add_u32 v51, v173, 2, v155
	v_add_f32_e32 v49, v49, v50
	ds_add_f32 v51, v49
; __device__ __forceinline__ float bf2f(bf16r h) { return __uint_as_float(((unsigned)h) << 16); }
; __device__ __forceinline__ float softplusf(float x) { return fmaxf(x, 0.f) + __logf(1.f + __expf(-fabsf(x))); }
; __device__ __forceinline__ void phase_sb(const Params& p, unsigned char* smem) {
;     ...
;       for (int i = 0; i < 16; i++) {
;         int row = wm * 32 + (i & 3) + 8 * (i >> 2) + 4 * hi;
;         int col = wn * 32 + cl;
;         int t = t0 + row, key = s0 + col;
;         bool m = (key < t) && (key >= NPADR);
;         float z = az[0][0][i] * scale;
;         float sp = softplusf(z);
;         float ln = m ? -sp : 0.f;
;         logsig[i] = z - sp;
;         if (m) mbits |= (1u << i);
;         bf16r hb = f2bf(ln);
;         sHi[row * 72 + col] = hb;
;         sLo[row * 72 + col] = f2bf(ln - bf2f(hb));
;         float rsum = ln;
; #pragma unroll
;         for (int o = 16; o > 0; o >>= 1) rsum += __shfl_xor(rsum, o, 64);
;         if (cl == 0) atomicAdd(&sBlk[row], rsum);
;         if ((i & 3) == 3) __builtin_amdgcn_sched_barrier(0);
;       }
.LBB0_1919:
	s_or_b64 exec, exec, s[10:11]
	v_mul_f32_e32 v177, 0x3db504f3, v61
	v_mul_f32_e64 v50, |v177|, s33
	v_exp_f32_e32 v50, v50
	v_or_b32_e32 v176, 25, v11
	v_add_u32_e32 v49, s20, v176
	v_cmp_lt_i32_e64 s[10:11], v48, v49
	v_add_f32_e32 v50, 1.0, v50
	s_and_b64 s[88:89], s[8:9], s[10:11]
	v_cmp_gt_f32_e64 s[10:11], s76, v50
	v_max_f32_e32 v49, 0, v177
	s_nop 0
	v_cndmask_b32_e64 v51, 0, 32, s[10:11]
	v_ldexp_f32 v50, v50, v51
	v_log_f32_e32 v50, v50
	s_nop 0
	v_mul_f32_e32 v51, 0x3f317217, v50
	v_fma_f32 v51, v50, s77, -v51
	v_fmac_f32_e32 v51, 0x3377d1cf, v50
	v_fmac_f32_e32 v51, 0x3f317217, v50
	v_cmp_lt_f32_e64 s[12:13], |v50|, s78
	s_nop 1
	v_cndmask_b32_e64 v50, v50, v51, s[12:13]
	v_cndmask_b32_e64 v51, 0, v154, s[10:11]
	v_sub_f32_e32 v50, v50, v51
	v_add_f32_e32 v178, v49, v50
	v_cndmask_b32_e64 v49, 0, -v178, s[88:89]
	v_bfe_u32 v50, v49, 16, 1
	v_add3_u32 v50, v49, v50, s79
	ds_write_b16_d16_hi v3, v50 offset:39440
	v_and_b32_e32 v50, 0xffff0000, v50
	v_sub_f32_e32 v50, v49, v50
	v_bfe_u32 v51, v50, 16, 1
	v_add3_u32 v50, v50, v51, s79
	ds_write_b16_d16_hi v3, v50 offset:48656
	s_nop 1
	v_add_f32_dpp v49, v49, v49 quad_perm:[1,0,3,2] row_mask:0xf bank_mask:0xf
	s_nop 1
	v_add_f32_dpp v49, v49, v49 quad_perm:[2,3,0,1] row_mask:0xf bank_mask:0xf
	s_nop 1
	v_add_f32_dpp v49, v49, v49 row_half_mirror row_mask:0xf bank_mask:0xf
	s_nop 1
	v_add_f32_dpp v49, v49, v49 row_mirror row_mask:0xf bank_mask:0xf
	s_nop 1
	v_mov_b32_dpp v50, v49 row_bcast:15 row_mask:0xa bank_mask:0xf
	s_and_saveexec_b64 s[10:11], vcc
	s_cbranch_execz .LBB0_1921
	v_lshl_add_u32 v51, v176, 2, v155
	v_add_f32_e32 v49, v49, v50
	ds_add_f32 v51, v49
.LBB0_1921:
	s_or_b64 exec, exec, s[10:11]
	v_mul_f32_e32 v180, 0x3db504f3, v62
	v_mul_f32_e64 v50, |v180|, s33
	v_exp_f32_e32 v50, v50
	v_or_b32_e32 v179, 26, v11
	v_add_u32_e32 v49, s20, v179
	v_cmp_lt_i32_e64 s[10:11], v48, v49
	v_add_f32_e32 v50, 1.0, v50
	s_and_b64 s[90:91], s[8:9], s[10:11]
	v_cmp_gt_f32_e64 s[10:11], s76, v50
	v_max_f32_e32 v49, 0, v180
	s_nop 0
	v_cndmask_b32_e64 v51, 0, 32, s[10:11]
	v_ldexp_f32 v50, v50, v51
	v_log_f32_e32 v50, v50
	s_nop 0
	v_mul_f32_e32 v51, 0x3f317217, v50
	v_fma_f32 v51, v50, s77, -v51
	v_fmac_f32_e32 v51, 0x3377d1cf, v50
	v_fmac_f32_e32 v51, 0x3f317217, v50
	v_cmp_lt_f32_e64 s[12:13], |v50|, s78
	s_nop 1
	v_cndmask_b32_e64 v50, v50, v51, s[12:13]
	v_cndmask_b32_e64 v51, 0, v154, s[10:11]
	v_sub_f32_e32 v50, v50, v51
	v_add_f32_e32 v181, v49, v50
	v_cndmask_b32_e64 v49, 0, -v181, s[90:91]
	v_bfe_u32 v50, v49, 16, 1
	v_add3_u32 v50, v49, v50, s79
	ds_write_b16_d16_hi v3, v50 offset:39584
	v_and_b32_e32 v50, 0xffff0000, v50
	v_sub_f32_e32 v50, v49, v50
	v_bfe_u32 v51, v50, 16, 1
	v_add3_u32 v50, v50, v51, s79
	ds_write_b16_d16_hi v3, v50 offset:48800
	s_nop 1
	v_add_f32_dpp v49, v49, v49 quad_perm:[1,0,3,2] row_mask:0xf bank_mask:0xf
	s_nop 1
	v_add_f32_dpp v49, v49, v49 quad_perm:[2,3,0,1] row_mask:0xf bank_mask:0xf
	s_nop 1
	v_add_f32_dpp v49, v49, v49 row_half_mirror row_mask:0xf bank_mask:0xf
	s_nop 1
	v_add_f32_dpp v49, v49, v49 row_mirror row_mask:0xf bank_mask:0xf
	s_nop 1
	v_mov_b32_dpp v50, v49 row_bcast:15 row_mask:0xa bank_mask:0xf
	s_and_saveexec_b64 s[10:11], vcc
	s_cbranch_execz .LBB0_1923
	v_lshl_add_u32 v51, v179, 2, v155
	v_add_f32_e32 v49, v49, v50
	ds_add_f32 v51, v49
.LBB0_1923:
	s_or_b64 exec, exec, s[10:11]
	v_or_b32_e32 v182, 27, v11
	v_add_u32_e32 v49, s20, v182
	v_mul_f32_e32 v183, 0x3db504f3, v63
	v_cmp_lt_i32_e64 s[10:11], v48, v49
	v_mul_f32_e64 v49, |v183|, s33
	v_exp_f32_e32 v49, v49
	s_and_b64 s[12:13], s[8:9], s[10:11]
	v_max_f32_e32 v48, 0, v183
	v_add_f32_e32 v49, 1.0, v49
	v_cmp_gt_f32_e64 s[8:9], s76, v49
	s_nop 0
	v_cndmask_b32_e64 v50, 0, 32, s[8:9]
	v_ldexp_f32 v49, v49, v50
	v_log_f32_e32 v49, v49
	s_nop 0
	v_mul_f32_e32 v50, 0x3f317217, v49
	v_fma_f32 v50, v49, s77, -v50
	v_fmac_f32_e32 v50, 0x3377d1cf, v49
	v_fmac_f32_e32 v50, 0x3f317217, v49
	v_cmp_lt_f32_e64 s[10:11], |v49|, s78
	s_nop 1
	v_cndmask_b32_e64 v49, v49, v50, s[10:11]
	v_cndmask_b32_e64 v50, 0, v154, s[8:9]
	v_sub_f32_e32 v49, v49, v50
	v_add_f32_e32 v184, v48, v49
	v_cndmask_b32_e64 v48, 0, -v184, s[12:13]
	v_bfe_u32 v49, v48, 16, 1
	v_add3_u32 v49, v48, v49, s79
	ds_write_b16_d16_hi v3, v49 offset:39728
	v_and_b32_e32 v49, 0xffff0000, v49
	v_sub_f32_e32 v49, v48, v49
	v_bfe_u32 v50, v49, 16, 1
	v_add3_u32 v49, v49, v50, s79
	ds_write_b16_d16_hi v3, v49 offset:48944
	s_nop 1
	v_add_f32_dpp v3, v48, v48 quad_perm:[1,0,3,2] row_mask:0xf bank_mask:0xf
	s_nop 1
	v_add_f32_dpp v3, v3, v3 quad_perm:[2,3,0,1] row_mask:0xf bank_mask:0xf
	s_nop 1
	v_add_f32_dpp v3, v3, v3 row_half_mirror row_mask:0xf bank_mask:0xf
	s_nop 1
	v_add_f32_dpp v3, v3, v3 row_mirror row_mask:0xf bank_mask:0xf
	s_nop 1
	v_mov_b32_dpp v48, v3 row_bcast:15 row_mask:0xa bank_mask:0xf
	s_and_saveexec_b64 s[8:9], vcc
	s_cbranch_execz .LBB0_1925
	v_lshl_add_u32 v49, v182, 2, v155
	v_add_f32_e32 v3, v3, v48
	ds_add_f32 v49, v3
	s_waitcnt lgkmcnt(0)

; __device__ __forceinline__ float bf2f(bf16r h) { return __uint_as_float(((unsigned)h) << 16); }
; __device__ __forceinline__ float siluf(float x) { return x / (1.f + __expf(-x)); }
; __device__ __forceinline__ void phase_ssd_out(const Params& p, int layer, unsigned char* smem) {
;     ...
;       {
;         const int t2 = relaunder(tid);
;         const int lane = t2 & 63, hi = lane >> 5, cl = lane & 31, wm = t2 >> 7, wn = (t2 >> 6) & 1;
; #pragma unroll
;         for (int mt = 0; mt < 2; mt++)
; #pragma unroll
;           for (int i = 0; i < 16; i++) {
;             int row = wm * 64 + mt * 32 + (i & 3) + 8 * (i >> 2) + 4 * hi;
;             int col = wn * 32 + cl;
;             bf16r* ybb = yb + (size_t)c * 128 * 1024 + h * 64;
;             unsigned off = (unsigned)(row * 1024 + col);
;             float z = bf2f(ybb[off]);
;             float y = ay[mt][0][i] * siluf(z);
;             *(ybb + off) = f2bf(y);
;             float sq = y * y;
; #pragma unroll
;             for (int o = 16; o > 0; o >>= 1) sq += __shfl_xor(sq, o, 64);
;             if (cl == 0) atomicAdd(&sRow[row], sq);
;             if ((i & 3) == 3) __builtin_amdgcn_sched_barrier(0);
;           }
;       }
.LBB0_3885:
	s_waitcnt vmcnt(0)
	v_mov_b32_e32 v98, v96
	s_lshl_b32 s6, s6, 7
	v_lshrrev_b32_e32 v144, 3, v98
	v_ashrrev_i32_e32 v143, 1, v98
	v_and_b32_e32 v144, 4, v144
	v_and_b32_e32 v142, 31, v98
	v_and_or_b32 v167, v143, s31, v144
	v_lshrrev_b32_e32 v98, 1, v98
	v_and_b32_e32 v168, 32, v98
	s_add_u32 s18, s77, s6
	v_lshlrev_b32_e32 v98, 10, v167
	s_addc_u32 s19, s78, 0
	v_or3_b32 v98, v98, v168, v142
	v_lshl_add_u64 v[170:171], v[98:99], 1, s[18:19]
	v_lshlrev_b32_e32 v248, 1, v98
	v_add_u32_e32 v240, 0x1000, v248
	v_add_u32_e32 v241, 0x5000, v248
	v_add_u32_e32 v242, 0x9000, v248
	v_add_u32_e32 v243, 0xd000, v248
	v_add_u32_e32 v244, 0x11000, v248
	v_add_u32_e32 v245, 0x15000, v248
	v_add_u32_e32 v246, 0x19000, v248
	v_add_u32_e32 v247, 0x1d000, v248
	global_load_ushort v207, v240, s[18:19] offset:-4096
	global_load_ushort v208, v240, s[18:19] offset:-2048
	global_load_ushort v209, v240, s[18:19] offset:0
	global_load_ushort v210, v240, s[18:19] offset:2048
	global_load_ushort v211, v241, s[18:19] offset:-4096
	global_load_ushort v212, v241, s[18:19] offset:-2048
	global_load_ushort v213, v241, s[18:19] offset:0
	global_load_ushort v214, v241, s[18:19] offset:2048
	global_load_ushort v215, v242, s[18:19] offset:-4096
	global_load_ushort v216, v242, s[18:19] offset:-2048
	global_load_ushort v217, v242, s[18:19] offset:0
	global_load_ushort v218, v242, s[18:19] offset:2048
	global_load_ushort v219, v243, s[18:19] offset:-4096
	global_load_ushort v220, v243, s[18:19] offset:-2048
	global_load_ushort v221, v243, s[18:19] offset:0
	global_load_ushort v222, v243, s[18:19] offset:2048
	global_load_ushort v223, v244, s[18:19] offset:-4096
	global_load_ushort v224, v244, s[18:19] offset:-2048
	global_load_ushort v225, v244, s[18:19] offset:0
	global_load_ushort v226, v244, s[18:19] offset:2048
	global_load_ushort v227, v245, s[18:19] offset:-4096
	global_load_ushort v228, v245, s[18:19] offset:-2048
	global_load_ushort v229, v245, s[18:19] offset:0
	global_load_ushort v231, v245, s[18:19] offset:2048
	global_load_ushort v232, v246, s[18:19] offset:-4096
	global_load_ushort v233, v246, s[18:19] offset:-2048
	global_load_ushort v234, v246, s[18:19] offset:0
	global_load_ushort v235, v246, s[18:19] offset:2048
	global_load_ushort v236, v247, s[18:19] offset:-4096
	global_load_ushort v237, v247, s[18:19] offset:-2048
	global_load_ushort v238, v247, s[18:19] offset:0
	global_load_ushort v239, v247, s[18:19] offset:2048
	s_waitcnt vmcnt(0)
	v_mov_b32_e32 v98, v207
	v_and_b32_e32 v143, 64, v164
	v_xor_b32_e32 v144, 16, v164
	v_add_u32_e32 v146, 64, v143
	v_cmp_lt_i32_e32 vcc, v144, v146
	v_lshlrev_b32_e32 v98, 16, v98
	v_mul_f32_e32 v145, 0xbfb8aa3b, v98
	v_exp_f32_e32 v145, v145
	v_cndmask_b32_e32 v143, v164, v144, vcc
	v_lshlrev_b32_e32 v143, 2, v143
	v_add_f32_e32 v144, 1.0, v145
	v_div_scale_f32 v145, s[6:7], v144, v144, v98
	v_rcp_f32_e32 v147, v145
	v_div_scale_f32 v169, vcc, v98, v144, v98
	v_cmp_eq_u32_e64 s[6:7], 16, v142
	v_fma_f32 v172, -v145, v147, 1.0
	v_fmac_f32_e32 v147, v172, v147
	v_mul_f32_e32 v172, v169, v147
	v_fma_f32 v173, -v145, v172, v169
	v_fmac_f32_e32 v172, v173, v147
	v_fma_f32 v145, -v145, v172, v169
	v_div_fmas_f32 v145, v145, v147, v172
	v_div_fixup_f32 v98, v145, v144, v98
	v_mul_f32_e32 v172, v80, v98
	v_mul_f32_e32 v80, v172, v172
	s_nop 1
	v_mov_b32_dpp v98, v80 quad_perm:[1,0,3,2] row_mask:0xf bank_mask:0xf
	v_xor_b32_e32 v80, 8, v164
	v_cmp_lt_i32_e32 vcc, v80, v146
	v_xor_b32_e32 v144, 4, v164
	v_xor_b32_e32 v169, 1, v164
	v_cndmask_b32_e32 v80, v164, v80, vcc
	v_lshlrev_b32_e32 v80, 2, v80
	s_waitcnt lgkmcnt(0)
	v_fmac_f32_e32 v98, v172, v172
	s_nop 1
	v_add_f32_dpp v98, v98, v98 quad_perm:[2,3,0,1] row_mask:0xf bank_mask:0xf
	v_cmp_lt_i32_e32 vcc, v144, v146
	v_cndmask_b32_e32 v144, v164, v144, vcc
	v_lshlrev_b32_e32 v144, 2, v144
	s_nop 1
	v_add_f32_dpp v98, v98, v98 row_half_mirror row_mask:0xf bank_mask:0xf
	v_xor_b32_e32 v145, 2, v164
	v_cmp_lt_i32_e32 vcc, v145, v146
	v_cndmask_b32_e32 v145, v164, v145, vcc
	v_lshlrev_b32_e32 v145, 2, v145
	s_nop 1
	v_add_f32_dpp v98, v98, v98 row_mirror row_mask:0xf bank_mask:0xf
	v_cmp_lt_i32_e32 vcc, v169, v146
	v_cndmask_b32_e32 v146, v164, v169, vcc
	v_lshlrev_b32_e32 v147, 2, v146
	s_nop 1
	v_mov_b32_dpp v169, v98 row_bcast:15 row_mask:0xa bank_mask:0xf
	v_bfe_u32 v146, v172, 16, 1
	v_add3_u32 v146, v172, v146, s30
	global_store_short_d16_hi v[170:171], v146, off
	v_lshlrev_b32_e32 v146, 2, v167
	s_and_saveexec_b64 s[20:21], s[6:7]
	s_cbranch_execz .LBB0_3887
	v_add_f32_e32 v98, v98, v169
	ds_add_f32 v146, v98 offset:38400
.LBB0_3887:
	s_or_b64 exec, exec, s[20:21]
	v_lshl_or_b32 v167, v167, 10, v168
	v_or3_b32 v98, v167, v142, s33
	v_lshl_add_u64 v[168:169], v[98:99], 1, s[18:19]
	v_mov_b32_e32 v98, v208
	v_lshlrev_b32_e32 v98, 16, v98
	v_mul_f32_e32 v170, 0xbfb8aa3b, v98
	v_exp_f32_e32 v170, v170
	s_nop 0
	v_add_f32_e32 v170, 1.0, v170
	v_div_scale_f32 v171, s[20:21], v170, v170, v98
	v_rcp_f32_e32 v172, v171
	v_div_scale_f32 v173, vcc, v98, v170, v98
	v_fma_f32 v174, -v171, v172, 1.0
	v_fmac_f32_e32 v172, v174, v172
	v_mul_f32_e32 v174, v173, v172
	v_fma_f32 v175, -v171, v174, v173
	v_fmac_f32_e32 v174, v175, v172
	v_fma_f32 v171, -v171, v174, v173
	v_div_fmas_f32 v171, v171, v172, v174
	v_div_fixup_f32 v98, v171, v170, v98
	v_mul_f32_e32 v170, v81, v98
	v_mul_f32_e32 v81, v170, v170
	s_nop 1
	v_mov_b32_dpp v81, v81 quad_perm:[1,0,3,2] row_mask:0xf bank_mask:0xf
	v_bfe_u32 v171, v170, 16, 1
	v_fmac_f32_e32 v81, v170, v170
	s_nop 1
	v_add_f32_dpp v81, v81, v81 quad_perm:[2,3,0,1] row_mask:0xf bank_mask:0xf
	v_add3_u32 v170, v170, v171, s30
	global_store_short_d16_hi v[168:169], v170, off
	s_nop 1
	v_add_f32_dpp v81, v81, v81 row_half_mirror row_mask:0xf bank_mask:0xf
	s_nop 1
	v_add_f32_dpp v81, v81, v81 row_mirror row_mask:0xf bank_mask:0xf
	s_nop 1
	v_mov_b32_dpp v98, v81 row_bcast:15 row_mask:0xa bank_mask:0xf
	s_and_saveexec_b64 s[20:21], s[6:7]
	s_cbranch_execz .LBB0_3889
	v_add_f32_e32 v81, v81, v98
	ds_add_f32 v146, v81 offset:38404
; __device__ __forceinline__ float bf2f(bf16r h) { return __uint_as_float(((unsigned)h) << 16); }
; __device__ __forceinline__ float siluf(float x) { return x / (1.f + __expf(-x)); }
; __device__ __forceinline__ void phase_ssd_out(const Params& p, int layer, unsigned char* smem) {
;     ...
;       {
;         const int t2 = relaunder(tid);
;         const int lane = t2 & 63, hi = lane >> 5, cl = lane & 31, wm = t2 >> 7, wn = (t2 >> 6) & 1;
; #pragma unroll
;         for (int mt = 0; mt < 2; mt++)
; #pragma unroll
;           for (int i = 0; i < 16; i++) {
;             int row = wm * 64 + mt * 32 + (i & 3) + 8 * (i >> 2) + 4 * hi;
;             int col = wn * 32 + cl;
;             bf16r* ybb = yb + (size_t)c * 128 * 1024 + h * 64;
;             unsigned off = (unsigned)(row * 1024 + col);
;             float z = bf2f(ybb[off]);
;             float y = ay[mt][0][i] * siluf(z);
;             *(ybb + off) = f2bf(y);
;             float sq = y * y;
; #pragma unroll
;             for (int o = 16; o > 0; o >>= 1) sq += __shfl_xor(sq, o, 64);
;             if (cl == 0) atomicAdd(&sRow[row], sq);
;             if ((i & 3) == 3) __builtin_amdgcn_sched_barrier(0);
;           }
;       }
.LBB0_3889:
	s_or_b64 exec, exec, s[20:21]
	v_or3_b32 v98, v167, v142, s34
	v_lshl_add_u64 v[168:169], v[98:99], 1, s[18:19]
	v_mov_b32_e32 v81, v209
	v_lshlrev_b32_e32 v81, 16, v81
	v_mul_f32_e32 v98, 0xbfb8aa3b, v81
	v_exp_f32_e32 v98, v98
	s_nop 0
	v_add_f32_e32 v98, 1.0, v98
	v_div_scale_f32 v170, s[20:21], v98, v98, v81
	v_rcp_f32_e32 v171, v170
	v_div_scale_f32 v172, vcc, v81, v98, v81
	v_fma_f32 v173, -v170, v171, 1.0
	v_fmac_f32_e32 v171, v173, v171
	v_mul_f32_e32 v173, v172, v171
	v_fma_f32 v174, -v170, v173, v172
	v_fmac_f32_e32 v173, v174, v171
	v_fma_f32 v170, -v170, v173, v172
	v_div_fmas_f32 v170, v170, v171, v173
	v_div_fixup_f32 v81, v170, v98, v81
	v_mul_f32_e32 v98, v82, v81
	v_mul_f32_e32 v81, v98, v98
	s_nop 1
	v_mov_b32_dpp v81, v81 quad_perm:[1,0,3,2] row_mask:0xf bank_mask:0xf
	v_bfe_u32 v170, v98, 16, 1
	v_fmac_f32_e32 v81, v98, v98
	s_nop 1
	v_add_f32_dpp v81, v81, v81 quad_perm:[2,3,0,1] row_mask:0xf bank_mask:0xf
	v_add3_u32 v98, v98, v170, s30
	global_store_short_d16_hi v[168:169], v98, off
	s_nop 1
	v_add_f32_dpp v81, v81, v81 row_half_mirror row_mask:0xf bank_mask:0xf
	s_nop 1
	v_add_f32_dpp v81, v81, v81 row_mirror row_mask:0xf bank_mask:0xf
	s_nop 1
	v_mov_b32_dpp v82, v81 row_bcast:15 row_mask:0xa bank_mask:0xf
	s_and_saveexec_b64 s[20:21], s[6:7]
	s_cbranch_execz .LBB0_3891
	v_add_f32_e32 v81, v81, v82
	ds_add_f32 v146, v81 offset:38408
.LBB0_3891:
	s_or_b64 exec, exec, s[20:21]
	v_or3_b32 v98, v167, v142, s35
	v_lshl_add_u64 v[168:169], v[98:99], 1, s[18:19]
	v_mov_b32_e32 v81, v210
	v_lshlrev_b32_e32 v81, 16, v81
	v_mul_f32_e32 v82, 0xbfb8aa3b, v81
	v_exp_f32_e32 v82, v82
	s_nop 0
	v_add_f32_e32 v82, 1.0, v82
	v_div_scale_f32 v98, s[20:21], v82, v82, v81
	v_rcp_f32_e32 v170, v98
	v_div_scale_f32 v171, vcc, v81, v82, v81
	v_fma_f32 v172, -v98, v170, 1.0
	v_fmac_f32_e32 v170, v172, v170
	v_mul_f32_e32 v172, v171, v170
	v_fma_f32 v173, -v98, v172, v171
	v_fmac_f32_e32 v172, v173, v170
	v_fma_f32 v98, -v98, v172, v171
	v_div_fmas_f32 v98, v98, v170, v172
	v_div_fixup_f32 v81, v98, v82, v81
	v_mul_f32_e32 v83, v83, v81
	v_mul_f32_e32 v81, v83, v83
	s_nop 1
	v_mov_b32_dpp v81, v81 quad_perm:[1,0,3,2] row_mask:0xf bank_mask:0xf
	v_bfe_u32 v98, v83, 16, 1
	v_fmac_f32_e32 v81, v83, v83
	s_nop 1
	v_add_f32_dpp v81, v81, v81 quad_perm:[2,3,0,1] row_mask:0xf bank_mask:0xf
	v_add3_u32 v83, v83, v98, s30
	global_store_short_d16_hi v[168:169], v83, off
	s_nop 1
	v_add_f32_dpp v81, v81, v81 row_half_mirror row_mask:0xf bank_mask:0xf
	s_nop 1
	v_add_f32_dpp v81, v81, v81 row_mirror row_mask:0xf bank_mask:0xf
	s_nop 1
	v_mov_b32_dpp v82, v81 row_bcast:15 row_mask:0xa bank_mask:0xf
	s_and_saveexec_b64 s[20:21], s[6:7]
	s_cbranch_execz .LBB0_3893
	v_add_f32_e32 v81, v81, v82
	ds_add_f32 v146, v81 offset:38412
.LBB0_3893:
	s_or_b64 exec, exec, s[20:21]
	v_or3_b32 v98, v167, v142, s36
	v_lshl_add_u64 v[168:169], v[98:99], 1, s[18:19]
	v_mov_b32_e32 v81, v211
	v_lshlrev_b32_e32 v81, 16, v81
	v_mul_f32_e32 v82, 0xbfb8aa3b, v81
	v_exp_f32_e32 v82, v82
	s_nop 0
	v_add_f32_e32 v82, 1.0, v82
	v_div_scale_f32 v83, s[20:21], v82, v82, v81
	v_rcp_f32_e32 v98, v83
	v_div_scale_f32 v170, vcc, v81, v82, v81
	v_fma_f32 v171, -v83, v98, 1.0
	v_fmac_f32_e32 v98, v171, v98
	v_mul_f32_e32 v171, v170, v98
	v_fma_f32 v172, -v83, v171, v170
	v_fmac_f32_e32 v171, v172, v98
	v_fma_f32 v83, -v83, v171, v170
	v_div_fmas_f32 v83, v83, v98, v171
	v_div_fixup_f32 v81, v83, v82, v81
	v_mul_f32_e32 v83, v84, v81
	v_mul_f32_e32 v81, v83, v83
	s_nop 1
	v_mov_b32_dpp v81, v81 quad_perm:[1,0,3,2] row_mask:0xf bank_mask:0xf
	v_bfe_u32 v84, v83, 16, 1
	v_fmac_f32_e32 v81, v83, v83
	s_nop 1
	v_add_f32_dpp v81, v81, v81 quad_perm:[2,3,0,1] row_mask:0xf bank_mask:0xf
	v_add3_u32 v83, v83, v84, s30
	global_store_short_d16_hi v[168:169], v83, off
	s_nop 1
	v_add_f32_dpp v81, v81, v81 row_half_mirror row_mask:0xf bank_mask:0xf
	s_nop 1
	v_add_f32_dpp v81, v81, v81 row_mirror row_mask:0xf bank_mask:0xf
	s_nop 1
	v_mov_b32_dpp v82, v81 row_bcast:15 row_mask:0xa bank_mask:0xf
	s_and_saveexec_b64 s[20:21], s[6:7]
	s_cbranch_execz .LBB0_3895
	v_add_f32_e32 v81, v81, v82
	ds_add_f32 v146, v81 offset:38432
.LBB0_3895:
	s_or_b64 exec, exec, s[20:21]
	v_or3_b32 v98, v167, v142, s25
	v_lshl_add_u64 v[168:169], v[98:99], 1, s[18:19]
	v_mov_b32_e32 v81, v212
	v_lshlrev_b32_e32 v81, 16, v81
	v_mul_f32_e32 v82, 0xbfb8aa3b, v81
	v_exp_f32_e32 v82, v82
	s_nop 0
	v_add_f32_e32 v82, 1.0, v82
	v_div_scale_f32 v83, s[20:21], v82, v82, v81
	v_rcp_f32_e32 v84, v83
	v_div_scale_f32 v98, vcc, v81, v82, v81
	v_fma_f32 v170, -v83, v84, 1.0
	v_fmac_f32_e32 v84, v170, v84
	v_mul_f32_e32 v170, v98, v84
	v_fma_f32 v171, -v83, v170, v98
	v_fmac_f32_e32 v170, v171, v84
	v_fma_f32 v83, -v83, v170, v98
	v_div_fmas_f32 v83, v83, v84, v170
	v_div_fixup_f32 v81, v83, v82, v81
	v_mul_f32_e32 v83, v85, v81
	v_mul_f32_e32 v81, v83, v83
	s_nop 1
	v_mov_b32_dpp v81, v81 quad_perm:[1,0,3,2] row_mask:0xf bank_mask:0xf
	v_bfe_u32 v84, v83, 16, 1
	v_fmac_f32_e32 v81, v83, v83
	s_nop 1
	v_add_f32_dpp v81, v81, v81 quad_perm:[2,3,0,1] row_mask:0xf bank_mask:0xf
	v_add3_u32 v83, v83, v84, s30
	global_store_short_d16_hi v[168:169], v83, off
	s_nop 1
	v_add_f32_dpp v81, v81, v81 row_half_mirror row_mask:0xf bank_mask:0xf
	s_nop 1
	v_add_f32_dpp v81, v81, v81 row_mirror row_mask:0xf bank_mask:0xf
	s_nop 1
	v_mov_b32_dpp v82, v81 row_bcast:15 row_mask:0xa bank_mask:0xf
	s_and_saveexec_b64 s[20:21], s[6:7]
	s_cbranch_execz .LBB0_3897
	v_add_f32_e32 v81, v81, v82
	ds_add_f32 v146, v81 offset:38436
; __device__ __forceinline__ float bf2f(bf16r h) { return __uint_as_float(((unsigned)h) << 16); }
; __device__ __forceinline__ float siluf(float x) { return x / (1.f + __expf(-x)); }
; __device__ __forceinline__ void phase_ssd_out(const Params& p, int layer, unsigned char* smem) {
;     ...
;       {
;         const int t2 = relaunder(tid);
;         const int lane = t2 & 63, hi = lane >> 5, cl = lane & 31, wm = t2 >> 7, wn = (t2 >> 6) & 1;
; #pragma unroll
;         for (int mt = 0; mt < 2; mt++)
; #pragma unroll
;           for (int i = 0; i < 16; i++) {
;             int row = wm * 64 + mt * 32 + (i & 3) + 8 * (i >> 2) + 4 * hi;
;             int col = wn * 32 + cl;
;             bf16r* ybb = yb + (size_t)c * 128 * 1024 + h * 64;
;             unsigned off = (unsigned)(row * 1024 + col);
;             float z = bf2f(ybb[off]);
;             float y = ay[mt][0][i] * siluf(z);
;             *(ybb + off) = f2bf(y);
;             float sq = y * y;
; #pragma unroll
;             for (int o = 16; o > 0; o >>= 1) sq += __shfl_xor(sq, o, 64);
;             if (cl == 0) atomicAdd(&sRow[row], sq);
;             if ((i & 3) == 3) __builtin_amdgcn_sched_barrier(0);
;           }
;       }
.LBB0_3897:
	s_or_b64 exec, exec, s[20:21]
	v_or3_b32 v98, v167, v142, s37
	v_lshl_add_u64 v[84:85], v[98:99], 1, s[18:19]
	v_mov_b32_e32 v81, v213
	v_lshlrev_b32_e32 v81, 16, v81
	v_mul_f32_e32 v82, 0xbfb8aa3b, v81
	v_exp_f32_e32 v82, v82
	s_nop 0
	v_add_f32_e32 v82, 1.0, v82
	v_div_scale_f32 v83, s[20:21], v82, v82, v81
	v_rcp_f32_e32 v98, v83
	v_div_scale_f32 v168, vcc, v81, v82, v81
	v_fma_f32 v169, -v83, v98, 1.0
	v_fmac_f32_e32 v98, v169, v98
	v_mul_f32_e32 v169, v168, v98
	v_fma_f32 v170, -v83, v169, v168
	v_fmac_f32_e32 v169, v170, v98
	v_fma_f32 v83, -v83, v169, v168
	v_div_fmas_f32 v83, v83, v98, v169
	v_div_fixup_f32 v81, v83, v82, v81
	v_mul_f32_e32 v83, v86, v81
	v_mul_f32_e32 v81, v83, v83
	s_nop 1
	v_mov_b32_dpp v81, v81 quad_perm:[1,0,3,2] row_mask:0xf bank_mask:0xf
	v_bfe_u32 v86, v83, 16, 1
	v_fmac_f32_e32 v81, v83, v83
	s_nop 1
	v_add_f32_dpp v81, v81, v81 quad_perm:[2,3,0,1] row_mask:0xf bank_mask:0xf
	v_add3_u32 v83, v83, v86, s30
	global_store_short_d16_hi v[84:85], v83, off
	s_nop 1
	v_add_f32_dpp v81, v81, v81 row_half_mirror row_mask:0xf bank_mask:0xf
	s_nop 1
	v_add_f32_dpp v81, v81, v81 row_mirror row_mask:0xf bank_mask:0xf
	s_nop 1
	v_mov_b32_dpp v82, v81 row_bcast:15 row_mask:0xa bank_mask:0xf
	s_and_saveexec_b64 s[20:21], s[6:7]
	s_cbranch_execz .LBB0_3899
	v_add_f32_e32 v81, v81, v82
	ds_add_f32 v146, v81 offset:38440
.LBB0_3899:
	s_or_b64 exec, exec, s[20:21]
	v_or3_b32 v98, v167, v142, s38
	v_lshl_add_u64 v[84:85], v[98:99], 1, s[18:19]
	v_mov_b32_e32 v81, v214
	v_lshlrev_b32_e32 v81, 16, v81
	v_mul_f32_e32 v82, 0xbfb8aa3b, v81
	v_exp_f32_e32 v82, v82
	s_nop 0
	v_add_f32_e32 v82, 1.0, v82
	v_div_scale_f32 v83, s[20:21], v82, v82, v81
	v_rcp_f32_e32 v86, v83
	v_div_scale_f32 v98, vcc, v81, v82, v81
	v_fma_f32 v168, -v83, v86, 1.0
	v_fmac_f32_e32 v86, v168, v86
	v_mul_f32_e32 v168, v98, v86
	v_fma_f32 v169, -v83, v168, v98
	v_fmac_f32_e32 v168, v169, v86
	v_fma_f32 v83, -v83, v168, v98
	v_div_fmas_f32 v83, v83, v86, v168
	v_div_fixup_f32 v81, v83, v82, v81
	v_mul_f32_e32 v83, v87, v81
	v_mul_f32_e32 v81, v83, v83
	s_nop 1
	v_mov_b32_dpp v81, v81 quad_perm:[1,0,3,2] row_mask:0xf bank_mask:0xf
	v_bfe_u32 v86, v83, 16, 1
	v_fmac_f32_e32 v81, v83, v83
	s_nop 1
	v_add_f32_dpp v81, v81, v81 quad_perm:[2,3,0,1] row_mask:0xf bank_mask:0xf
	v_add3_u32 v83, v83, v86, s30
	global_store_short_d16_hi v[84:85], v83, off
	s_nop 1
	v_add_f32_dpp v81, v81, v81 row_half_mirror row_mask:0xf bank_mask:0xf
	s_nop 1
	v_add_f32_dpp v81, v81, v81 row_mirror row_mask:0xf bank_mask:0xf
	s_nop 1
	v_mov_b32_dpp v82, v81 row_bcast:15 row_mask:0xa bank_mask:0xf
	s_and_saveexec_b64 s[20:21], s[6:7]
	s_cbranch_execz .LBB0_3901
	v_add_f32_e32 v81, v81, v82
	ds_add_f32 v146, v81 offset:38444
.LBB0_3901:
	s_or_b64 exec, exec, s[20:21]
	v_or3_b32 v98, v167, v142, s39
	v_lshl_add_u64 v[84:85], v[98:99], 1, s[18:19]
	v_mov_b32_e32 v81, v215
	v_lshlrev_b32_e32 v81, 16, v81
	v_mul_f32_e32 v82, 0xbfb8aa3b, v81
	v_exp_f32_e32 v82, v82
	s_nop 0
	v_add_f32_e32 v82, 1.0, v82
	v_div_scale_f32 v83, s[20:21], v82, v82, v81
	v_rcp_f32_e32 v86, v83
	v_div_scale_f32 v87, vcc, v81, v82, v81
	v_fma_f32 v98, -v83, v86, 1.0
	v_fmac_f32_e32 v86, v98, v86
	v_mul_f32_e32 v98, v87, v86
	v_fma_f32 v168, -v83, v98, v87
	v_fmac_f32_e32 v98, v168, v86
	v_fma_f32 v83, -v83, v98, v87
	v_div_fmas_f32 v83, v83, v86, v98
	v_div_fixup_f32 v81, v83, v82, v81
	v_mul_f32_e32 v83, v88, v81
	v_mul_f32_e32 v81, v83, v83
	s_nop 1
	v_mov_b32_dpp v81, v81 quad_perm:[1,0,3,2] row_mask:0xf bank_mask:0xf
	v_bfe_u32 v86, v83, 16, 1
	v_fmac_f32_e32 v81, v83, v83
	s_nop 1
	v_add_f32_dpp v81, v81, v81 quad_perm:[2,3,0,1] row_mask:0xf bank_mask:0xf
	v_add3_u32 v83, v83, v86, s30
	global_store_short_d16_hi v[84:85], v83, off
	s_nop 1
	v_add_f32_dpp v81, v81, v81 row_half_mirror row_mask:0xf bank_mask:0xf
	s_nop 1
	v_add_f32_dpp v81, v81, v81 row_mirror row_mask:0xf bank_mask:0xf
	s_nop 1
	v_mov_b32_dpp v82, v81 row_bcast:15 row_mask:0xa bank_mask:0xf
	s_and_saveexec_b64 s[20:21], s[6:7]
	s_cbranch_execz .LBB0_3903
	v_add_f32_e32 v81, v81, v82
	ds_add_f32 v146, v81 offset:38464
.LBB0_3903:
	s_or_b64 exec, exec, s[20:21]
	v_or3_b32 v98, v167, v142, s40
	v_lshl_add_u64 v[84:85], v[98:99], 1, s[18:19]
	v_mov_b32_e32 v81, v216
	v_lshlrev_b32_e32 v81, 16, v81
	v_mul_f32_e32 v82, 0xbfb8aa3b, v81
	v_exp_f32_e32 v82, v82
	s_nop 0
	v_add_f32_e32 v82, 1.0, v82
	v_div_scale_f32 v83, s[20:21], v82, v82, v81
	v_rcp_f32_e32 v86, v83
	v_div_scale_f32 v87, vcc, v81, v82, v81
	v_fma_f32 v88, -v83, v86, 1.0
	v_fmac_f32_e32 v86, v88, v86
	v_mul_f32_e32 v88, v87, v86
	v_fma_f32 v98, -v83, v88, v87
	v_fmac_f32_e32 v88, v98, v86
	v_fma_f32 v83, -v83, v88, v87
	v_div_fmas_f32 v83, v83, v86, v88
	v_div_fixup_f32 v81, v83, v82, v81
	v_mul_f32_e32 v83, v89, v81
	v_mul_f32_e32 v81, v83, v83
	s_nop 1
	v_mov_b32_dpp v81, v81 quad_perm:[1,0,3,2] row_mask:0xf bank_mask:0xf
	v_bfe_u32 v86, v83, 16, 1
	v_fmac_f32_e32 v81, v83, v83
	s_nop 1
	v_add_f32_dpp v81, v81, v81 quad_perm:[2,3,0,1] row_mask:0xf bank_mask:0xf
	v_add3_u32 v83, v83, v86, s30
	global_store_short_d16_hi v[84:85], v83, off
	s_nop 1
	v_add_f32_dpp v81, v81, v81 row_half_mirror row_mask:0xf bank_mask:0xf
	s_nop 1
	v_add_f32_dpp v81, v81, v81 row_mirror row_mask:0xf bank_mask:0xf
	s_nop 1
	v_mov_b32_dpp v82, v81 row_bcast:15 row_mask:0xa bank_mask:0xf
	s_and_saveexec_b64 s[20:21], s[6:7]
	s_cbranch_execz .LBB0_3905
	v_add_f32_e32 v81, v81, v82
	ds_add_f32 v146, v81 offset:38468
; __device__ __forceinline__ float bf2f(bf16r h) { return __uint_as_float(((unsigned)h) << 16); }
; __device__ __forceinline__ float siluf(float x) { return x / (1.f + __expf(-x)); }
; __device__ __forceinline__ void phase_ssd_out(const Params& p, int layer, unsigned char* smem) {
;     ...
;       {
;         const int t2 = relaunder(tid);
;         const int lane = t2 & 63, hi = lane >> 5, cl = lane & 31, wm = t2 >> 7, wn = (t2 >> 6) & 1;
; #pragma unroll
;         for (int mt = 0; mt < 2; mt++)
; #pragma unroll
;           for (int i = 0; i < 16; i++) {
;             int row = wm * 64 + mt * 32 + (i & 3) + 8 * (i >> 2) + 4 * hi;
;             int col = wn * 32 + cl;
;             bf16r* ybb = yb + (size_t)c * 128 * 1024 + h * 64;
;             unsigned off = (unsigned)(row * 1024 + col);
;             float z = bf2f(ybb[off]);
;             float y = ay[mt][0][i] * siluf(z);
;             *(ybb + off) = f2bf(y);
;             float sq = y * y;
; #pragma unroll
;             for (int o = 16; o > 0; o >>= 1) sq += __shfl_xor(sq, o, 64);
;             if (cl == 0) atomicAdd(&sRow[row], sq);
;             if ((i & 3) == 3) __builtin_amdgcn_sched_barrier(0);
;           }
;       }
.LBB0_3905:
	s_or_b64 exec, exec, s[20:21]
	v_or3_b32 v98, v167, v142, s41
	v_lshl_add_u64 v[84:85], v[98:99], 1, s[18:19]
	v_mov_b32_e32 v81, v217
	v_lshlrev_b32_e32 v81, 16, v81
	v_mul_f32_e32 v82, 0xbfb8aa3b, v81
	v_exp_f32_e32 v82, v82
	s_nop 0
	v_add_f32_e32 v82, 1.0, v82
	v_div_scale_f32 v83, s[20:21], v82, v82, v81
	v_rcp_f32_e32 v86, v83
	v_div_scale_f32 v87, vcc, v81, v82, v81
	v_fma_f32 v88, -v83, v86, 1.0
	v_fmac_f32_e32 v86, v88, v86
	v_mul_f32_e32 v88, v87, v86
	v_fma_f32 v89, -v83, v88, v87
	v_fmac_f32_e32 v88, v89, v86
	v_fma_f32 v83, -v83, v88, v87
	v_div_fmas_f32 v83, v83, v86, v88
	v_div_fixup_f32 v81, v83, v82, v81
	v_mul_f32_e32 v83, v90, v81
	v_mul_f32_e32 v81, v83, v83
	s_nop 1
	v_mov_b32_dpp v81, v81 quad_perm:[1,0,3,2] row_mask:0xf bank_mask:0xf
	v_bfe_u32 v86, v83, 16, 1
	v_fmac_f32_e32 v81, v83, v83
	s_nop 1
	v_add_f32_dpp v81, v81, v81 quad_perm:[2,3,0,1] row_mask:0xf bank_mask:0xf
	v_add3_u32 v83, v83, v86, s30
	global_store_short_d16_hi v[84:85], v83, off
	s_nop 1
	v_add_f32_dpp v81, v81, v81 row_half_mirror row_mask:0xf bank_mask:0xf
	s_nop 1
	v_add_f32_dpp v81, v81, v81 row_mirror row_mask:0xf bank_mask:0xf
	s_nop 1
	v_mov_b32_dpp v82, v81 row_bcast:15 row_mask:0xa bank_mask:0xf
	s_and_saveexec_b64 s[20:21], s[6:7]
	s_cbranch_execz .LBB0_3907
	v_add_f32_e32 v81, v81, v82
	ds_add_f32 v146, v81 offset:38472
.LBB0_3907:
	s_or_b64 exec, exec, s[20:21]
	v_or3_b32 v98, v167, v142, s42
	v_lshl_add_u64 v[84:85], v[98:99], 1, s[18:19]
	v_mov_b32_e32 v81, v218
	v_lshlrev_b32_e32 v81, 16, v81
	v_mul_f32_e32 v82, 0xbfb8aa3b, v81
	v_exp_f32_e32 v82, v82
	s_nop 0
	v_add_f32_e32 v82, 1.0, v82
	v_div_scale_f32 v83, s[20:21], v82, v82, v81
	v_rcp_f32_e32 v86, v83
	v_div_scale_f32 v87, vcc, v81, v82, v81
	v_fma_f32 v88, -v83, v86, 1.0
	v_fmac_f32_e32 v86, v88, v86
	v_mul_f32_e32 v88, v87, v86
	v_fma_f32 v89, -v83, v88, v87
	v_fmac_f32_e32 v88, v89, v86
	v_fma_f32 v83, -v83, v88, v87
	v_div_fmas_f32 v83, v83, v86, v88
	v_div_fixup_f32 v81, v83, v82, v81
	v_mul_f32_e32 v83, v91, v81
	v_mul_f32_e32 v81, v83, v83
	s_nop 1
	v_mov_b32_dpp v81, v81 quad_perm:[1,0,3,2] row_mask:0xf bank_mask:0xf
	v_bfe_u32 v86, v83, 16, 1
	v_fmac_f32_e32 v81, v83, v83
	s_nop 1
	v_add_f32_dpp v81, v81, v81 quad_perm:[2,3,0,1] row_mask:0xf bank_mask:0xf
	v_add3_u32 v83, v83, v86, s30
	global_store_short_d16_hi v[84:85], v83, off
	s_nop 1
	v_add_f32_dpp v81, v81, v81 row_half_mirror row_mask:0xf bank_mask:0xf
	s_nop 1
	v_add_f32_dpp v81, v81, v81 row_mirror row_mask:0xf bank_mask:0xf
	s_nop 1
	v_mov_b32_dpp v82, v81 row_bcast:15 row_mask:0xa bank_mask:0xf
	s_and_saveexec_b64 s[20:21], s[6:7]
	s_cbranch_execz .LBB0_3909
	v_add_f32_e32 v81, v81, v82
	ds_add_f32 v146, v81 offset:38476
.LBB0_3909:
	s_or_b64 exec, exec, s[20:21]
	v_or3_b32 v98, v167, v142, s43
	v_lshl_add_u64 v[84:85], v[98:99], 1, s[18:19]
	v_mov_b32_e32 v81, v219
	v_lshlrev_b32_e32 v81, 16, v81
	v_mul_f32_e32 v82, 0xbfb8aa3b, v81
	v_exp_f32_e32 v82, v82
	s_nop 0
	v_add_f32_e32 v82, 1.0, v82
	v_div_scale_f32 v83, s[20:21], v82, v82, v81
	v_rcp_f32_e32 v86, v83
	v_div_scale_f32 v87, vcc, v81, v82, v81
	v_fma_f32 v88, -v83, v86, 1.0
	v_fmac_f32_e32 v86, v88, v86
	v_mul_f32_e32 v88, v87, v86
	v_fma_f32 v89, -v83, v88, v87
	v_fmac_f32_e32 v88, v89, v86
	v_fma_f32 v83, -v83, v88, v87
	v_div_fmas_f32 v83, v83, v86, v88
	v_div_fixup_f32 v81, v83, v82, v81
	v_mul_f32_e32 v83, v92, v81
	v_mul_f32_e32 v81, v83, v83
	s_nop 1
	v_mov_b32_dpp v81, v81 quad_perm:[1,0,3,2] row_mask:0xf bank_mask:0xf
	v_bfe_u32 v86, v83, 16, 1
	v_fmac_f32_e32 v81, v83, v83
	s_nop 1
	v_add_f32_dpp v81, v81, v81 quad_perm:[2,3,0,1] row_mask:0xf bank_mask:0xf
	v_add3_u32 v83, v83, v86, s30
	global_store_short_d16_hi v[84:85], v83, off
	s_nop 1
	v_add_f32_dpp v81, v81, v81 row_half_mirror row_mask:0xf bank_mask:0xf
	s_nop 1
	v_add_f32_dpp v81, v81, v81 row_mirror row_mask:0xf bank_mask:0xf
	s_nop 1
	v_mov_b32_dpp v82, v81 row_bcast:15 row_mask:0xa bank_mask:0xf
	s_and_saveexec_b64 s[20:21], s[6:7]
	s_cbranch_execz .LBB0_3911
	v_add_f32_e32 v81, v81, v82
	ds_add_f32 v146, v81 offset:38496
.LBB0_3911:
	s_or_b64 exec, exec, s[20:21]
	v_or3_b32 v98, v167, v142, s46
	v_lshl_add_u64 v[84:85], v[98:99], 1, s[18:19]
	v_mov_b32_e32 v81, v220
	v_lshlrev_b32_e32 v81, 16, v81
	v_mul_f32_e32 v82, 0xbfb8aa3b, v81
	v_exp_f32_e32 v82, v82
	s_nop 0
	v_add_f32_e32 v82, 1.0, v82
	v_div_scale_f32 v83, s[20:21], v82, v82, v81
	v_rcp_f32_e32 v86, v83
	v_div_scale_f32 v87, vcc, v81, v82, v81
	v_fma_f32 v88, -v83, v86, 1.0
	v_fmac_f32_e32 v86, v88, v86
	v_mul_f32_e32 v88, v87, v86
	v_fma_f32 v89, -v83, v88, v87
	v_fmac_f32_e32 v88, v89, v86
	v_fma_f32 v83, -v83, v88, v87
	v_div_fmas_f32 v83, v83, v86, v88
	v_div_fixup_f32 v81, v83, v82, v81
	v_mul_f32_e32 v83, v93, v81
	v_mul_f32_e32 v81, v83, v83
	s_nop 1
	v_mov_b32_dpp v81, v81 quad_perm:[1,0,3,2] row_mask:0xf bank_mask:0xf
	v_bfe_u32 v86, v83, 16, 1
	v_fmac_f32_e32 v81, v83, v83
	s_nop 1
	v_add_f32_dpp v81, v81, v81 quad_perm:[2,3,0,1] row_mask:0xf bank_mask:0xf
	v_add3_u32 v83, v83, v86, s30
	global_store_short_d16_hi v[84:85], v83, off
	s_nop 1
	v_add_f32_dpp v81, v81, v81 row_half_mirror row_mask:0xf bank_mask:0xf
	s_nop 1
	v_add_f32_dpp v81, v81, v81 row_mirror row_mask:0xf bank_mask:0xf
	s_nop 1
	v_mov_b32_dpp v82, v81 row_bcast:15 row_mask:0xa bank_mask:0xf
	s_and_saveexec_b64 s[20:21], s[6:7]
	s_cbranch_execz .LBB0_3913
	v_add_f32_e32 v81, v81, v82
	ds_add_f32 v146, v81 offset:38500
; __device__ __forceinline__ float bf2f(bf16r h) { return __uint_as_float(((unsigned)h) << 16); }
; __device__ __forceinline__ float siluf(float x) { return x / (1.f + __expf(-x)); }
; __device__ __forceinline__ void phase_ssd_out(const Params& p, int layer, unsigned char* smem) {
;     ...
;       {
;         const int t2 = relaunder(tid);
;         const int lane = t2 & 63, hi = lane >> 5, cl = lane & 31, wm = t2 >> 7, wn = (t2 >> 6) & 1;
; #pragma unroll
;         for (int mt = 0; mt < 2; mt++)
; #pragma unroll
;           for (int i = 0; i < 16; i++) {
;             int row = wm * 64 + mt * 32 + (i & 3) + 8 * (i >> 2) + 4 * hi;
;             int col = wn * 32 + cl;
;             bf16r* ybb = yb + (size_t)c * 128 * 1024 + h * 64;
;             unsigned off = (unsigned)(row * 1024 + col);
;             float z = bf2f(ybb[off]);
;             float y = ay[mt][0][i] * siluf(z);
;             *(ybb + off) = f2bf(y);
;             float sq = y * y;
; #pragma unroll
;             for (int o = 16; o > 0; o >>= 1) sq += __shfl_xor(sq, o, 64);
;             if (cl == 0) atomicAdd(&sRow[row], sq);
;             if ((i & 3) == 3) __builtin_amdgcn_sched_barrier(0);
;           }
;       }
.LBB0_3913:
	s_or_b64 exec, exec, s[20:21]
	v_or3_b32 v98, v167, v142, s47
	v_lshl_add_u64 v[84:85], v[98:99], 1, s[18:19]
	v_mov_b32_e32 v81, v221
	v_lshlrev_b32_e32 v81, 16, v81
	v_mul_f32_e32 v82, 0xbfb8aa3b, v81
	v_exp_f32_e32 v82, v82
	s_nop 0
	v_add_f32_e32 v82, 1.0, v82
	v_div_scale_f32 v83, s[20:21], v82, v82, v81
	v_rcp_f32_e32 v86, v83
	v_div_scale_f32 v87, vcc, v81, v82, v81
	v_fma_f32 v88, -v83, v86, 1.0
	v_fmac_f32_e32 v86, v88, v86
	v_mul_f32_e32 v88, v87, v86
	v_fma_f32 v89, -v83, v88, v87
	v_fmac_f32_e32 v88, v89, v86
	v_fma_f32 v83, -v83, v88, v87
	v_div_fmas_f32 v83, v83, v86, v88
	v_div_fixup_f32 v81, v83, v82, v81
	v_mul_f32_e32 v83, v94, v81
	v_mul_f32_e32 v81, v83, v83
	s_nop 1
	v_mov_b32_dpp v81, v81 quad_perm:[1,0,3,2] row_mask:0xf bank_mask:0xf
	v_bfe_u32 v86, v83, 16, 1
	v_fmac_f32_e32 v81, v83, v83
	s_nop 1
	v_add_f32_dpp v81, v81, v81 quad_perm:[2,3,0,1] row_mask:0xf bank_mask:0xf
	v_add3_u32 v83, v83, v86, s30
	global_store_short_d16_hi v[84:85], v83, off
	s_nop 1
	v_add_f32_dpp v81, v81, v81 row_half_mirror row_mask:0xf bank_mask:0xf
	s_nop 1
	v_add_f32_dpp v81, v81, v81 row_mirror row_mask:0xf bank_mask:0xf
	s_nop 1
	v_mov_b32_dpp v82, v81 row_bcast:15 row_mask:0xa bank_mask:0xf
	s_and_saveexec_b64 s[20:21], s[6:7]
	s_cbranch_execz .LBB0_3915
	v_add_f32_e32 v81, v81, v82
	ds_add_f32 v146, v81 offset:38504
.LBB0_3915:
	s_or_b64 exec, exec, s[20:21]
	v_or3_b32 v98, v167, v142, s48
	v_lshl_add_u64 v[84:85], v[98:99], 1, s[18:19]
	v_mov_b32_e32 v81, v222
	v_lshlrev_b32_e32 v81, 16, v81
	v_mul_f32_e32 v82, 0xbfb8aa3b, v81
	v_exp_f32_e32 v82, v82
	s_nop 0
	v_add_f32_e32 v82, 1.0, v82
	v_div_scale_f32 v83, s[20:21], v82, v82, v81
	v_rcp_f32_e32 v86, v83
	v_div_scale_f32 v87, vcc, v81, v82, v81
	v_fma_f32 v88, -v83, v86, 1.0
	v_fmac_f32_e32 v86, v88, v86
	v_mul_f32_e32 v88, v87, v86
	v_fma_f32 v89, -v83, v88, v87
	v_fmac_f32_e32 v88, v89, v86
	v_fma_f32 v83, -v83, v88, v87
	v_div_fmas_f32 v83, v83, v86, v88
	v_div_fixup_f32 v81, v83, v82, v81
	v_mul_f32_e32 v83, v95, v81
	v_mul_f32_e32 v81, v83, v83
	s_nop 1
	v_mov_b32_dpp v81, v81 quad_perm:[1,0,3,2] row_mask:0xf bank_mask:0xf
	v_bfe_u32 v86, v83, 16, 1
	v_fmac_f32_e32 v81, v83, v83
	s_nop 1
	v_add_f32_dpp v81, v81, v81 quad_perm:[2,3,0,1] row_mask:0xf bank_mask:0xf
	v_add3_u32 v83, v83, v86, s30
	global_store_short_d16_hi v[84:85], v83, off
	s_nop 1
	v_add_f32_dpp v81, v81, v81 row_half_mirror row_mask:0xf bank_mask:0xf
	s_nop 1
	v_add_f32_dpp v81, v81, v81 row_mirror row_mask:0xf bank_mask:0xf
	s_nop 1
	v_mov_b32_dpp v82, v81 row_bcast:15 row_mask:0xa bank_mask:0xf
	s_and_saveexec_b64 s[20:21], s[6:7]
	s_cbranch_execz .LBB0_3917
	v_add_f32_e32 v81, v81, v82
	ds_add_f32 v146, v81 offset:38508
.LBB0_3917:
	s_or_b64 exec, exec, s[20:21]
	v_or3_b32 v98, v167, v142, s49
	v_lshl_add_u64 v[82:83], v[98:99], 1, s[18:19]
	v_mov_b32_e32 v81, v223
	v_lshlrev_b32_e32 v81, 16, v81
	v_mul_f32_e32 v84, 0xbfb8aa3b, v81
	v_exp_f32_e32 v84, v84
	s_nop 0
	v_add_f32_e32 v84, 1.0, v84
	v_div_scale_f32 v85, s[20:21], v84, v84, v81
	v_rcp_f32_e32 v86, v85
	v_div_scale_f32 v87, vcc, v81, v84, v81
	v_fma_f32 v88, -v85, v86, 1.0
	v_fmac_f32_e32 v86, v88, v86
	v_mul_f32_e32 v88, v87, v86
	v_fma_f32 v89, -v85, v88, v87
	v_fmac_f32_e32 v88, v89, v86
	v_fma_f32 v85, -v85, v88, v87
	v_div_fmas_f32 v85, v85, v86, v88
	v_div_fixup_f32 v81, v85, v84, v81
	v_mul_f32_e32 v84, v64, v81
	v_mul_f32_e32 v64, v84, v84
	s_nop 1
	v_mov_b32_dpp v64, v64 quad_perm:[1,0,3,2] row_mask:0xf bank_mask:0xf
	v_bfe_u32 v85, v84, 16, 1
	v_fmac_f32_e32 v64, v84, v84
	s_nop 1
	v_add_f32_dpp v64, v64, v64 quad_perm:[2,3,0,1] row_mask:0xf bank_mask:0xf
	v_add3_u32 v84, v84, v85, s30
	global_store_short_d16_hi v[82:83], v84, off
	s_nop 1
	v_add_f32_dpp v64, v64, v64 row_half_mirror row_mask:0xf bank_mask:0xf
	s_nop 1
	v_add_f32_dpp v64, v64, v64 row_mirror row_mask:0xf bank_mask:0xf
	s_nop 1
	v_mov_b32_dpp v81, v64 row_bcast:15 row_mask:0xa bank_mask:0xf
	s_and_saveexec_b64 s[20:21], s[6:7]
	s_cbranch_execz .LBB0_3919
	v_add_f32_e32 v64, v64, v81
	ds_add_f32 v146, v64 offset:38528
.LBB0_3919:
	s_or_b64 exec, exec, s[20:21]
	v_or3_b32 v98, v167, v142, s50
	v_lshl_add_u64 v[82:83], v[98:99], 1, s[18:19]
	v_mov_b32_e32 v64, v224
	v_lshlrev_b32_e32 v64, 16, v64
	v_mul_f32_e32 v81, 0xbfb8aa3b, v64
	v_exp_f32_e32 v81, v81
	s_nop 0
	v_add_f32_e32 v81, 1.0, v81
	v_div_scale_f32 v84, s[20:21], v81, v81, v64
	v_rcp_f32_e32 v85, v84
	v_div_scale_f32 v86, vcc, v64, v81, v64
	v_fma_f32 v87, -v84, v85, 1.0
	v_fmac_f32_e32 v85, v87, v85
	v_mul_f32_e32 v87, v86, v85
	v_fma_f32 v88, -v84, v87, v86
	v_fmac_f32_e32 v87, v88, v85
	v_fma_f32 v84, -v84, v87, v86
	v_div_fmas_f32 v84, v84, v85, v87
	v_div_fixup_f32 v64, v84, v81, v64
	v_mul_f32_e32 v81, v65, v64
	v_mul_f32_e32 v64, v81, v81
	s_nop 1
	v_mov_b32_dpp v64, v64 quad_perm:[1,0,3,2] row_mask:0xf bank_mask:0xf
	v_bfe_u32 v84, v81, 16, 1
	v_fmac_f32_e32 v64, v81, v81
	s_nop 1
	v_add_f32_dpp v64, v64, v64 quad_perm:[2,3,0,1] row_mask:0xf bank_mask:0xf
	v_add3_u32 v81, v81, v84, s30
	global_store_short_d16_hi v[82:83], v81, off
	s_nop 1
	v_add_f32_dpp v64, v64, v64 row_half_mirror row_mask:0xf bank_mask:0xf
	s_nop 1
	v_add_f32_dpp v64, v64, v64 row_mirror row_mask:0xf bank_mask:0xf
	s_nop 1
	v_mov_b32_dpp v65, v64 row_bcast:15 row_mask:0xa bank_mask:0xf
	s_and_saveexec_b64 s[20:21], s[6:7]
	s_cbranch_execz .LBB0_3921
	v_add_f32_e32 v64, v64, v65
	ds_add_f32 v146, v64 offset:38532
; __device__ __forceinline__ float bf2f(bf16r h) { return __uint_as_float(((unsigned)h) << 16); }
; __device__ __forceinline__ float siluf(float x) { return x / (1.f + __expf(-x)); }
; __device__ __forceinline__ void phase_ssd_out(const Params& p, int layer, unsigned char* smem) {
;     ...
;       {
;         const int t2 = relaunder(tid);
;         const int lane = t2 & 63, hi = lane >> 5, cl = lane & 31, wm = t2 >> 7, wn = (t2 >> 6) & 1;
; #pragma unroll
;         for (int mt = 0; mt < 2; mt++)
; #pragma unroll
;           for (int i = 0; i < 16; i++) {
;             int row = wm * 64 + mt * 32 + (i & 3) + 8 * (i >> 2) + 4 * hi;
;             int col = wn * 32 + cl;
;             bf16r* ybb = yb + (size_t)c * 128 * 1024 + h * 64;
;             unsigned off = (unsigned)(row * 1024 + col);
;             float z = bf2f(ybb[off]);
;             float y = ay[mt][0][i] * siluf(z);
;             *(ybb + off) = f2bf(y);
;             float sq = y * y;
; #pragma unroll
;             for (int o = 16; o > 0; o >>= 1) sq += __shfl_xor(sq, o, 64);
;             if (cl == 0) atomicAdd(&sRow[row], sq);
;             if ((i & 3) == 3) __builtin_amdgcn_sched_barrier(0);
;           }
;       }
.LBB0_3921:
	s_or_b64 exec, exec, s[20:21]
	v_or3_b32 v98, v167, v142, s51
	v_lshl_add_u64 v[82:83], v[98:99], 1, s[18:19]
	v_mov_b32_e32 v64, v225
	v_lshlrev_b32_e32 v64, 16, v64
	v_mul_f32_e32 v65, 0xbfb8aa3b, v64
	v_exp_f32_e32 v65, v65
	s_nop 0
	v_add_f32_e32 v65, 1.0, v65
	v_div_scale_f32 v81, s[20:21], v65, v65, v64
	v_rcp_f32_e32 v84, v81
	v_div_scale_f32 v85, vcc, v64, v65, v64
	v_fma_f32 v86, -v81, v84, 1.0
	v_fmac_f32_e32 v84, v86, v84
	v_mul_f32_e32 v86, v85, v84
	v_fma_f32 v87, -v81, v86, v85
	v_fmac_f32_e32 v86, v87, v84
	v_fma_f32 v81, -v81, v86, v85
	v_div_fmas_f32 v81, v81, v84, v86
	v_div_fixup_f32 v64, v81, v65, v64
	v_mul_f32_e32 v66, v66, v64
	v_mul_f32_e32 v64, v66, v66
	s_nop 1
	v_mov_b32_dpp v64, v64 quad_perm:[1,0,3,2] row_mask:0xf bank_mask:0xf
	v_bfe_u32 v81, v66, 16, 1
	v_fmac_f32_e32 v64, v66, v66
	s_nop 1
	v_add_f32_dpp v64, v64, v64 quad_perm:[2,3,0,1] row_mask:0xf bank_mask:0xf
	v_add3_u32 v66, v66, v81, s30
	global_store_short_d16_hi v[82:83], v66, off
	s_nop 1
	v_add_f32_dpp v64, v64, v64 row_half_mirror row_mask:0xf bank_mask:0xf
	s_nop 1
	v_add_f32_dpp v64, v64, v64 row_mirror row_mask:0xf bank_mask:0xf
	s_nop 1
	v_mov_b32_dpp v65, v64 row_bcast:15 row_mask:0xa bank_mask:0xf
	s_and_saveexec_b64 s[20:21], s[6:7]
	s_cbranch_execz .LBB0_3923
	v_add_f32_e32 v64, v64, v65
	ds_add_f32 v146, v64 offset:38536
.LBB0_3923:
	s_or_b64 exec, exec, s[20:21]
	v_or3_b32 v98, v167, v142, s52
	v_lshl_add_u64 v[82:83], v[98:99], 1, s[18:19]
	v_mov_b32_e32 v64, v226
	v_lshlrev_b32_e32 v64, 16, v64
	v_mul_f32_e32 v65, 0xbfb8aa3b, v64
	v_exp_f32_e32 v65, v65
	s_nop 0
	v_add_f32_e32 v65, 1.0, v65
	v_div_scale_f32 v66, s[20:21], v65, v65, v64
	v_rcp_f32_e32 v81, v66
	v_div_scale_f32 v84, vcc, v64, v65, v64
	v_fma_f32 v85, -v66, v81, 1.0
	v_fmac_f32_e32 v81, v85, v81
	v_mul_f32_e32 v85, v84, v81
	v_fma_f32 v86, -v66, v85, v84
	v_fmac_f32_e32 v85, v86, v81
	v_fma_f32 v66, -v66, v85, v84
	v_div_fmas_f32 v66, v66, v81, v85
	v_div_fixup_f32 v64, v66, v65, v64
	v_mul_f32_e32 v66, v67, v64
	v_mul_f32_e32 v64, v66, v66
	s_nop 1
	v_mov_b32_dpp v64, v64 quad_perm:[1,0,3,2] row_mask:0xf bank_mask:0xf
	v_bfe_u32 v67, v66, 16, 1
	v_fmac_f32_e32 v64, v66, v66
	s_nop 1
	v_add_f32_dpp v64, v64, v64 quad_perm:[2,3,0,1] row_mask:0xf bank_mask:0xf
	v_add3_u32 v66, v66, v67, s30
	global_store_short_d16_hi v[82:83], v66, off
	s_nop 1
	v_add_f32_dpp v64, v64, v64 row_half_mirror row_mask:0xf bank_mask:0xf
	s_nop 1
	v_add_f32_dpp v64, v64, v64 row_mirror row_mask:0xf bank_mask:0xf
	s_nop 1
	v_mov_b32_dpp v65, v64 row_bcast:15 row_mask:0xa bank_mask:0xf
	s_and_saveexec_b64 s[20:21], s[6:7]
	s_cbranch_execz .LBB0_3925
	v_add_f32_e32 v64, v64, v65
	ds_add_f32 v146, v64 offset:38540
.LBB0_3925:
	s_or_b64 exec, exec, s[20:21]
	v_or3_b32 v98, v167, v142, s53
	v_lshl_add_u64 v[66:67], v[98:99], 1, s[18:19]
	v_mov_b32_e32 v64, v227
	v_lshlrev_b32_e32 v64, 16, v64
	v_mul_f32_e32 v65, 0xbfb8aa3b, v64
	v_exp_f32_e32 v65, v65
	s_nop 0
	v_add_f32_e32 v65, 1.0, v65
	v_div_scale_f32 v81, s[20:21], v65, v65, v64
	v_rcp_f32_e32 v82, v81
	v_div_scale_f32 v83, vcc, v64, v65, v64
	v_fma_f32 v84, -v81, v82, 1.0
	v_fmac_f32_e32 v82, v84, v82
	v_mul_f32_e32 v84, v83, v82
	v_fma_f32 v85, -v81, v84, v83
	v_fmac_f32_e32 v84, v85, v82
	v_fma_f32 v81, -v81, v84, v83
	v_div_fmas_f32 v81, v81, v82, v84
	v_div_fixup_f32 v64, v81, v65, v64
	v_mul_f32_e32 v68, v68, v64
	v_mul_f32_e32 v64, v68, v68
	s_nop 1
	v_mov_b32_dpp v64, v64 quad_perm:[1,0,3,2] row_mask:0xf bank_mask:0xf
	v_bfe_u32 v81, v68, 16, 1
	v_fmac_f32_e32 v64, v68, v68
	s_nop 1
	v_add_f32_dpp v64, v64, v64 quad_perm:[2,3,0,1] row_mask:0xf bank_mask:0xf
	v_add3_u32 v68, v68, v81, s30
	global_store_short_d16_hi v[66:67], v68, off
	s_nop 1
	v_add_f32_dpp v64, v64, v64 row_half_mirror row_mask:0xf bank_mask:0xf
	s_nop 1
	v_add_f32_dpp v64, v64, v64 row_mirror row_mask:0xf bank_mask:0xf
	s_nop 1
	v_mov_b32_dpp v65, v64 row_bcast:15 row_mask:0xa bank_mask:0xf
	s_and_saveexec_b64 s[20:21], s[6:7]
	s_cbranch_execz .LBB0_3927
	v_add_f32_e32 v64, v64, v65
	ds_add_f32 v146, v64 offset:38560
.LBB0_3927:
	s_or_b64 exec, exec, s[20:21]
	v_or3_b32 v98, v167, v142, s54
	v_lshl_add_u64 v[66:67], v[98:99], 1, s[18:19]
	v_mov_b32_e32 v64, v228
	v_lshlrev_b32_e32 v64, 16, v64
	v_mul_f32_e32 v65, 0xbfb8aa3b, v64
	v_exp_f32_e32 v65, v65
	s_nop 0
	v_add_f32_e32 v65, 1.0, v65
	v_div_scale_f32 v68, s[20:21], v65, v65, v64
	v_rcp_f32_e32 v81, v68
	v_div_scale_f32 v82, vcc, v64, v65, v64
	v_fma_f32 v83, -v68, v81, 1.0
	v_fmac_f32_e32 v81, v83, v81
	v_mul_f32_e32 v83, v82, v81
	v_fma_f32 v84, -v68, v83, v82
	v_fmac_f32_e32 v83, v84, v81
	v_fma_f32 v68, -v68, v83, v82
	v_div_fmas_f32 v68, v68, v81, v83
	v_div_fixup_f32 v64, v68, v65, v64
	v_mul_f32_e32 v68, v69, v64
	v_mul_f32_e32 v64, v68, v68
	s_nop 1
	v_mov_b32_dpp v64, v64 quad_perm:[1,0,3,2] row_mask:0xf bank_mask:0xf
	v_bfe_u32 v69, v68, 16, 1
	v_fmac_f32_e32 v64, v68, v68
	s_nop 1
	v_add_f32_dpp v64, v64, v64 quad_perm:[2,3,0,1] row_mask:0xf bank_mask:0xf
	v_add3_u32 v68, v68, v69, s30
	global_store_short_d16_hi v[66:67], v68, off
	s_nop 1
	v_add_f32_dpp v64, v64, v64 row_half_mirror row_mask:0xf bank_mask:0xf
	s_nop 1
	v_add_f32_dpp v64, v64, v64 row_mirror row_mask:0xf bank_mask:0xf
	s_nop 1
	v_mov_b32_dpp v65, v64 row_bcast:15 row_mask:0xa bank_mask:0xf
	s_and_saveexec_b64 s[20:21], s[6:7]
	s_cbranch_execz .LBB0_3929
	v_add_f32_e32 v64, v64, v65
	ds_add_f32 v146, v64 offset:38564
; __device__ __forceinline__ float bf2f(bf16r h) { return __uint_as_float(((unsigned)h) << 16); }
; __device__ __forceinline__ float siluf(float x) { return x / (1.f + __expf(-x)); }
; __device__ __forceinline__ void phase_ssd_out(const Params& p, int layer, unsigned char* smem) {
;     ...
;       {
;         const int t2 = relaunder(tid);
;         const int lane = t2 & 63, hi = lane >> 5, cl = lane & 31, wm = t2 >> 7, wn = (t2 >> 6) & 1;
; #pragma unroll
;         for (int mt = 0; mt < 2; mt++)
; #pragma unroll
;           for (int i = 0; i < 16; i++) {
;             int row = wm * 64 + mt * 32 + (i & 3) + 8 * (i >> 2) + 4 * hi;
;             int col = wn * 32 + cl;
;             bf16r* ybb = yb + (size_t)c * 128 * 1024 + h * 64;
;             unsigned off = (unsigned)(row * 1024 + col);
;             float z = bf2f(ybb[off]);
;             float y = ay[mt][0][i] * siluf(z);
;             *(ybb + off) = f2bf(y);
;             float sq = y * y;
; #pragma unroll
;             for (int o = 16; o > 0; o >>= 1) sq += __shfl_xor(sq, o, 64);
;             if (cl == 0) atomicAdd(&sRow[row], sq);
;             if ((i & 3) == 3) __builtin_amdgcn_sched_barrier(0);
;           }
;       }
.LBB0_3929:
	s_or_b64 exec, exec, s[20:21]
	v_or3_b32 v98, v167, v142, s55
	v_lshl_add_u64 v[66:67], v[98:99], 1, s[18:19]
	v_mov_b32_e32 v64, v229
	v_lshlrev_b32_e32 v64, 16, v64
	v_mul_f32_e32 v65, 0xbfb8aa3b, v64
	v_exp_f32_e32 v65, v65
	s_nop 0
	v_add_f32_e32 v65, 1.0, v65
	v_div_scale_f32 v68, s[20:21], v65, v65, v64
	v_rcp_f32_e32 v69, v68
	v_div_scale_f32 v81, vcc, v64, v65, v64
	v_fma_f32 v82, -v68, v69, 1.0
	v_fmac_f32_e32 v69, v82, v69
	v_mul_f32_e32 v82, v81, v69
	v_fma_f32 v83, -v68, v82, v81
	v_fmac_f32_e32 v82, v83, v69
	v_fma_f32 v68, -v68, v82, v81
	v_div_fmas_f32 v68, v68, v69, v82
	v_div_fixup_f32 v64, v68, v65, v64
	v_mul_f32_e32 v68, v70, v64
	v_mul_f32_e32 v64, v68, v68
	s_nop 1
	v_mov_b32_dpp v64, v64 quad_perm:[1,0,3,2] row_mask:0xf bank_mask:0xf
	v_bfe_u32 v69, v68, 16, 1
	v_fmac_f32_e32 v64, v68, v68
	s_nop 1
	v_add_f32_dpp v64, v64, v64 quad_perm:[2,3,0,1] row_mask:0xf bank_mask:0xf
	v_add3_u32 v68, v68, v69, s30
	global_store_short_d16_hi v[66:67], v68, off
	s_nop 1
	v_add_f32_dpp v64, v64, v64 row_half_mirror row_mask:0xf bank_mask:0xf
	s_nop 1
	v_add_f32_dpp v64, v64, v64 row_mirror row_mask:0xf bank_mask:0xf
	s_nop 1
	v_mov_b32_dpp v65, v64 row_bcast:15 row_mask:0xa bank_mask:0xf
	s_and_saveexec_b64 s[20:21], s[6:7]
	s_cbranch_execz .LBB0_3931
	v_add_f32_e32 v64, v64, v65
	ds_add_f32 v146, v64 offset:38568
.LBB0_3931:
	s_or_b64 exec, exec, s[20:21]
	v_or3_b32 v98, v167, v142, s56
	v_lshl_add_u64 v[66:67], v[98:99], 1, s[18:19]
	v_mov_b32_e32 v64, v231
	v_lshlrev_b32_e32 v64, 16, v64
	v_mul_f32_e32 v65, 0xbfb8aa3b, v64
	v_exp_f32_e32 v65, v65
	s_nop 0
	v_add_f32_e32 v65, 1.0, v65
	v_div_scale_f32 v68, s[20:21], v65, v65, v64
	v_rcp_f32_e32 v69, v68
	v_div_scale_f32 v70, vcc, v64, v65, v64
	v_fma_f32 v81, -v68, v69, 1.0
	v_fmac_f32_e32 v69, v81, v69
	v_mul_f32_e32 v81, v70, v69
	v_fma_f32 v82, -v68, v81, v70
	v_fmac_f32_e32 v81, v82, v69
	v_fma_f32 v68, -v68, v81, v70
	v_div_fmas_f32 v68, v68, v69, v81
	v_div_fixup_f32 v64, v68, v65, v64
	v_mul_f32_e32 v68, v71, v64
	v_mul_f32_e32 v64, v68, v68
	s_nop 1
	v_mov_b32_dpp v64, v64 quad_perm:[1,0,3,2] row_mask:0xf bank_mask:0xf
	v_bfe_u32 v69, v68, 16, 1
	v_fmac_f32_e32 v64, v68, v68
	s_nop 1
	v_add_f32_dpp v64, v64, v64 quad_perm:[2,3,0,1] row_mask:0xf bank_mask:0xf
	v_add3_u32 v68, v68, v69, s30
	global_store_short_d16_hi v[66:67], v68, off
	s_nop 1
	v_add_f32_dpp v64, v64, v64 row_half_mirror row_mask:0xf bank_mask:0xf
	s_nop 1
	v_add_f32_dpp v64, v64, v64 row_mirror row_mask:0xf bank_mask:0xf
	s_nop 1
	v_mov_b32_dpp v65, v64 row_bcast:15 row_mask:0xa bank_mask:0xf
	s_and_saveexec_b64 s[20:21], s[6:7]
	s_cbranch_execz .LBB0_3933
	v_add_f32_e32 v64, v64, v65
	ds_add_f32 v146, v64 offset:38572
.LBB0_3933:
	s_or_b64 exec, exec, s[20:21]
	v_or3_b32 v98, v167, v142, s57
	v_lshl_add_u64 v[66:67], v[98:99], 1, s[18:19]
	v_mov_b32_e32 v64, v232
	v_lshlrev_b32_e32 v64, 16, v64
	v_mul_f32_e32 v65, 0xbfb8aa3b, v64
	v_exp_f32_e32 v65, v65
	s_nop 0
	v_add_f32_e32 v65, 1.0, v65
	v_div_scale_f32 v68, s[20:21], v65, v65, v64
	v_rcp_f32_e32 v69, v68
	v_div_scale_f32 v70, vcc, v64, v65, v64
	v_fma_f32 v71, -v68, v69, 1.0
	v_fmac_f32_e32 v69, v71, v69
	v_mul_f32_e32 v71, v70, v69
	v_fma_f32 v81, -v68, v71, v70
	v_fmac_f32_e32 v71, v81, v69
	v_fma_f32 v68, -v68, v71, v70
	v_div_fmas_f32 v68, v68, v69, v71
	v_div_fixup_f32 v64, v68, v65, v64
	v_mul_f32_e32 v68, v72, v64
	v_mul_f32_e32 v64, v68, v68
	s_nop 1
	v_mov_b32_dpp v64, v64 quad_perm:[1,0,3,2] row_mask:0xf bank_mask:0xf
	v_bfe_u32 v69, v68, 16, 1
	v_fmac_f32_e32 v64, v68, v68
	s_nop 1
	v_add_f32_dpp v64, v64, v64 quad_perm:[2,3,0,1] row_mask:0xf bank_mask:0xf
	v_add3_u32 v68, v68, v69, s30
	global_store_short_d16_hi v[66:67], v68, off
	s_nop 1
	v_add_f32_dpp v64, v64, v64 row_half_mirror row_mask:0xf bank_mask:0xf
	s_nop 1
	v_add_f32_dpp v64, v64, v64 row_mirror row_mask:0xf bank_mask:0xf
	s_nop 1
	v_mov_b32_dpp v65, v64 row_bcast:15 row_mask:0xa bank_mask:0xf
	s_and_saveexec_b64 s[20:21], s[6:7]
	s_cbranch_execz .LBB0_3935
	v_add_f32_e32 v64, v64, v65
	ds_add_f32 v146, v64 offset:38592
.LBB0_3935:
	s_or_b64 exec, exec, s[20:21]
	v_or3_b32 v98, v167, v142, s60
	v_lshl_add_u64 v[66:67], v[98:99], 1, s[18:19]
	v_mov_b32_e32 v64, v233
	v_lshlrev_b32_e32 v64, 16, v64
	v_mul_f32_e32 v65, 0xbfb8aa3b, v64
	v_exp_f32_e32 v65, v65
	s_nop 0
	v_add_f32_e32 v65, 1.0, v65
	v_div_scale_f32 v68, s[20:21], v65, v65, v64
	v_rcp_f32_e32 v69, v68
	v_div_scale_f32 v70, vcc, v64, v65, v64
	v_fma_f32 v71, -v68, v69, 1.0
	v_fmac_f32_e32 v69, v71, v69
	v_mul_f32_e32 v71, v70, v69
	v_fma_f32 v72, -v68, v71, v70
	v_fmac_f32_e32 v71, v72, v69
	v_fma_f32 v68, -v68, v71, v70
	v_div_fmas_f32 v68, v68, v69, v71
	v_div_fixup_f32 v64, v68, v65, v64
	v_mul_f32_e32 v68, v73, v64
	v_mul_f32_e32 v64, v68, v68
	s_nop 1
	v_mov_b32_dpp v64, v64 quad_perm:[1,0,3,2] row_mask:0xf bank_mask:0xf
	v_bfe_u32 v69, v68, 16, 1
	v_fmac_f32_e32 v64, v68, v68
	s_nop 1
	v_add_f32_dpp v64, v64, v64 quad_perm:[2,3,0,1] row_mask:0xf bank_mask:0xf
	v_add3_u32 v68, v68, v69, s30
	global_store_short_d16_hi v[66:67], v68, off
	s_nop 1
	v_add_f32_dpp v64, v64, v64 row_half_mirror row_mask:0xf bank_mask:0xf
	s_nop 1
	v_add_f32_dpp v64, v64, v64 row_mirror row_mask:0xf bank_mask:0xf
	s_nop 1
	v_mov_b32_dpp v65, v64 row_bcast:15 row_mask:0xa bank_mask:0xf
	s_and_saveexec_b64 s[20:21], s[6:7]
	s_cbranch_execz .LBB0_3937
	v_add_f32_e32 v64, v64, v65
	ds_add_f32 v146, v64 offset:38596
; __device__ __forceinline__ float bf2f(bf16r h) { return __uint_as_float(((unsigned)h) << 16); }
; __device__ __forceinline__ float siluf(float x) { return x / (1.f + __expf(-x)); }
; __device__ __forceinline__ void phase_ssd_out(const Params& p, int layer, unsigned char* smem) {
;     ...
;       {
;         const int t2 = relaunder(tid);
;         const int lane = t2 & 63, hi = lane >> 5, cl = lane & 31, wm = t2 >> 7, wn = (t2 >> 6) & 1;
; #pragma unroll
;         for (int mt = 0; mt < 2; mt++)
; #pragma unroll
;           for (int i = 0; i < 16; i++) {
;             int row = wm * 64 + mt * 32 + (i & 3) + 8 * (i >> 2) + 4 * hi;
;             int col = wn * 32 + cl;
;             bf16r* ybb = yb + (size_t)c * 128 * 1024 + h * 64;
;             unsigned off = (unsigned)(row * 1024 + col);
;             float z = bf2f(ybb[off]);
;             float y = ay[mt][0][i] * siluf(z);
;             *(ybb + off) = f2bf(y);
;             float sq = y * y;
; #pragma unroll
;             for (int o = 16; o > 0; o >>= 1) sq += __shfl_xor(sq, o, 64);
;             if (cl == 0) atomicAdd(&sRow[row], sq);
;             if ((i & 3) == 3) __builtin_amdgcn_sched_barrier(0);
;           }
;       }
.LBB0_3937:
	s_or_b64 exec, exec, s[20:21]
	v_or3_b32 v98, v167, v142, s61
	v_lshl_add_u64 v[66:67], v[98:99], 1, s[18:19]
	v_mov_b32_e32 v64, v234
	v_lshlrev_b32_e32 v64, 16, v64
	v_mul_f32_e32 v65, 0xbfb8aa3b, v64
	v_exp_f32_e32 v65, v65
	s_nop 0
	v_add_f32_e32 v65, 1.0, v65
	v_div_scale_f32 v68, s[20:21], v65, v65, v64
	v_rcp_f32_e32 v69, v68
	v_div_scale_f32 v70, vcc, v64, v65, v64
	v_fma_f32 v71, -v68, v69, 1.0
	v_fmac_f32_e32 v69, v71, v69
	v_mul_f32_e32 v71, v70, v69
	v_fma_f32 v72, -v68, v71, v70
	v_fmac_f32_e32 v71, v72, v69
	v_fma_f32 v68, -v68, v71, v70
	v_div_fmas_f32 v68, v68, v69, v71
	v_div_fixup_f32 v64, v68, v65, v64
	v_mul_f32_e32 v68, v74, v64
	v_mul_f32_e32 v64, v68, v68
	s_nop 1
	v_mov_b32_dpp v64, v64 quad_perm:[1,0,3,2] row_mask:0xf bank_mask:0xf
	v_bfe_u32 v69, v68, 16, 1
	v_fmac_f32_e32 v64, v68, v68
	s_nop 1
	v_add_f32_dpp v64, v64, v64 quad_perm:[2,3,0,1] row_mask:0xf bank_mask:0xf
	v_add3_u32 v68, v68, v69, s30
	global_store_short_d16_hi v[66:67], v68, off
	s_nop 1
	v_add_f32_dpp v64, v64, v64 row_half_mirror row_mask:0xf bank_mask:0xf
	s_nop 1
	v_add_f32_dpp v64, v64, v64 row_mirror row_mask:0xf bank_mask:0xf
	s_nop 1
	v_mov_b32_dpp v65, v64 row_bcast:15 row_mask:0xa bank_mask:0xf
	s_and_saveexec_b64 s[20:21], s[6:7]
	s_cbranch_execz .LBB0_3939
	v_add_f32_e32 v64, v64, v65
	ds_add_f32 v146, v64 offset:38600
.LBB0_3939:
	s_or_b64 exec, exec, s[20:21]
	v_or3_b32 v98, v167, v142, s62
	v_lshl_add_u64 v[66:67], v[98:99], 1, s[18:19]
	v_mov_b32_e32 v64, v235
	v_lshlrev_b32_e32 v64, 16, v64
	v_mul_f32_e32 v65, 0xbfb8aa3b, v64
	v_exp_f32_e32 v65, v65
	s_nop 0
	v_add_f32_e32 v65, 1.0, v65
	v_div_scale_f32 v68, s[20:21], v65, v65, v64
	v_rcp_f32_e32 v69, v68
	v_div_scale_f32 v70, vcc, v64, v65, v64
	v_fma_f32 v71, -v68, v69, 1.0
	v_fmac_f32_e32 v69, v71, v69
	v_mul_f32_e32 v71, v70, v69
	v_fma_f32 v72, -v68, v71, v70
	v_fmac_f32_e32 v71, v72, v69
	v_fma_f32 v68, -v68, v71, v70
	v_div_fmas_f32 v68, v68, v69, v71
	v_div_fixup_f32 v64, v68, v65, v64
	v_mul_f32_e32 v68, v75, v64
	v_mul_f32_e32 v64, v68, v68
	s_nop 1
	v_mov_b32_dpp v64, v64 quad_perm:[1,0,3,2] row_mask:0xf bank_mask:0xf
	v_bfe_u32 v69, v68, 16, 1
	v_fmac_f32_e32 v64, v68, v68
	s_nop 1
	v_add_f32_dpp v64, v64, v64 quad_perm:[2,3,0,1] row_mask:0xf bank_mask:0xf
	v_add3_u32 v68, v68, v69, s30
	global_store_short_d16_hi v[66:67], v68, off
	s_nop 1
	v_add_f32_dpp v64, v64, v64 row_half_mirror row_mask:0xf bank_mask:0xf
	s_nop 1
	v_add_f32_dpp v64, v64, v64 row_mirror row_mask:0xf bank_mask:0xf
	s_nop 1
	v_mov_b32_dpp v65, v64 row_bcast:15 row_mask:0xa bank_mask:0xf
	s_and_saveexec_b64 s[20:21], s[6:7]
	s_cbranch_execz .LBB0_3941
	v_add_f32_e32 v64, v64, v65
	ds_add_f32 v146, v64 offset:38604
.LBB0_3941:
	s_or_b64 exec, exec, s[20:21]
	v_or3_b32 v98, v167, v142, s63
	v_lshl_add_u64 v[66:67], v[98:99], 1, s[18:19]
	v_mov_b32_e32 v64, v236
	v_lshlrev_b32_e32 v64, 16, v64
	v_mul_f32_e32 v65, 0xbfb8aa3b, v64
	v_exp_f32_e32 v65, v65
	s_nop 0
	v_add_f32_e32 v65, 1.0, v65
	v_div_scale_f32 v68, s[20:21], v65, v65, v64
	v_rcp_f32_e32 v69, v68
	v_div_scale_f32 v70, vcc, v64, v65, v64
	v_fma_f32 v71, -v68, v69, 1.0
	v_fmac_f32_e32 v69, v71, v69
	v_mul_f32_e32 v71, v70, v69
	v_fma_f32 v72, -v68, v71, v70
	v_fmac_f32_e32 v71, v72, v69
	v_fma_f32 v68, -v68, v71, v70
	v_div_fmas_f32 v68, v68, v69, v71
	v_div_fixup_f32 v64, v68, v65, v64
	v_mul_f32_e32 v68, v76, v64
	v_mul_f32_e32 v64, v68, v68
	s_nop 1
	v_mov_b32_dpp v64, v64 quad_perm:[1,0,3,2] row_mask:0xf bank_mask:0xf
	v_bfe_u32 v69, v68, 16, 1
	v_fmac_f32_e32 v64, v68, v68
	s_nop 1
	v_add_f32_dpp v64, v64, v64 quad_perm:[2,3,0,1] row_mask:0xf bank_mask:0xf
	v_add3_u32 v68, v68, v69, s30
	global_store_short_d16_hi v[66:67], v68, off
	s_nop 1
	v_add_f32_dpp v64, v64, v64 row_half_mirror row_mask:0xf bank_mask:0xf
	s_nop 1
	v_add_f32_dpp v64, v64, v64 row_mirror row_mask:0xf bank_mask:0xf
	s_nop 1
	v_mov_b32_dpp v65, v64 row_bcast:15 row_mask:0xa bank_mask:0xf
	s_and_saveexec_b64 s[20:21], s[6:7]
	s_cbranch_execz .LBB0_3943
	v_add_f32_e32 v64, v64, v65
	ds_add_f32 v146, v64 offset:38624
; __device__ __forceinline__ float bf2f(bf16r h) { return __uint_as_float(((unsigned)h) << 16); }
; __device__ __forceinline__ float siluf(float x) { return x / (1.f + __expf(-x)); }
; __device__ __forceinline__ void phase_ssd_out(const Params& p, int layer, unsigned char* smem) {
;     ...
;       {
;         const int t2 = relaunder(tid);
;         const int lane = t2 & 63, hi = lane >> 5, cl = lane & 31, wm = t2 >> 7, wn = (t2 >> 6) & 1;
; #pragma unroll
;         for (int mt = 0; mt < 2; mt++)
; #pragma unroll
;           for (int i = 0; i < 16; i++) {
;             int row = wm * 64 + mt * 32 + (i & 3) + 8 * (i >> 2) + 4 * hi;
;             int col = wn * 32 + cl;
;             bf16r* ybb = yb + (size_t)c * 128 * 1024 + h * 64;
;             unsigned off = (unsigned)(row * 1024 + col);
;             float z = bf2f(ybb[off]);
;             float y = ay[mt][0][i] * siluf(z);
;             *(ybb + off) = f2bf(y);
;             float sq = y * y;
; #pragma unroll
;             for (int o = 16; o > 0; o >>= 1) sq += __shfl_xor(sq, o, 64);
;             if (cl == 0) atomicAdd(&sRow[row], sq);
;             if ((i & 3) == 3) __builtin_amdgcn_sched_barrier(0);
;           }
;       }
.LBB0_3943:
	s_or_b64 exec, exec, s[20:21]
	v_or3_b32 v98, v167, v142, s64
	v_lshl_add_u64 v[66:67], v[98:99], 1, s[18:19]
	v_mov_b32_e32 v64, v237
	v_lshlrev_b32_e32 v64, 16, v64
	v_mul_f32_e32 v65, 0xbfb8aa3b, v64
	v_exp_f32_e32 v65, v65
	s_nop 0
	v_add_f32_e32 v65, 1.0, v65
	v_div_scale_f32 v68, s[20:21], v65, v65, v64
	v_rcp_f32_e32 v69, v68
	v_div_scale_f32 v70, vcc, v64, v65, v64
	v_fma_f32 v71, -v68, v69, 1.0
	v_fmac_f32_e32 v69, v71, v69
	v_mul_f32_e32 v71, v70, v69
	v_fma_f32 v72, -v68, v71, v70
	v_fmac_f32_e32 v71, v72, v69
	v_fma_f32 v68, -v68, v71, v70
	v_div_fmas_f32 v68, v68, v69, v71
	v_div_fixup_f32 v64, v68, v65, v64
	v_mul_f32_e32 v68, v77, v64
	v_mul_f32_e32 v64, v68, v68
	s_nop 1
	v_mov_b32_dpp v64, v64 quad_perm:[1,0,3,2] row_mask:0xf bank_mask:0xf
	v_bfe_u32 v69, v68, 16, 1
	v_fmac_f32_e32 v64, v68, v68
	s_nop 1
	v_add_f32_dpp v64, v64, v64 quad_perm:[2,3,0,1] row_mask:0xf bank_mask:0xf
	v_add3_u32 v68, v68, v69, s30
	global_store_short_d16_hi v[66:67], v68, off
	s_nop 1
	v_add_f32_dpp v64, v64, v64 row_half_mirror row_mask:0xf bank_mask:0xf
	s_nop 1
	v_add_f32_dpp v64, v64, v64 row_mirror row_mask:0xf bank_mask:0xf
	s_nop 1
	v_mov_b32_dpp v65, v64 row_bcast:15 row_mask:0xa bank_mask:0xf
	s_and_saveexec_b64 s[20:21], s[6:7]
	s_cbranch_execz .LBB0_3945
	v_add_f32_e32 v64, v64, v65
	ds_add_f32 v146, v64 offset:38628
.LBB0_3945:
	s_or_b64 exec, exec, s[20:21]
	v_or3_b32 v98, v167, v142, s65
	v_lshl_add_u64 v[66:67], v[98:99], 1, s[18:19]
	v_mov_b32_e32 v64, v238
	v_lshlrev_b32_e32 v64, 16, v64
	v_mul_f32_e32 v65, 0xbfb8aa3b, v64
	v_exp_f32_e32 v65, v65
	s_nop 0
	v_add_f32_e32 v65, 1.0, v65
	v_div_scale_f32 v68, s[20:21], v65, v65, v64
	v_rcp_f32_e32 v69, v68
	v_div_scale_f32 v70, vcc, v64, v65, v64
	v_fma_f32 v71, -v68, v69, 1.0
	v_fmac_f32_e32 v69, v71, v69
	v_mul_f32_e32 v71, v70, v69
	v_fma_f32 v72, -v68, v71, v70
	v_fmac_f32_e32 v71, v72, v69
	v_fma_f32 v68, -v68, v71, v70
	v_div_fmas_f32 v68, v68, v69, v71
	v_div_fixup_f32 v64, v68, v65, v64
	v_mul_f32_e32 v68, v78, v64
	v_mul_f32_e32 v64, v68, v68
	s_nop 1
	v_mov_b32_dpp v64, v64 quad_perm:[1,0,3,2] row_mask:0xf bank_mask:0xf
	v_bfe_u32 v69, v68, 16, 1
	v_fmac_f32_e32 v64, v68, v68
	s_nop 1
	v_add_f32_dpp v64, v64, v64 quad_perm:[2,3,0,1] row_mask:0xf bank_mask:0xf
	v_add3_u32 v68, v68, v69, s30
	global_store_short_d16_hi v[66:67], v68, off
	s_nop 1
	v_add_f32_dpp v64, v64, v64 row_half_mirror row_mask:0xf bank_mask:0xf
	s_nop 1
	v_add_f32_dpp v64, v64, v64 row_mirror row_mask:0xf bank_mask:0xf
	s_nop 1
	v_mov_b32_dpp v65, v64 row_bcast:15 row_mask:0xa bank_mask:0xf
	s_and_saveexec_b64 s[20:21], s[6:7]
	s_cbranch_execz .LBB0_3947
	v_add_f32_e32 v64, v64, v65
	ds_add_f32 v146, v64 offset:38632
.LBB0_3947:
	s_or_b64 exec, exec, s[20:21]
	v_or3_b32 v98, v167, v142, s66
	v_lshl_add_u64 v[66:67], v[98:99], 1, s[18:19]
	v_mov_b32_e32 v64, v239
	v_lshlrev_b32_e32 v64, 16, v64
	v_mul_f32_e32 v65, 0xbfb8aa3b, v64
	v_exp_f32_e32 v65, v65
	s_nop 0
	v_add_f32_e32 v65, 1.0, v65
	v_div_scale_f32 v68, s[18:19], v65, v65, v64
	v_rcp_f32_e32 v69, v68
	v_div_scale_f32 v70, vcc, v64, v65, v64
	v_fma_f32 v71, -v68, v69, 1.0
	v_fmac_f32_e32 v69, v71, v69
	v_mul_f32_e32 v71, v70, v69
	v_fma_f32 v72, -v68, v71, v70
	v_fmac_f32_e32 v71, v72, v69
	v_fma_f32 v68, -v68, v71, v70
	v_div_fmas_f32 v68, v68, v69, v71
	v_div_fixup_f32 v64, v68, v65, v64
	v_mul_f32_e32 v68, v79, v64
	v_mul_f32_e32 v64, v68, v68
	s_nop 1
	v_mov_b32_dpp v64, v64 quad_perm:[1,0,3,2] row_mask:0xf bank_mask:0xf
	v_bfe_u32 v69, v68, 16, 1
	v_fmac_f32_e32 v64, v68, v68
	s_nop 1
	v_add_f32_dpp v64, v64, v64 quad_perm:[2,3,0,1] row_mask:0xf bank_mask:0xf
	v_add3_u32 v68, v68, v69, s30
	global_store_short_d16_hi v[66:67], v68, off
	s_nop 1
	v_add_f32_dpp v64, v64, v64 row_half_mirror row_mask:0xf bank_mask:0xf
	s_nop 1
	v_add_f32_dpp v64, v64, v64 row_mirror row_mask:0xf bank_mask:0xf
	s_nop 1
	v_mov_b32_dpp v65, v64 row_bcast:15 row_mask:0xa bank_mask:0xf
	s_and_saveexec_b64 s[18:19], s[6:7]
	s_cbranch_execz .LBB0_3746
	v_add_f32_e32 v64, v64, v65
	ds_add_f32 v146, v64 offset:38636
	s_waitcnt lgkmcnt(0)
	s_branch .LBB0_3746

; __device__ __forceinline__ float bf2f(bf16r h) { return __uint_as_float(((unsigned)h) << 16); }
; __device__ __forceinline__ float softplusf(float x) { return fmaxf(x, 0.f) + __logf(1.f + __expf(-fabsf(x))); }
; __device__ __forceinline__ void phase_sb(const Params& p, unsigned char* smem) {
;     ...
;       __syncthreads();
;       if (*sFlag) break;
;       int s0 = kb * 64;
;       stage_copy<64>(tid, sKV, 136, sk + (size_t)s0 * 1024 + h * 128, 1024);
;       stage_copy<64>(tid, sKV + 64, 136, sk + (size_t)s0 * 1024 + h * 128 + 64, 1024);
;       __syncthreads();
;       const int t2 = relaunder(tid);
;       const int hi = (t2 >> 5) & 1, cl = t2 & 31, wm = t2 >> 7, wn = (t2 >> 6) & 1;
;       f32x16 az[1][1];
;       zero_acc(az);
;       mma<1, 1, 8>(tid, az, sQ + wm * 32 * 136, 136, sKV + wn * 32 * 136, 136);
;       float logsig[16];
;       unsigned mbits = 0;
; #pragma unroll
;       for (int i = 0; i < 16; i++) {
;         int row = wm * 32 + (i & 3) + 8 * (i >> 2) + 4 * hi;
;         int col = wn * 32 + cl;
;         int t = t0 + row, key = s0 + col;
;         bool m = (key < t) && (key >= NPADR);
;         float z = az[0][0][i] * scale;
;         float sp = softplusf(z);
;         float ln = m ? -sp : 0.f;
;         logsig[i] = z - sp;
;         if (m) mbits |= (1u << i);
;         bf16r hb = f2bf(ln);
;         sHi[row * 72 + col] = hb;
;         sLo[row * 72 + col] = f2bf(ln - bf2f(hb));
;         float rsum = ln;
; #pragma unroll
;         for (int o = 16; o > 0; o >>= 1) rsum += __shfl_xor(rsum, o, 64);
;         if (cl == 0) atomicAdd(&sBlk[row], rsum);
;         if ((i & 3) == 3) __builtin_amdgcn_sched_barrier(0);
;       }
.LBB0_4400:
	s_waitcnt lgkmcnt(0)
	s_barrier
	ds_read_b32 v1, v141
	s_waitcnt lgkmcnt(0)
	v_cmp_ne_u32_e32 vcc, 0, v1
	s_cbranch_vccnz .LBB0_4399
	s_lshl_b64 s[8:9], s[16:17], 11
	v_lshl_add_u64 v[6:7], v[108:109], 0, s[8:9]
	v_lshl_add_u64 v[10:11], v[80:81], 1, v[6:7]
	v_lshl_add_u64 v[14:15], v[84:85], 1, v[6:7]
	global_load_dwordx4 v[2:5], v[10:11], off
	global_load_dwordx4 v[6:9], v[14:15], off
	s_nop 0
	global_load_dwordx4 v[10:13], v[10:11], off offset:128
	s_nop 0
	global_load_dwordx4 v[48:51], v[14:15], off offset:128
	v_mov_b32_e32 v70, v89
	v_cmp_lt_i32_e32 vcc, v144, v143
	s_waitcnt vmcnt(3)
	ds_write_b128 v82, v[2:5] offset:17408
	s_waitcnt vmcnt(2)
	ds_write_b128 v86, v[6:9] offset:17408
	s_waitcnt vmcnt(1)
	ds_write_b128 v82, v[10:13] offset:17536
	s_waitcnt vmcnt(0)
	ds_write_b128 v86, v[48:51] offset:17536
	s_waitcnt lgkmcnt(0)
	s_barrier
	s_nop 0
	v_ashrrev_i32_e32 v1, 2, v70
	v_and_b32_e32 v2, 0xffffffe0, v1
	v_mad_u64_u32 v[68:69], s[8:9], v2, s2, v[88:89]
	ds_read_b128 v[4:7], v68
	v_bfe_u32 v1, v70, 6, 1
	v_mad_u32_u24 v3, v1, s60, v88
	ds_read_b128 v[8:11], v3 offset:17408
	ds_read_b128 v[12:15], v3 offset:17440
	ds_read_b128 v[64:67], v68 offset:32
	s_waitcnt lgkmcnt(2)
	v_mfma_f32_32x32x16_bf16 v[48:63], v[4:7], v[8:11], 0
	s_waitcnt lgkmcnt(0)
	v_mfma_f32_32x32x16_bf16 v[48:63], v[64:67], v[12:15], v[48:63]
	ds_read_b128 v[4:7], v68 offset:64
	ds_read_b128 v[8:11], v3 offset:17472
	ds_read_b128 v[12:15], v3 offset:17504
	ds_read_b128 v[64:67], v68 offset:96
	s_waitcnt lgkmcnt(2)
	v_mfma_f32_32x32x16_bf16 v[48:63], v[4:7], v[8:11], v[48:63]
	s_waitcnt lgkmcnt(0)
	v_mfma_f32_32x32x16_bf16 v[48:63], v[64:67], v[12:15], v[48:63]
	ds_read_b128 v[4:7], v68 offset:128
	ds_read_b128 v[8:11], v3 offset:17536
	ds_read_b128 v[12:15], v3 offset:17568
	ds_read_b128 v[64:67], v68 offset:160
	s_waitcnt lgkmcnt(2)
	v_mfma_f32_32x32x16_bf16 v[48:63], v[4:7], v[8:11], v[48:63]
	s_waitcnt lgkmcnt(0)
	v_mfma_f32_32x32x16_bf16 v[48:63], v[64:67], v[12:15], v[48:63]
	ds_read_b128 v[4:7], v68 offset:192
	ds_read_b128 v[8:11], v3 offset:17600
	ds_read_b128 v[12:15], v3 offset:17632
	ds_read_b128 v[64:67], v68 offset:224
	v_cndmask_b32_e32 v3, v142, v144, vcc
	s_waitcnt lgkmcnt(2)
	v_mfma_f32_32x32x16_bf16 v[48:63], v[4:7], v[8:11], v[48:63]
	v_lshlrev_b32_e32 v4, 2, v3
	v_lshrrev_b32_e32 v3, 3, v70
	v_and_or_b32 v11, v3, 4, v2
	v_and_b32_e32 v9, 31, v70
	v_lshlrev_b32_e32 v10, 5, v1
	v_or_b32_e32 v8, v10, v9
	v_add_u32_e32 v6, s20, v11
	s_waitcnt lgkmcnt(0)
	v_mfma_f32_32x32x16_bf16 v[48:63], v[64:67], v[12:15], v[48:63]
	s_nop 11
	v_mul_f32_e32 v12, 0x3db504f3, v48
	v_mul_f32_e64 v3, |v12|, s62
	v_exp_f32_e32 v5, v3
	v_add_u32_e32 v3, s16, v8
	v_cmp_lt_u32_e32 vcc, s61, v3
	v_cmp_lt_i32_e64 s[10:11], v3, v6
	v_add_f32_e32 v5, 1.0, v5
	v_cmp_gt_f32_e64 s[8:9], s63, v5
	v_max_f32_e32 v6, 0, v12
	s_and_b64 s[22:23], vcc, s[10:11]
	v_cndmask_b32_e64 v7, 0, 32, s[8:9]
	v_ldexp_f32 v5, v5, v7
	v_log_f32_e32 v5, v5
	v_cndmask_b32_e64 v7, 0, v154, s[8:9]
	v_mul_f32_e32 v13, 0x3f317217, v5
	v_fma_f32 v13, v5, s64, -v13
	v_fmac_f32_e32 v13, 0x3377d1cf, v5
	v_fmac_f32_e32 v13, 0x3f317217, v5
	v_cmp_lt_f32_e64 s[8:9], |v5|, s65
	s_nop 1
	v_cndmask_b32_e64 v5, v5, v13, s[8:9]
	v_sub_f32_e32 v5, v5, v7
	v_add_f32_e32 v13, v6, v5
	v_cndmask_b32_e64 v64, 0, -v13, s[22:23]
	s_nop 1
	v_add_f32_dpp v14, v64, v64 quad_perm:[1,0,3,2] row_mask:0xf bank_mask:0xf
	v_cmp_lt_i32_e64 s[8:9], v145, v143
	s_waitcnt lgkmcnt(0)
	v_cndmask_b32_e64 v5, v142, v145, s[8:9]
	v_lshlrev_b32_e32 v5, 2, v5
	s_nop 1
	v_add_f32_dpp v14, v14, v14 quad_perm:[2,3,0,1] row_mask:0xf bank_mask:0xf
	v_cmp_lt_i32_e64 s[8:9], v146, v143
	v_cndmask_b32_e64 v7, v142, v146, s[8:9]
	v_lshlrev_b32_e32 v6, 2, v7
	s_nop 1
	v_mov_b32_dpp v15, v14 row_half_mirror row_mask:0xf bank_mask:0xf
	v_cmp_lt_i32_e64 s[8:9], v147, v143
	s_nop 1
	v_cndmask_b32_e64 v48, v142, v147, s[8:9]
	v_lshlrev_b32_e32 v7, 2, v48
	v_mul_lo_u32 v48, v11, s33
	v_add_lshl_u32 v48, v48, v8, 1
	v_add_f32_e32 v8, v14, v15
	s_nop 1
	v_add_f32_dpp v14, v8, v8 row_mirror row_mask:0xf bank_mask:0xf
	v_cmp_lt_i32_e64 s[8:9], v148, v143
	v_bfe_u32 v15, v64, 16, 1
	v_add3_u32 v15, v64, v15, s66
	v_cndmask_b32_e64 v65, v142, v148, s[8:9]
	v_lshlrev_b32_e32 v8, 2, v65
	ds_write_b16_d16_hi v48, v15 offset:35840
	v_and_b32_e32 v66, 0xffff0000, v15
	s_nop 1
	v_mov_b32_dpp v15, v14 row_bcast:15 row_mask:0xa bank_mask:0xf
	v_sub_f32_e32 v64, v64, v66
	v_bfe_u32 v65, v64, 16, 1
	v_cmp_eq_u32_e64 s[8:9], 16, v9
	v_add3_u32 v64, v64, v65, s66
	ds_write_b16_d16_hi v48, v64 offset:45056
	s_and_saveexec_b64 s[10:11], s[8:9]
	s_cbranch_execz .LBB0_4403
	v_lshl_add_u32 v64, v11, 2, v155
	v_add_f32_e32 v14, v14, v15
	ds_add_f32 v64, v14
.LBB0_4403:
	s_or_b64 exec, exec, s[10:11]
	v_mul_f32_e32 v14, 0x3db504f3, v49
	v_mul_f32_e64 v15, |v14|, s62
	v_exp_f32_e32 v49, v15
	v_or_b32_e32 v15, 1, v11
	v_max_f32_e32 v65, 0, v14
	v_add_f32_e32 v49, 1.0, v49
	v_cmp_gt_f32_e64 s[10:11], s63, v49
	s_nop 1
	v_cndmask_b32_e64 v64, 0, 32, s[10:11]
	v_ldexp_f32 v49, v49, v64
	v_log_f32_e32 v49, v49
	v_add_u32_e32 v64, s20, v15
	v_cmp_lt_i32_e64 s[12:13], v3, v64
	s_and_b64 s[24:25], vcc, s[12:13]
	v_mul_f32_e32 v64, 0x3f317217, v49
	v_fma_f32 v64, v49, s64, -v64
	v_fmac_f32_e32 v64, 0x3377d1cf, v49
	v_fmac_f32_e32 v64, 0x3f317217, v49
	v_cmp_lt_f32_e64 s[14:15], |v49|, s65
	s_nop 1
	v_cndmask_b32_e64 v49, v49, v64, s[14:15]
	v_cndmask_b32_e64 v64, 0, v154, s[10:11]
	v_sub_f32_e32 v49, v49, v64
	v_add_f32_e32 v64, v65, v49
	v_cndmask_b32_e64 v66, 0, -v64, s[24:25]
	s_nop 1
	v_add_f32_dpp v49, v66, v66 quad_perm:[1,0,3,2] row_mask:0xf bank_mask:0xf
	v_bfe_u32 v67, v66, 16, 1
	v_add3_u32 v67, v66, v67, s66
	ds_write_b16_d16_hi v48, v67 offset:35984
	v_and_b32_e32 v67, 0xffff0000, v67
	s_nop 1
	v_add_f32_dpp v49, v49, v49 quad_perm:[2,3,0,1] row_mask:0xf bank_mask:0xf
	v_sub_f32_e32 v66, v66, v67
	v_bfe_u32 v67, v66, 16, 1
	v_add3_u32 v66, v66, v67, s66
	ds_write_b16_d16_hi v48, v66 offset:45200
	s_nop 1
	v_add_f32_dpp v49, v49, v49 row_half_mirror row_mask:0xf bank_mask:0xf
	s_nop 1
	v_add_f32_dpp v49, v49, v49 row_mirror row_mask:0xf bank_mask:0xf
	s_nop 1
	v_mov_b32_dpp v65, v49 row_bcast:15 row_mask:0xa bank_mask:0xf
	s_and_saveexec_b64 s[10:11], s[8:9]
	s_cbranch_execz .LBB0_4405
	v_lshl_add_u32 v66, v15, 2, v155
	v_add_f32_e32 v49, v49, v65
	ds_add_f32 v66, v49
; __device__ __forceinline__ float bf2f(bf16r h) { return __uint_as_float(((unsigned)h) << 16); }
; __device__ __forceinline__ float softplusf(float x) { return fmaxf(x, 0.f) + __logf(1.f + __expf(-fabsf(x))); }
; __device__ __forceinline__ void phase_sb(const Params& p, unsigned char* smem) {
;     ...
;       for (int i = 0; i < 16; i++) {
;         int row = wm * 32 + (i & 3) + 8 * (i >> 2) + 4 * hi;
;         int col = wn * 32 + cl;
;         int t = t0 + row, key = s0 + col;
;         bool m = (key < t) && (key >= NPADR);
;         float z = az[0][0][i] * scale;
;         float sp = softplusf(z);
;         float ln = m ? -sp : 0.f;
;         logsig[i] = z - sp;
;         if (m) mbits |= (1u << i);
;         bf16r hb = f2bf(ln);
;         sHi[row * 72 + col] = hb;
;         sLo[row * 72 + col] = f2bf(ln - bf2f(hb));
;         float rsum = ln;
; #pragma unroll
;         for (int o = 16; o > 0; o >>= 1) rsum += __shfl_xor(rsum, o, 64);
;         if (cl == 0) atomicAdd(&sBlk[row], rsum);
;         if ((i & 3) == 3) __builtin_amdgcn_sched_barrier(0);
;       }
.LBB0_4405:
	s_or_b64 exec, exec, s[10:11]
	v_mul_f32_e32 v65, 0x3db504f3, v50
	v_mul_f32_e64 v49, |v65|, s62
	v_exp_f32_e32 v49, v49
	v_or_b32_e32 v66, 2, v11
	v_max_f32_e32 v67, 0, v65
	v_add_f32_e32 v49, 1.0, v49
	v_cmp_gt_f32_e64 s[10:11], s63, v49
	s_nop 1
	v_cndmask_b32_e64 v50, 0, 32, s[10:11]
	v_ldexp_f32 v49, v49, v50
	v_log_f32_e32 v49, v49
	v_add_u32_e32 v50, s20, v66
	v_cmp_lt_i32_e64 s[12:13], v3, v50
	s_and_b64 s[26:27], vcc, s[12:13]
	v_mul_f32_e32 v50, 0x3f317217, v49
	v_fma_f32 v50, v49, s64, -v50
	v_fmac_f32_e32 v50, 0x3377d1cf, v49
	v_fmac_f32_e32 v50, 0x3f317217, v49
	v_cmp_lt_f32_e64 s[14:15], |v49|, s65
	s_nop 1
	v_cndmask_b32_e64 v49, v49, v50, s[14:15]
	v_cndmask_b32_e64 v50, 0, v154, s[10:11]
	v_sub_f32_e32 v49, v49, v50
	v_add_f32_e32 v67, v67, v49
	v_cndmask_b32_e64 v68, 0, -v67, s[26:27]
	s_nop 1
	v_add_f32_dpp v49, v68, v68 quad_perm:[1,0,3,2] row_mask:0xf bank_mask:0xf
	v_bfe_u32 v69, v68, 16, 1
	v_add3_u32 v69, v68, v69, s66
	ds_write_b16_d16_hi v48, v69 offset:36128
	v_and_b32_e32 v69, 0xffff0000, v69
	s_nop 1
	v_add_f32_dpp v49, v49, v49 quad_perm:[2,3,0,1] row_mask:0xf bank_mask:0xf
	v_sub_f32_e32 v68, v68, v69
	v_bfe_u32 v69, v68, 16, 1
	v_add3_u32 v68, v68, v69, s66
	ds_write_b16_d16_hi v48, v68 offset:45344
	s_nop 1
	v_add_f32_dpp v49, v49, v49 row_half_mirror row_mask:0xf bank_mask:0xf
	s_nop 1
	v_add_f32_dpp v49, v49, v49 row_mirror row_mask:0xf bank_mask:0xf
	s_nop 1
	v_mov_b32_dpp v50, v49 row_bcast:15 row_mask:0xa bank_mask:0xf
	s_and_saveexec_b64 s[10:11], s[8:9]
	s_cbranch_execz .LBB0_4407
	v_lshl_add_u32 v68, v66, 2, v155
	v_add_f32_e32 v49, v49, v50
	ds_add_f32 v68, v49
.LBB0_4407:
	s_or_b64 exec, exec, s[10:11]
	v_mul_f32_e32 v68, 0x3db504f3, v51
	v_mul_f32_e64 v49, |v68|, s62
	v_exp_f32_e32 v49, v49
	v_or_b32_e32 v69, 3, v11
	v_max_f32_e32 v51, 0, v68
	v_add_f32_e32 v49, 1.0, v49
	v_cmp_gt_f32_e64 s[10:11], s63, v49
	s_nop 0
	v_cndmask_b32_e64 v50, 0, 32, s[10:11]
	v_ldexp_f32 v49, v49, v50
	v_log_f32_e32 v49, v49
	v_add_u32_e32 v50, s20, v69
	v_cmp_lt_i32_e64 s[12:13], v3, v50
	s_and_b64 s[28:29], vcc, s[12:13]
	v_mul_f32_e32 v50, 0x3f317217, v49
	v_fma_f32 v50, v49, s64, -v50
	v_fmac_f32_e32 v50, 0x3377d1cf, v49
	v_fmac_f32_e32 v50, 0x3f317217, v49
	v_cmp_lt_f32_e64 s[14:15], |v49|, s65
	s_nop 1
	v_cndmask_b32_e64 v49, v49, v50, s[14:15]
	v_cndmask_b32_e64 v50, 0, v154, s[10:11]
	v_sub_f32_e32 v49, v49, v50
	v_add_f32_e32 v70, v51, v49
	v_cndmask_b32_e64 v51, 0, -v70, s[28:29]
	s_nop 1
	v_add_f32_dpp v49, v51, v51 quad_perm:[1,0,3,2] row_mask:0xf bank_mask:0xf
	v_bfe_u32 v71, v51, 16, 1
	v_add3_u32 v71, v51, v71, s66
	ds_write_b16_d16_hi v48, v71 offset:36272
	v_and_b32_e32 v71, 0xffff0000, v71
	s_nop 1
	v_add_f32_dpp v49, v49, v49 quad_perm:[2,3,0,1] row_mask:0xf bank_mask:0xf
	v_sub_f32_e32 v51, v51, v71
	v_bfe_u32 v71, v51, 16, 1
	v_add3_u32 v51, v51, v71, s66
	ds_write_b16_d16_hi v48, v51 offset:45488
	s_nop 1
	v_add_f32_dpp v49, v49, v49 row_half_mirror row_mask:0xf bank_mask:0xf
	s_nop 1
	v_add_f32_dpp v49, v49, v49 row_mirror row_mask:0xf bank_mask:0xf
	s_nop 1
	v_mov_b32_dpp v50, v49 row_bcast:15 row_mask:0xa bank_mask:0xf
	s_and_saveexec_b64 s[10:11], s[8:9]
	s_cbranch_execz .LBB0_4409
	v_lshl_add_u32 v51, v69, 2, v155
	v_add_f32_e32 v49, v49, v50
	ds_add_f32 v51, v49
.LBB0_4409:
	s_or_b64 exec, exec, s[10:11]
	v_mul_f32_e32 v71, 0x3db504f3, v52
	v_mul_f32_e64 v49, |v71|, s62
	v_exp_f32_e32 v49, v49
	v_or_b32_e32 v72, 8, v11
	v_max_f32_e32 v51, 0, v71
	v_add_f32_e32 v49, 1.0, v49
	v_cmp_gt_f32_e64 s[10:11], s63, v49
	s_nop 0
	v_cndmask_b32_e64 v50, 0, 32, s[10:11]
	v_ldexp_f32 v49, v49, v50
	v_log_f32_e32 v49, v49
	v_add_u32_e32 v50, s20, v72
	v_cmp_lt_i32_e64 s[12:13], v3, v50
	s_and_b64 s[30:31], vcc, s[12:13]
	v_mul_f32_e32 v50, 0x3f317217, v49
	v_fma_f32 v50, v49, s64, -v50
	v_fmac_f32_e32 v50, 0x3377d1cf, v49
	v_fmac_f32_e32 v50, 0x3f317217, v49
	v_cmp_lt_f32_e64 s[14:15], |v49|, s65
	s_nop 1
	v_cndmask_b32_e64 v49, v49, v50, s[14:15]
	v_cndmask_b32_e64 v50, 0, v154, s[10:11]
	v_sub_f32_e32 v49, v49, v50
	v_add_f32_e32 v73, v51, v49
	v_cndmask_b32_e64 v51, 0, -v73, s[30:31]
	s_nop 1
	v_add_f32_dpp v49, v51, v51 quad_perm:[1,0,3,2] row_mask:0xf bank_mask:0xf
	v_bfe_u32 v52, v51, 16, 1
	v_add3_u32 v52, v51, v52, s66
	ds_write_b16_d16_hi v48, v52 offset:36992
	v_and_b32_e32 v52, 0xffff0000, v52
	s_nop 1
	v_add_f32_dpp v49, v49, v49 quad_perm:[2,3,0,1] row_mask:0xf bank_mask:0xf
	v_sub_f32_e32 v51, v51, v52
	v_bfe_u32 v52, v51, 16, 1
	v_add3_u32 v51, v51, v52, s66
	ds_write_b16_d16_hi v48, v51 offset:46208
	s_nop 1
	v_add_f32_dpp v49, v49, v49 row_half_mirror row_mask:0xf bank_mask:0xf
	s_nop 1
	v_add_f32_dpp v49, v49, v49 row_mirror row_mask:0xf bank_mask:0xf
	s_nop 1
	v_mov_b32_dpp v50, v49 row_bcast:15 row_mask:0xa bank_mask:0xf
	s_and_saveexec_b64 s[10:11], s[8:9]
	s_cbranch_execz .LBB0_4411
	v_lshl_add_u32 v51, v72, 2, v155
	v_add_f32_e32 v49, v49, v50
	ds_add_f32 v51, v49
; __device__ __forceinline__ float bf2f(bf16r h) { return __uint_as_float(((unsigned)h) << 16); }
; __device__ __forceinline__ float softplusf(float x) { return fmaxf(x, 0.f) + __logf(1.f + __expf(-fabsf(x))); }
; __device__ __forceinline__ void phase_sb(const Params& p, unsigned char* smem) {
;     ...
;       for (int i = 0; i < 16; i++) {
;         int row = wm * 32 + (i & 3) + 8 * (i >> 2) + 4 * hi;
;         int col = wn * 32 + cl;
;         int t = t0 + row, key = s0 + col;
;         bool m = (key < t) && (key >= NPADR);
;         float z = az[0][0][i] * scale;
;         float sp = softplusf(z);
;         float ln = m ? -sp : 0.f;
;         logsig[i] = z - sp;
;         if (m) mbits |= (1u << i);
;         bf16r hb = f2bf(ln);
;         sHi[row * 72 + col] = hb;
;         sLo[row * 72 + col] = f2bf(ln - bf2f(hb));
;         float rsum = ln;
; #pragma unroll
;         for (int o = 16; o > 0; o >>= 1) rsum += __shfl_xor(rsum, o, 64);
;         if (cl == 0) atomicAdd(&sBlk[row], rsum);
;         if ((i & 3) == 3) __builtin_amdgcn_sched_barrier(0);
;       }
.LBB0_4411:
	s_or_b64 exec, exec, s[10:11]
	v_mul_f32_e32 v74, 0x3db504f3, v53
	v_mul_f32_e64 v49, |v74|, s62
	v_exp_f32_e32 v49, v49
	v_or_b32_e32 v75, 9, v11
	v_max_f32_e32 v51, 0, v74
	v_add_f32_e32 v49, 1.0, v49
	v_cmp_gt_f32_e64 s[10:11], s63, v49
	s_nop 0
	v_cndmask_b32_e64 v50, 0, 32, s[10:11]
	v_ldexp_f32 v49, v49, v50
	v_log_f32_e32 v49, v49
	v_add_u32_e32 v50, s20, v75
	v_cmp_lt_i32_e64 s[12:13], v3, v50
	s_and_b64 s[34:35], vcc, s[12:13]
	v_mul_f32_e32 v50, 0x3f317217, v49
	v_fma_f32 v50, v49, s64, -v50
	v_fmac_f32_e32 v50, 0x3377d1cf, v49
	v_fmac_f32_e32 v50, 0x3f317217, v49
	v_cmp_lt_f32_e64 s[14:15], |v49|, s65
	s_nop 1
	v_cndmask_b32_e64 v49, v49, v50, s[14:15]
	v_cndmask_b32_e64 v50, 0, v154, s[10:11]
	v_sub_f32_e32 v49, v49, v50
	v_add_f32_e32 v76, v51, v49
	v_cndmask_b32_e64 v51, 0, -v76, s[34:35]
	s_nop 1
	v_add_f32_dpp v49, v51, v51 quad_perm:[1,0,3,2] row_mask:0xf bank_mask:0xf
	v_bfe_u32 v52, v51, 16, 1
	v_add3_u32 v52, v51, v52, s66
	ds_write_b16_d16_hi v48, v52 offset:37136
	v_and_b32_e32 v52, 0xffff0000, v52
	s_nop 1
	v_add_f32_dpp v49, v49, v49 quad_perm:[2,3,0,1] row_mask:0xf bank_mask:0xf
	v_sub_f32_e32 v51, v51, v52
	v_bfe_u32 v52, v51, 16, 1
	v_add3_u32 v51, v51, v52, s66
	ds_write_b16_d16_hi v48, v51 offset:46352
	s_nop 1
	v_add_f32_dpp v49, v49, v49 row_half_mirror row_mask:0xf bank_mask:0xf
	s_nop 1
	v_add_f32_dpp v49, v49, v49 row_mirror row_mask:0xf bank_mask:0xf
	s_nop 1
	v_mov_b32_dpp v50, v49 row_bcast:15 row_mask:0xa bank_mask:0xf
	s_and_saveexec_b64 s[10:11], s[8:9]
	s_cbranch_execz .LBB0_4413
	v_lshl_add_u32 v51, v75, 2, v155
	v_add_f32_e32 v49, v49, v50
	ds_add_f32 v51, v49
.LBB0_4413:
	s_or_b64 exec, exec, s[10:11]
	v_mul_f32_e32 v77, 0x3db504f3, v54
	v_mul_f32_e64 v49, |v77|, s62
	v_exp_f32_e32 v49, v49
	v_or_b32_e32 v78, 10, v11
	v_max_f32_e32 v51, 0, v77
	v_add_f32_e32 v49, 1.0, v49
	v_cmp_gt_f32_e64 s[10:11], s63, v49
	s_nop 0
	v_cndmask_b32_e64 v50, 0, 32, s[10:11]
	v_ldexp_f32 v49, v49, v50
	v_log_f32_e32 v49, v49
	v_add_u32_e32 v50, s20, v78
	v_cmp_lt_i32_e64 s[12:13], v3, v50
	s_and_b64 s[36:37], vcc, s[12:13]
	v_mul_f32_e32 v50, 0x3f317217, v49
	v_fma_f32 v50, v49, s64, -v50
	v_fmac_f32_e32 v50, 0x3377d1cf, v49
	v_fmac_f32_e32 v50, 0x3f317217, v49
	v_cmp_lt_f32_e64 s[14:15], |v49|, s65
	s_nop 1
	v_cndmask_b32_e64 v49, v49, v50, s[14:15]
	v_cndmask_b32_e64 v50, 0, v154, s[10:11]
	v_sub_f32_e32 v49, v49, v50
	v_add_f32_e32 v79, v51, v49
	v_cndmask_b32_e64 v51, 0, -v79, s[36:37]
	s_nop 1
	v_add_f32_dpp v49, v51, v51 quad_perm:[1,0,3,2] row_mask:0xf bank_mask:0xf
	v_bfe_u32 v52, v51, 16, 1
	v_add3_u32 v52, v51, v52, s66
	ds_write_b16_d16_hi v48, v52 offset:37280
	v_and_b32_e32 v52, 0xffff0000, v52
	s_nop 1
	v_add_f32_dpp v49, v49, v49 quad_perm:[2,3,0,1] row_mask:0xf bank_mask:0xf
	v_sub_f32_e32 v51, v51, v52
	v_bfe_u32 v52, v51, 16, 1
	v_add3_u32 v51, v51, v52, s66
	ds_write_b16_d16_hi v48, v51 offset:46496
	s_nop 1
	v_add_f32_dpp v49, v49, v49 row_half_mirror row_mask:0xf bank_mask:0xf
	s_nop 1
	v_add_f32_dpp v49, v49, v49 row_mirror row_mask:0xf bank_mask:0xf
	s_nop 1
	v_mov_b32_dpp v50, v49 row_bcast:15 row_mask:0xa bank_mask:0xf
	s_and_saveexec_b64 s[10:11], s[8:9]
	s_cbranch_execz .LBB0_4415
	v_lshl_add_u32 v51, v78, 2, v155
	v_add_f32_e32 v49, v49, v50
	ds_add_f32 v51, v49
.LBB0_4415:
	s_or_b64 exec, exec, s[10:11]
	v_mul_f32_e32 v158, 0x3db504f3, v55
	v_mul_f32_e64 v49, |v158|, s62
	v_exp_f32_e32 v49, v49
	v_or_b32_e32 v159, 11, v11
	v_max_f32_e32 v51, 0, v158
	v_add_f32_e32 v49, 1.0, v49
	v_cmp_gt_f32_e64 s[10:11], s63, v49
	s_nop 0
	v_cndmask_b32_e64 v50, 0, 32, s[10:11]
	v_ldexp_f32 v49, v49, v50
	v_log_f32_e32 v49, v49
	v_add_u32_e32 v50, s20, v159
	v_cmp_lt_i32_e64 s[12:13], v3, v50
	s_and_b64 s[38:39], vcc, s[12:13]
	v_mul_f32_e32 v50, 0x3f317217, v49
	v_fma_f32 v50, v49, s64, -v50
	v_fmac_f32_e32 v50, 0x3377d1cf, v49
	v_fmac_f32_e32 v50, 0x3f317217, v49
	v_cmp_lt_f32_e64 s[14:15], |v49|, s65
	s_nop 1
	v_cndmask_b32_e64 v49, v49, v50, s[14:15]
	v_cndmask_b32_e64 v50, 0, v154, s[10:11]
	v_sub_f32_e32 v49, v49, v50
	v_add_f32_e32 v160, v51, v49
	v_cndmask_b32_e64 v51, 0, -v160, s[38:39]
	s_nop 1
	v_add_f32_dpp v49, v51, v51 quad_perm:[1,0,3,2] row_mask:0xf bank_mask:0xf
	v_bfe_u32 v52, v51, 16, 1
	v_add3_u32 v52, v51, v52, s66
	ds_write_b16_d16_hi v48, v52 offset:37424
	v_and_b32_e32 v52, 0xffff0000, v52
	s_nop 1
	v_add_f32_dpp v49, v49, v49 quad_perm:[2,3,0,1] row_mask:0xf bank_mask:0xf
	v_sub_f32_e32 v51, v51, v52
	v_bfe_u32 v52, v51, 16, 1
	v_add3_u32 v51, v51, v52, s66
	ds_write_b16_d16_hi v48, v51 offset:46640
	s_nop 1
	v_add_f32_dpp v49, v49, v49 row_half_mirror row_mask:0xf bank_mask:0xf
	s_nop 1
	v_add_f32_dpp v49, v49, v49 row_mirror row_mask:0xf bank_mask:0xf
	s_nop 1
	v_mov_b32_dpp v50, v49 row_bcast:15 row_mask:0xa bank_mask:0xf
	s_and_saveexec_b64 s[10:11], s[8:9]
	s_cbranch_execz .LBB0_4417
	v_lshl_add_u32 v51, v159, 2, v155
	v_add_f32_e32 v49, v49, v50
	ds_add_f32 v51, v49
; __device__ __forceinline__ float bf2f(bf16r h) { return __uint_as_float(((unsigned)h) << 16); }
; __device__ __forceinline__ float softplusf(float x) { return fmaxf(x, 0.f) + __logf(1.f + __expf(-fabsf(x))); }
; __device__ __forceinline__ void phase_sb(const Params& p, unsigned char* smem) {
;     ...
;       for (int i = 0; i < 16; i++) {
;         int row = wm * 32 + (i & 3) + 8 * (i >> 2) + 4 * hi;
;         int col = wn * 32 + cl;
;         int t = t0 + row, key = s0 + col;
;         bool m = (key < t) && (key >= NPADR);
;         float z = az[0][0][i] * scale;
;         float sp = softplusf(z);
;         float ln = m ? -sp : 0.f;
;         logsig[i] = z - sp;
;         if (m) mbits |= (1u << i);
;         bf16r hb = f2bf(ln);
;         sHi[row * 72 + col] = hb;
;         sLo[row * 72 + col] = f2bf(ln - bf2f(hb));
;         float rsum = ln;
; #pragma unroll
;         for (int o = 16; o > 0; o >>= 1) rsum += __shfl_xor(rsum, o, 64);
;         if (cl == 0) atomicAdd(&sBlk[row], rsum);
;         if ((i & 3) == 3) __builtin_amdgcn_sched_barrier(0);
;       }
.LBB0_4417:
	s_or_b64 exec, exec, s[10:11]
	v_mul_f32_e32 v161, 0x3db504f3, v56
	v_mul_f32_e64 v49, |v161|, s62
	v_exp_f32_e32 v49, v49
	v_or_b32_e32 v162, 16, v11
	v_max_f32_e32 v51, 0, v161
	v_add_f32_e32 v49, 1.0, v49
	v_cmp_gt_f32_e64 s[10:11], s63, v49
	s_nop 0
	v_cndmask_b32_e64 v50, 0, 32, s[10:11]
	v_ldexp_f32 v49, v49, v50
	v_log_f32_e32 v49, v49
	v_add_u32_e32 v50, s20, v162
	v_cmp_lt_i32_e64 s[12:13], v3, v50
	s_and_b64 s[40:41], vcc, s[12:13]
	v_mul_f32_e32 v50, 0x3f317217, v49
	v_fma_f32 v50, v49, s64, -v50
	v_fmac_f32_e32 v50, 0x3377d1cf, v49
	v_fmac_f32_e32 v50, 0x3f317217, v49
	v_cmp_lt_f32_e64 s[14:15], |v49|, s65
	s_nop 1
	v_cndmask_b32_e64 v49, v49, v50, s[14:15]
	v_cndmask_b32_e64 v50, 0, v154, s[10:11]
	v_sub_f32_e32 v49, v49, v50
	v_add_f32_e32 v163, v51, v49
	v_cndmask_b32_e64 v51, 0, -v163, s[40:41]
	s_nop 1
	v_add_f32_dpp v49, v51, v51 quad_perm:[1,0,3,2] row_mask:0xf bank_mask:0xf
	v_bfe_u32 v52, v51, 16, 1
	v_add3_u32 v52, v51, v52, s66
	ds_write_b16_d16_hi v48, v52 offset:38144
	v_and_b32_e32 v52, 0xffff0000, v52
	s_nop 1
	v_add_f32_dpp v49, v49, v49 quad_perm:[2,3,0,1] row_mask:0xf bank_mask:0xf
	v_sub_f32_e32 v51, v51, v52
	v_bfe_u32 v52, v51, 16, 1
	v_add3_u32 v51, v51, v52, s66
	ds_write_b16_d16_hi v48, v51 offset:47360
	s_nop 1
	v_add_f32_dpp v49, v49, v49 row_half_mirror row_mask:0xf bank_mask:0xf
	s_nop 1
	v_add_f32_dpp v49, v49, v49 row_mirror row_mask:0xf bank_mask:0xf
	s_nop 1
	v_mov_b32_dpp v50, v49 row_bcast:15 row_mask:0xa bank_mask:0xf
	s_and_saveexec_b64 s[10:11], s[8:9]
	s_cbranch_execz .LBB0_4419
	v_lshl_add_u32 v51, v162, 2, v155
	v_add_f32_e32 v49, v49, v50
	ds_add_f32 v51, v49
.LBB0_4419:
	s_or_b64 exec, exec, s[10:11]
	v_mul_f32_e32 v164, 0x3db504f3, v57
	v_mul_f32_e64 v49, |v164|, s62
	v_exp_f32_e32 v49, v49
	v_or_b32_e32 v165, 17, v11
	v_max_f32_e32 v51, 0, v164
	v_add_f32_e32 v49, 1.0, v49
	v_cmp_gt_f32_e64 s[10:11], s63, v49
	s_nop 0
	v_cndmask_b32_e64 v50, 0, 32, s[10:11]
	v_ldexp_f32 v49, v49, v50
	v_log_f32_e32 v49, v49
	v_add_u32_e32 v50, s20, v165
	v_cmp_lt_i32_e64 s[12:13], v3, v50
	s_and_b64 s[42:43], vcc, s[12:13]
	v_mul_f32_e32 v50, 0x3f317217, v49
	v_fma_f32 v50, v49, s64, -v50
	v_fmac_f32_e32 v50, 0x3377d1cf, v49
	v_fmac_f32_e32 v50, 0x3f317217, v49
	v_cmp_lt_f32_e64 s[14:15], |v49|, s65
	s_nop 1
	v_cndmask_b32_e64 v49, v49, v50, s[14:15]
	v_cndmask_b32_e64 v50, 0, v154, s[10:11]
	v_sub_f32_e32 v49, v49, v50
	v_add_f32_e32 v166, v51, v49
	v_cndmask_b32_e64 v51, 0, -v166, s[42:43]
	s_nop 1
	v_add_f32_dpp v49, v51, v51 quad_perm:[1,0,3,2] row_mask:0xf bank_mask:0xf
	v_bfe_u32 v52, v51, 16, 1
	v_add3_u32 v52, v51, v52, s66
	ds_write_b16_d16_hi v48, v52 offset:38288
	v_and_b32_e32 v52, 0xffff0000, v52
	s_nop 1
	v_add_f32_dpp v49, v49, v49 quad_perm:[2,3,0,1] row_mask:0xf bank_mask:0xf
	v_sub_f32_e32 v51, v51, v52
	v_bfe_u32 v52, v51, 16, 1
	v_add3_u32 v51, v51, v52, s66
	ds_write_b16_d16_hi v48, v51 offset:47504
	s_nop 1
	v_add_f32_dpp v49, v49, v49 row_half_mirror row_mask:0xf bank_mask:0xf
	s_nop 1
	v_add_f32_dpp v49, v49, v49 row_mirror row_mask:0xf bank_mask:0xf
	s_nop 1
	v_mov_b32_dpp v50, v49 row_bcast:15 row_mask:0xa bank_mask:0xf
	s_and_saveexec_b64 s[10:11], s[8:9]
	s_cbranch_execz .LBB0_4421
	v_lshl_add_u32 v51, v165, 2, v155
	v_add_f32_e32 v49, v49, v50
	ds_add_f32 v51, v49
.LBB0_4421:
	s_or_b64 exec, exec, s[10:11]
	v_mul_f32_e32 v167, 0x3db504f3, v58
	v_mul_f32_e64 v49, |v167|, s62
	v_exp_f32_e32 v49, v49
	v_or_b32_e32 v168, 18, v11
	v_max_f32_e32 v51, 0, v167
	v_add_f32_e32 v49, 1.0, v49
	v_cmp_gt_f32_e64 s[10:11], s63, v49
	s_nop 0
	v_cndmask_b32_e64 v50, 0, 32, s[10:11]
	v_ldexp_f32 v49, v49, v50
	v_log_f32_e32 v49, v49
	v_add_u32_e32 v50, s20, v168
	v_cmp_lt_i32_e64 s[12:13], v3, v50
	s_and_b64 s[48:49], vcc, s[12:13]
	v_mul_f32_e32 v50, 0x3f317217, v49
	v_fma_f32 v50, v49, s64, -v50
	v_fmac_f32_e32 v50, 0x3377d1cf, v49
	v_fmac_f32_e32 v50, 0x3f317217, v49
	v_cmp_lt_f32_e64 s[14:15], |v49|, s65
	s_nop 1
	v_cndmask_b32_e64 v49, v49, v50, s[14:15]
	v_cndmask_b32_e64 v50, 0, v154, s[10:11]
	v_sub_f32_e32 v49, v49, v50
	v_add_f32_e32 v169, v51, v49
	v_cndmask_b32_e64 v51, 0, -v169, s[48:49]
	s_nop 1
	v_add_f32_dpp v49, v51, v51 quad_perm:[1,0,3,2] row_mask:0xf bank_mask:0xf
	v_bfe_u32 v52, v51, 16, 1
	v_add3_u32 v52, v51, v52, s66
	ds_write_b16_d16_hi v48, v52 offset:38432
	v_and_b32_e32 v52, 0xffff0000, v52
	s_nop 1
	v_add_f32_dpp v49, v49, v49 quad_perm:[2,3,0,1] row_mask:0xf bank_mask:0xf
	v_sub_f32_e32 v51, v51, v52
	v_bfe_u32 v52, v51, 16, 1
	v_add3_u32 v51, v51, v52, s66
	ds_write_b16_d16_hi v48, v51 offset:47648
	s_nop 1
	v_add_f32_dpp v49, v49, v49 row_half_mirror row_mask:0xf bank_mask:0xf
	s_nop 1
	v_add_f32_dpp v49, v49, v49 row_mirror row_mask:0xf bank_mask:0xf
	s_nop 1
	v_mov_b32_dpp v50, v49 row_bcast:15 row_mask:0xa bank_mask:0xf
	s_and_saveexec_b64 s[10:11], s[8:9]
	s_cbranch_execz .LBB0_4423
	v_lshl_add_u32 v51, v168, 2, v155
	v_add_f32_e32 v49, v49, v50
	ds_add_f32 v51, v49
; __device__ __forceinline__ float bf2f(bf16r h) { return __uint_as_float(((unsigned)h) << 16); }
; __device__ __forceinline__ float softplusf(float x) { return fmaxf(x, 0.f) + __logf(1.f + __expf(-fabsf(x))); }
; __device__ __forceinline__ void phase_sb(const Params& p, unsigned char* smem) {
;     ...
;       for (int i = 0; i < 16; i++) {
;         int row = wm * 32 + (i & 3) + 8 * (i >> 2) + 4 * hi;
;         int col = wn * 32 + cl;
;         int t = t0 + row, key = s0 + col;
;         bool m = (key < t) && (key >= NPADR);
;         float z = az[0][0][i] * scale;
;         float sp = softplusf(z);
;         float ln = m ? -sp : 0.f;
;         logsig[i] = z - sp;
;         if (m) mbits |= (1u << i);
;         bf16r hb = f2bf(ln);
;         sHi[row * 72 + col] = hb;
;         sLo[row * 72 + col] = f2bf(ln - bf2f(hb));
;         float rsum = ln;
; #pragma unroll
;         for (int o = 16; o > 0; o >>= 1) rsum += __shfl_xor(rsum, o, 64);
;         if (cl == 0) atomicAdd(&sBlk[row], rsum);
;         if ((i & 3) == 3) __builtin_amdgcn_sched_barrier(0);
;       }
.LBB0_4423:
	s_or_b64 exec, exec, s[10:11]
	v_mul_f32_e32 v170, 0x3db504f3, v59
	v_mul_f32_e64 v49, |v170|, s62
	v_exp_f32_e32 v49, v49
	v_or_b32_e32 v171, 19, v11
	v_max_f32_e32 v51, 0, v170
	v_add_f32_e32 v49, 1.0, v49
	v_cmp_gt_f32_e64 s[10:11], s63, v49
	s_nop 0
	v_cndmask_b32_e64 v50, 0, 32, s[10:11]
	v_ldexp_f32 v49, v49, v50
	v_log_f32_e32 v49, v49
	v_add_u32_e32 v50, s20, v171
	v_cmp_lt_i32_e64 s[12:13], v3, v50
	s_and_b64 s[50:51], vcc, s[12:13]
	v_mul_f32_e32 v50, 0x3f317217, v49
	v_fma_f32 v50, v49, s64, -v50
	v_fmac_f32_e32 v50, 0x3377d1cf, v49
	v_fmac_f32_e32 v50, 0x3f317217, v49
	v_cmp_lt_f32_e64 s[14:15], |v49|, s65
	s_nop 1
	v_cndmask_b32_e64 v49, v49, v50, s[14:15]
	v_cndmask_b32_e64 v50, 0, v154, s[10:11]
	v_sub_f32_e32 v49, v49, v50
	v_add_f32_e32 v172, v51, v49
	v_cndmask_b32_e64 v51, 0, -v172, s[50:51]
	s_nop 1
	v_add_f32_dpp v49, v51, v51 quad_perm:[1,0,3,2] row_mask:0xf bank_mask:0xf
	v_bfe_u32 v52, v51, 16, 1
	v_add3_u32 v52, v51, v52, s66
	ds_write_b16_d16_hi v48, v52 offset:38576
	v_and_b32_e32 v52, 0xffff0000, v52
	s_nop 1
	v_add_f32_dpp v49, v49, v49 quad_perm:[2,3,0,1] row_mask:0xf bank_mask:0xf
	v_sub_f32_e32 v51, v51, v52
	v_bfe_u32 v52, v51, 16, 1
	v_add3_u32 v51, v51, v52, s66
	ds_write_b16_d16_hi v48, v51 offset:47792
	s_nop 1
	v_add_f32_dpp v49, v49, v49 row_half_mirror row_mask:0xf bank_mask:0xf
	s_nop 1
	v_add_f32_dpp v49, v49, v49 row_mirror row_mask:0xf bank_mask:0xf
	s_nop 1
	v_mov_b32_dpp v50, v49 row_bcast:15 row_mask:0xa bank_mask:0xf
	s_and_saveexec_b64 s[10:11], s[8:9]
	s_cbranch_execz .LBB0_4425
	v_lshl_add_u32 v51, v171, 2, v155
	v_add_f32_e32 v49, v49, v50
	ds_add_f32 v51, v49
.LBB0_4425:
	s_or_b64 exec, exec, s[10:11]
	v_mul_f32_e32 v173, 0x3db504f3, v60
	v_mul_f32_e64 v49, |v173|, s62
	v_exp_f32_e32 v49, v49
	v_or_b32_e32 v174, 24, v11
	v_max_f32_e32 v51, 0, v173
	v_add_f32_e32 v49, 1.0, v49
	v_cmp_gt_f32_e64 s[10:11], s63, v49
	s_nop 0
	v_cndmask_b32_e64 v50, 0, 32, s[10:11]
	v_ldexp_f32 v49, v49, v50
	v_log_f32_e32 v49, v49
	v_add_u32_e32 v50, s20, v174
	v_cmp_lt_i32_e64 s[12:13], v3, v50
	s_and_b64 s[52:53], vcc, s[12:13]
	v_mul_f32_e32 v50, 0x3f317217, v49
	v_fma_f32 v50, v49, s64, -v50
	v_fmac_f32_e32 v50, 0x3377d1cf, v49
	v_fmac_f32_e32 v50, 0x3f317217, v49
	v_cmp_lt_f32_e64 s[14:15], |v49|, s65
	s_nop 1
	v_cndmask_b32_e64 v49, v49, v50, s[14:15]
	v_cndmask_b32_e64 v50, 0, v154, s[10:11]
	v_sub_f32_e32 v49, v49, v50
	v_add_f32_e32 v175, v51, v49
	v_cndmask_b32_e64 v51, 0, -v175, s[52:53]
	s_nop 1
	v_add_f32_dpp v49, v51, v51 quad_perm:[1,0,3,2] row_mask:0xf bank_mask:0xf
	v_bfe_u32 v52, v51, 16, 1
	v_add3_u32 v52, v51, v52, s66
	ds_write_b16_d16_hi v48, v52 offset:39296
	v_and_b32_e32 v52, 0xffff0000, v52
	s_nop 1
	v_add_f32_dpp v49, v49, v49 quad_perm:[2,3,0,1] row_mask:0xf bank_mask:0xf
	v_sub_f32_e32 v51, v51, v52
	v_bfe_u32 v52, v51, 16, 1
	v_add3_u32 v51, v51, v52, s66
	ds_write_b16_d16_hi v48, v51 offset:48512
	s_nop 1
	v_add_f32_dpp v49, v49, v49 row_half_mirror row_mask:0xf bank_mask:0xf
	s_nop 1
	v_add_f32_dpp v49, v49, v49 row_mirror row_mask:0xf bank_mask:0xf
	s_nop 1
	v_mov_b32_dpp v50, v49 row_bcast:15 row_mask:0xa bank_mask:0xf
	s_and_saveexec_b64 s[10:11], s[8:9]
	s_cbranch_execz .LBB0_4427
	v_lshl_add_u32 v51, v174, 2, v155
	v_add_f32_e32 v49, v49, v50
	ds_add_f32 v51, v49
; __device__ __forceinline__ float bf2f(bf16r h) { return __uint_as_float(((unsigned)h) << 16); }
; __device__ __forceinline__ float softplusf(float x) { return fmaxf(x, 0.f) + __logf(1.f + __expf(-fabsf(x))); }
; __device__ __forceinline__ void phase_sb(const Params& p, unsigned char* smem) {
;     ...
;       for (int i = 0; i < 16; i++) {
;         int row = wm * 32 + (i & 3) + 8 * (i >> 2) + 4 * hi;
;         int col = wn * 32 + cl;
;         int t = t0 + row, key = s0 + col;
;         bool m = (key < t) && (key >= NPADR);
;         float z = az[0][0][i] * scale;
;         float sp = softplusf(z);
;         float ln = m ? -sp : 0.f;
;         logsig[i] = z - sp;
;         if (m) mbits |= (1u << i);
;         bf16r hb = f2bf(ln);
;         sHi[row * 72 + col] = hb;
;         sLo[row * 72 + col] = f2bf(ln - bf2f(hb));
;         float rsum = ln;
; #pragma unroll
;         for (int o = 16; o > 0; o >>= 1) rsum += __shfl_xor(rsum, o, 64);
;         if (cl == 0) atomicAdd(&sBlk[row], rsum);
;         if ((i & 3) == 3) __builtin_amdgcn_sched_barrier(0);
;       }
.LBB0_4427:
	s_or_b64 exec, exec, s[10:11]
	v_mul_f32_e32 v176, 0x3db504f3, v61
	v_mul_f32_e64 v49, |v176|, s62
	v_exp_f32_e32 v49, v49
	v_or_b32_e32 v177, 25, v11
	v_max_f32_e32 v51, 0, v176
	v_add_f32_e32 v49, 1.0, v49
	v_cmp_gt_f32_e64 s[10:11], s63, v49
	s_nop 0
	v_cndmask_b32_e64 v50, 0, 32, s[10:11]
	v_ldexp_f32 v49, v49, v50
	v_log_f32_e32 v49, v49
	v_add_u32_e32 v50, s20, v177
	v_cmp_lt_i32_e64 s[12:13], v3, v50
	s_and_b64 s[54:55], vcc, s[12:13]
	v_mul_f32_e32 v50, 0x3f317217, v49
	v_fma_f32 v50, v49, s64, -v50
	v_fmac_f32_e32 v50, 0x3377d1cf, v49
	v_fmac_f32_e32 v50, 0x3f317217, v49
	v_cmp_lt_f32_e64 s[14:15], |v49|, s65
	s_nop 1
	v_cndmask_b32_e64 v49, v49, v50, s[14:15]
	v_cndmask_b32_e64 v50, 0, v154, s[10:11]
	v_sub_f32_e32 v49, v49, v50
	v_add_f32_e32 v178, v51, v49
	v_cndmask_b32_e64 v51, 0, -v178, s[54:55]
	s_nop 1
	v_add_f32_dpp v49, v51, v51 quad_perm:[1,0,3,2] row_mask:0xf bank_mask:0xf
	v_bfe_u32 v52, v51, 16, 1
	v_add3_u32 v52, v51, v52, s66
	ds_write_b16_d16_hi v48, v52 offset:39440
	v_and_b32_e32 v52, 0xffff0000, v52
	s_nop 1
	v_add_f32_dpp v49, v49, v49 quad_perm:[2,3,0,1] row_mask:0xf bank_mask:0xf
	v_sub_f32_e32 v51, v51, v52
	v_bfe_u32 v52, v51, 16, 1
	v_add3_u32 v51, v51, v52, s66
	ds_write_b16_d16_hi v48, v51 offset:48656
	s_nop 1
	v_add_f32_dpp v49, v49, v49 row_half_mirror row_mask:0xf bank_mask:0xf
	s_nop 1
	v_add_f32_dpp v49, v49, v49 row_mirror row_mask:0xf bank_mask:0xf
	s_nop 1
	v_mov_b32_dpp v50, v49 row_bcast:15 row_mask:0xa bank_mask:0xf
	s_and_saveexec_b64 s[10:11], s[8:9]
	s_cbranch_execz .LBB0_4429
	v_lshl_add_u32 v51, v177, 2, v155
	v_add_f32_e32 v49, v49, v50
	ds_add_f32 v51, v49
.LBB0_4429:
	s_or_b64 exec, exec, s[10:11]
	v_mul_f32_e32 v179, 0x3db504f3, v62
	v_mul_f32_e64 v49, |v179|, s62
	v_exp_f32_e32 v49, v49
	v_or_b32_e32 v180, 26, v11
	v_max_f32_e32 v51, 0, v179
	v_add_f32_e32 v49, 1.0, v49
	v_cmp_gt_f32_e64 s[10:11], s63, v49
	s_nop 0
	v_cndmask_b32_e64 v50, 0, 32, s[10:11]
	v_ldexp_f32 v49, v49, v50
	v_log_f32_e32 v49, v49
	v_add_u32_e32 v50, s20, v180
	v_cmp_lt_i32_e64 s[12:13], v3, v50
	s_and_b64 s[56:57], vcc, s[12:13]
	v_mul_f32_e32 v50, 0x3f317217, v49
	v_fma_f32 v50, v49, s64, -v50
	v_fmac_f32_e32 v50, 0x3377d1cf, v49
	v_fmac_f32_e32 v50, 0x3f317217, v49
	v_cmp_lt_f32_e64 s[14:15], |v49|, s65
	s_nop 1
	v_cndmask_b32_e64 v49, v49, v50, s[14:15]
	v_cndmask_b32_e64 v50, 0, v154, s[10:11]
	v_sub_f32_e32 v49, v49, v50
	v_add_f32_e32 v181, v51, v49
	v_cndmask_b32_e64 v51, 0, -v181, s[56:57]
	s_nop 1
	v_add_f32_dpp v49, v51, v51 quad_perm:[1,0,3,2] row_mask:0xf bank_mask:0xf
	v_bfe_u32 v52, v51, 16, 1
	v_add3_u32 v52, v51, v52, s66
	ds_write_b16_d16_hi v48, v52 offset:39584
	v_and_b32_e32 v52, 0xffff0000, v52
	s_nop 1
	v_add_f32_dpp v49, v49, v49 quad_perm:[2,3,0,1] row_mask:0xf bank_mask:0xf
	v_sub_f32_e32 v51, v51, v52
	v_bfe_u32 v52, v51, 16, 1
	v_add3_u32 v51, v51, v52, s66
	ds_write_b16_d16_hi v48, v51 offset:48800
	s_nop 1
	v_add_f32_dpp v49, v49, v49 row_half_mirror row_mask:0xf bank_mask:0xf
	s_nop 1
	v_add_f32_dpp v49, v49, v49 row_mirror row_mask:0xf bank_mask:0xf
	s_nop 1
	v_mov_b32_dpp v50, v49 row_bcast:15 row_mask:0xa bank_mask:0xf
	s_and_saveexec_b64 s[10:11], s[8:9]
	s_cbranch_execz .LBB0_4431
	v_lshl_add_u32 v51, v180, 2, v155
	v_add_f32_e32 v49, v49, v50
	ds_add_f32 v51, v49
.LBB0_4431:
	s_or_b64 exec, exec, s[10:11]
	v_mul_f32_e32 v182, 0x3db504f3, v63
	v_mul_f32_e64 v49, |v182|, s62
	v_exp_f32_e32 v49, v49
	v_or_b32_e32 v183, 27, v11
	v_max_f32_e32 v51, 0, v182
	v_add_f32_e32 v49, 1.0, v49
	v_cmp_gt_f32_e64 s[10:11], s63, v49
	s_nop 0
	v_cndmask_b32_e64 v50, 0, 32, s[10:11]
	v_ldexp_f32 v49, v49, v50
	v_log_f32_e32 v49, v49
	v_add_u32_e32 v50, s20, v183
	v_cmp_lt_i32_e64 s[12:13], v3, v50
	v_mul_f32_e32 v3, 0x3f317217, v49
	v_fma_f32 v3, v49, s64, -v3
	v_fmac_f32_e32 v3, 0x3377d1cf, v49
	v_fmac_f32_e32 v3, 0x3f317217, v49
	v_cmp_lt_f32_e64 s[14:15], |v49|, s65
	s_nop 1
	v_cndmask_b32_e64 v3, v49, v3, s[14:15]
	v_cndmask_b32_e64 v49, 0, v154, s[10:11]
	v_sub_f32_e32 v3, v3, v49
	v_add_f32_e32 v184, v51, v3
	s_and_b64 s[10:11], vcc, s[12:13]
	v_cndmask_b32_e64 v50, 0, -v184, s[10:11]
	s_nop 1
	v_add_f32_dpp v3, v50, v50 quad_perm:[1,0,3,2] row_mask:0xf bank_mask:0xf
	v_bfe_u32 v51, v50, 16, 1
	v_add3_u32 v51, v50, v51, s66
	ds_write_b16_d16_hi v48, v51 offset:39728
	v_and_b32_e32 v51, 0xffff0000, v51
	s_nop 1
	v_add_f32_dpp v3, v3, v3 quad_perm:[2,3,0,1] row_mask:0xf bank_mask:0xf
	v_sub_f32_e32 v50, v50, v51
	v_bfe_u32 v51, v50, 16, 1
	v_add3_u32 v50, v50, v51, s66
	ds_write_b16_d16_hi v48, v50 offset:48944
	s_nop 1
	v_add_f32_dpp v3, v3, v3 row_half_mirror row_mask:0xf bank_mask:0xf
	s_nop 1
	v_add_f32_dpp v3, v3, v3 row_mirror row_mask:0xf bank_mask:0xf
	s_nop 1
	v_mov_b32_dpp v49, v3 row_bcast:15 row_mask:0xa bank_mask:0xf
	s_and_saveexec_b64 s[12:13], s[8:9]
	s_cbranch_execz .LBB0_4433
	v_lshl_add_u32 v48, v183, 2, v155
	v_add_f32_e32 v3, v3, v49
	ds_add_f32 v48, v3
	s_waitcnt lgkmcnt(0)
